# first K-tile of each GEMM unit peeled with srcC=0 MFMAs, accumulator zeroing removed
# speedup vs baseline: 1.0076x; 1.0010x over previous
.LBB0_552:
	s_mov_b32 s17, s9
	s_lshl_b64 s[20:21], s[16:17], 1
	s_add_u32 s20, s58, s20
	s_addc_u32 s21, s59, s21
	s_and_b64 s[22:23], s[6:7], exec
	s_mov_b32 s19, s9
	s_cselect_b32 s17, s21, s27
	s_cselect_b32 s54, s20, s26
	s_lshl_b64 s[22:23], s[18:19], 1
	s_add_u32 s22, s93, s22
	v_readlane_b32 s19, v250, 4
	s_addc_u32 s23, s19, s23
	s_and_b64 s[28:29], s[6:7], exec
	s_cselect_b32 s19, s23, s25
	s_cselect_b32 s55, s22, s24
	s_add_u32 s56, s24, 0x2c0000
	s_addc_u32 s57, s25, 0
	s_add_u32 s24, s26, 0x404000
	s_addc_u32 s25, s27, 0
	s_mov_b32 s62, -2
	ds_read_b128 v[152:155], v149
	ds_read_b128 v[156:159], v149 offset:1024
	ds_read_b128 v[160:163], v149 offset:2048
	ds_read_b128 v[164:167], v149 offset:3072
	ds_read_b128 v[168:171], v150
	ds_read_b128 v[172:175], v150 offset:1024
	ds_read_b128 v[176:179], v150 offset:2048
	ds_read_b128 v[180:183], v150 offset:3072
	s_add_u32 s26, s24, 0x3fc000
	s_addc_u32 s27, s25, 0
	s_cmp_eq_u32 s62, 28
	s_cselect_b32 s30, s54, s26
	s_cselect_b32 s31, s17, s27
	s_cselect_b32 s28, s55, s56
	s_cselect_b32 s29, s19, s57
	s_add_u32 s26, s30, 0x400000
	s_addc_u32 s27, s31, 0
	s_add_i32 m0, s15, 0xc000
	ds_read_b128 v[184:187], v151
	ds_read_b128 v[188:191], v151 offset:1024
	ds_read_b128 v[192:195], v151 offset:2048
	ds_read_b128 v[196:199], v151 offset:3072
	ds_read_b128 v[200:203], v151 offset:4096
	ds_read_b128 v[204:207], v151 offset:5120
	ds_read_b128 v[208:211], v151 offset:6144
	ds_read_b128 v[212:215], v151 offset:7168
	global_load_lds_dwordx4 v136, s[24:25]
	s_add_i32 m0, s15, 0xe000
	s_nop 0
	global_load_lds_dwordx4 v138, s[24:25]
	s_waitcnt vmcnt(8)
	s_waitcnt lgkmcnt(0)
	s_setprio 1
	s_barrier
	v_mfma_f32_16x16x32_bf16 v[124:127], v[152:155], v[184:187], 0
	v_mfma_f32_16x16x32_bf16 v[120:123], v[160:163], v[184:187], 0
	v_mfma_f32_16x16x32_bf16 v[108:111], v[152:155], v[192:195], 0
	v_mfma_f32_16x16x32_bf16 v[104:107], v[160:163], v[192:195], 0
	v_mfma_f32_16x16x32_bf16 v[92:95], v[152:155], v[200:203], 0
	v_mfma_f32_16x16x32_bf16 v[88:91], v[160:163], v[200:203], 0
	v_mfma_f32_16x16x32_bf16 v[76:79], v[152:155], v[208:211], 0
	v_mfma_f32_16x16x32_bf16 v[72:75], v[160:163], v[208:211], 0
	v_mfma_f32_16x16x32_bf16 v[124:127], v[156:159], v[188:191], v[124:127]
	v_mfma_f32_16x16x32_bf16 v[120:123], v[164:167], v[188:191], v[120:123]
	v_mfma_f32_16x16x32_bf16 v[108:111], v[156:159], v[196:199], v[108:111]
	v_mfma_f32_16x16x32_bf16 v[104:107], v[164:167], v[196:199], v[104:107]
	v_mfma_f32_16x16x32_bf16 v[92:95], v[156:159], v[204:207], v[92:95]
	v_mfma_f32_16x16x32_bf16 v[88:91], v[164:167], v[204:207], v[88:91]
	v_mfma_f32_16x16x32_bf16 v[76:79], v[156:159], v[212:215], v[76:79]
	v_mfma_f32_16x16x32_bf16 v[72:75], v[164:167], v[212:215], v[72:75]
	v_mfma_f32_16x16x32_bf16 v[116:119], v[168:171], v[184:187], 0
	v_mfma_f32_16x16x32_bf16 v[112:115], v[176:179], v[184:187], 0
	v_mfma_f32_16x16x32_bf16 v[100:103], v[168:171], v[192:195], 0
	v_mfma_f32_16x16x32_bf16 v[96:99], v[176:179], v[192:195], 0
	v_mfma_f32_16x16x32_bf16 v[84:87], v[168:171], v[200:203], 0
	v_mfma_f32_16x16x32_bf16 v[80:83], v[176:179], v[200:203], 0
	v_mfma_f32_16x16x32_bf16 v[68:71], v[168:171], v[208:211], 0
	v_mfma_f32_16x16x32_bf16 v[64:67], v[176:179], v[208:211], 0
	v_mfma_f32_16x16x32_bf16 v[116:119], v[172:175], v[188:191], v[116:119]
	v_mfma_f32_16x16x32_bf16 v[112:115], v[180:183], v[188:191], v[112:115]
	v_mfma_f32_16x16x32_bf16 v[100:103], v[172:175], v[196:199], v[100:103]
	v_mfma_f32_16x16x32_bf16 v[96:99], v[180:183], v[196:199], v[96:99]
	v_mfma_f32_16x16x32_bf16 v[84:87], v[172:175], v[204:207], v[84:87]
	v_mfma_f32_16x16x32_bf16 v[80:83], v[180:183], v[204:207], v[80:83]
	v_mfma_f32_16x16x32_bf16 v[68:71], v[172:175], v[212:215], v[68:71]
	v_mfma_f32_16x16x32_bf16 v[64:67], v[180:183], v[212:215], v[64:67]
	s_barrier
	s_setprio 0
	s_add_i32 s63, s42, s5
	s_mov_b32 m0, s63
	ds_read_b128 v[184:187], v151 offset:16384
	ds_read_b128 v[188:191], v151 offset:17408
	ds_read_b128 v[192:195], v151 offset:18432
	ds_read_b128 v[196:199], v151 offset:19456
	ds_read_b128 v[200:203], v151 offset:20480
	ds_read_b128 v[204:207], v151 offset:21504
	ds_read_b128 v[208:211], v151 offset:22528
	ds_read_b128 v[212:215], v151 offset:23552
	global_load_lds_dwordx4 v132, s[28:29]
	s_add_i32 m0, s63, 0x2000
	s_add_u32 s66, s28, 0x4000
	s_addc_u32 s67, s29, 0
	s_add_i32 s63, s43, s5
	global_load_lds_dwordx4 v128, s[28:29]
	s_mov_b32 m0, s63
	s_nop 0
	global_load_lds_dwordx4 v132, s[66:67]
	s_add_i32 m0, s63, 0x2000
	s_nop 0
	global_load_lds_dwordx4 v128, s[66:67]
	s_mov_b32 m0, s15
	s_nop 0
	global_load_lds_dwordx4 v134, s[30:31]
	s_mov_b32 m0, s33
	s_nop 0
	global_load_lds_dwordx4 v130, s[30:31]
	s_waitcnt vmcnt(8)
	s_waitcnt lgkmcnt(0)
	s_setprio 1
	s_barrier
	v_mfma_f32_16x16x32_bf16 v[60:63], v[152:155], v[184:187], 0
	v_mfma_f32_16x16x32_bf16 v[56:59], v[160:163], v[184:187], 0
	v_mfma_f32_16x16x32_bf16 v[44:47], v[152:155], v[192:195], 0
	v_mfma_f32_16x16x32_bf16 v[40:43], v[160:163], v[192:195], 0
	v_mfma_f32_16x16x32_bf16 v[28:31], v[152:155], v[200:203], 0
	v_mfma_f32_16x16x32_bf16 v[24:27], v[160:163], v[200:203], 0
	v_mfma_f32_16x16x32_bf16 v[12:15], v[152:155], v[208:211], 0
	v_mfma_f32_16x16x32_bf16 v[8:11], v[160:163], v[208:211], 0
	v_mfma_f32_16x16x32_bf16 v[60:63], v[156:159], v[188:191], v[60:63]
	v_mfma_f32_16x16x32_bf16 v[56:59], v[164:167], v[188:191], v[56:59]
	v_mfma_f32_16x16x32_bf16 v[44:47], v[156:159], v[196:199], v[44:47]
	v_mfma_f32_16x16x32_bf16 v[40:43], v[164:167], v[196:199], v[40:43]
	v_mfma_f32_16x16x32_bf16 v[28:31], v[156:159], v[204:207], v[28:31]
	v_mfma_f32_16x16x32_bf16 v[24:27], v[164:167], v[204:207], v[24:27]
	v_mfma_f32_16x16x32_bf16 v[12:15], v[156:159], v[212:215], v[12:15]
	v_mfma_f32_16x16x32_bf16 v[8:11], v[164:167], v[212:215], v[8:11]
	v_mfma_f32_16x16x32_bf16 v[52:55], v[168:171], v[184:187], 0
	v_mfma_f32_16x16x32_bf16 v[48:51], v[176:179], v[184:187], 0
	v_mfma_f32_16x16x32_bf16 v[36:39], v[168:171], v[192:195], 0
	v_mfma_f32_16x16x32_bf16 v[32:35], v[176:179], v[192:195], 0
	v_mfma_f32_16x16x32_bf16 v[20:23], v[168:171], v[200:203], 0
	v_mfma_f32_16x16x32_bf16 v[16:19], v[176:179], v[200:203], 0
	v_mfma_f32_16x16x32_bf16 v[4:7], v[168:171], v[208:211], 0
	v_mfma_f32_16x16x32_bf16 v[0:3], v[176:179], v[208:211], 0
	v_mfma_f32_16x16x32_bf16 v[52:55], v[172:175], v[188:191], v[52:55]
	v_mfma_f32_16x16x32_bf16 v[48:51], v[180:183], v[188:191], v[48:51]
	v_mfma_f32_16x16x32_bf16 v[36:39], v[172:175], v[196:199], v[36:39]
	v_mfma_f32_16x16x32_bf16 v[32:35], v[180:183], v[196:199], v[32:35]
	v_mfma_f32_16x16x32_bf16 v[20:23], v[172:175], v[204:207], v[20:23]
	v_mfma_f32_16x16x32_bf16 v[16:19], v[180:183], v[204:207], v[16:19]
	v_mfma_f32_16x16x32_bf16 v[4:7], v[172:175], v[212:215], v[4:7]
	v_mfma_f32_16x16x32_bf16 v[0:3], v[180:183], v[212:215], v[0:3]
	s_barrier
	s_setprio 0
	s_branch .Lzmid1

.Lzmid1:
	s_add_i32 s63, 0, 0x18000
	v_add_u32_e32 v144, s63, v148
	s_add_i32 s66, 0, 0x1c000
	ds_read_b128 v[152:155], v144
	ds_read_b128 v[156:159], v144 offset:1024
	ds_read_b128 v[160:163], v144 offset:2048
	ds_read_b128 v[164:167], v144 offset:3072
	v_add_u32_e32 v144, s66, v148
	ds_read_b128 v[168:171], v144
	ds_read_b128 v[172:175], v144 offset:1024
	ds_read_b128 v[176:179], v144 offset:2048
	ds_read_b128 v[180:183], v144 offset:3072
	s_add_u32 s30, s30, 0x4000
	s_addc_u32 s31, s31, 0
	s_mov_b32 m0, s34
	ds_read_b128 v[184:187], v151 offset:32768
	ds_read_b128 v[188:191], v151 offset:33792
	ds_read_b128 v[192:195], v151 offset:34816
	ds_read_b128 v[196:199], v151 offset:35840
	ds_read_b128 v[200:203], v151 offset:36864
	ds_read_b128 v[204:207], v151 offset:37888
	ds_read_b128 v[208:211], v151 offset:38912
	ds_read_b128 v[212:215], v151 offset:39936
	global_load_lds_dwordx4 v134, s[30:31]
	s_mov_b32 m0, s35
	s_nop 0
	global_load_lds_dwordx4 v130, s[30:31]
	s_waitcnt vmcnt(8)
	s_waitcnt lgkmcnt(0)
	s_setprio 1
	s_barrier
	v_mfma_f32_16x16x32_bf16 v[124:127], v[152:155], v[184:187], v[124:127]
	v_mfma_f32_16x16x32_bf16 v[120:123], v[160:163], v[184:187], v[120:123]
	v_mfma_f32_16x16x32_bf16 v[108:111], v[152:155], v[192:195], v[108:111]
	v_mfma_f32_16x16x32_bf16 v[104:107], v[160:163], v[192:195], v[104:107]
	v_mfma_f32_16x16x32_bf16 v[92:95], v[152:155], v[200:203], v[92:95]
	v_mfma_f32_16x16x32_bf16 v[88:91], v[160:163], v[200:203], v[88:91]
	v_mfma_f32_16x16x32_bf16 v[76:79], v[152:155], v[208:211], v[76:79]
	v_mfma_f32_16x16x32_bf16 v[72:75], v[160:163], v[208:211], v[72:75]
	v_mfma_f32_16x16x32_bf16 v[124:127], v[156:159], v[188:191], v[124:127]
	v_mfma_f32_16x16x32_bf16 v[120:123], v[164:167], v[188:191], v[120:123]
	v_mfma_f32_16x16x32_bf16 v[108:111], v[156:159], v[196:199], v[108:111]
	v_mfma_f32_16x16x32_bf16 v[104:107], v[164:167], v[196:199], v[104:107]
	v_mfma_f32_16x16x32_bf16 v[92:95], v[156:159], v[204:207], v[92:95]
	v_mfma_f32_16x16x32_bf16 v[88:91], v[164:167], v[204:207], v[88:91]
	v_mfma_f32_16x16x32_bf16 v[76:79], v[156:159], v[212:215], v[76:79]
	v_mfma_f32_16x16x32_bf16 v[72:75], v[164:167], v[212:215], v[72:75]
	v_mfma_f32_16x16x32_bf16 v[116:119], v[168:171], v[184:187], v[116:119]
	v_mfma_f32_16x16x32_bf16 v[112:115], v[176:179], v[184:187], v[112:115]
	v_mfma_f32_16x16x32_bf16 v[100:103], v[168:171], v[192:195], v[100:103]
	v_mfma_f32_16x16x32_bf16 v[96:99], v[176:179], v[192:195], v[96:99]
	v_mfma_f32_16x16x32_bf16 v[84:87], v[168:171], v[200:203], v[84:87]
	v_mfma_f32_16x16x32_bf16 v[80:83], v[176:179], v[200:203], v[80:83]
	v_mfma_f32_16x16x32_bf16 v[68:71], v[168:171], v[208:211], v[68:71]
	v_mfma_f32_16x16x32_bf16 v[64:67], v[176:179], v[208:211], v[64:67]
	v_mfma_f32_16x16x32_bf16 v[116:119], v[172:175], v[188:191], v[116:119]
	v_mfma_f32_16x16x32_bf16 v[112:115], v[180:183], v[188:191], v[112:115]
	v_mfma_f32_16x16x32_bf16 v[100:103], v[172:175], v[196:199], v[100:103]
	v_mfma_f32_16x16x32_bf16 v[96:99], v[180:183], v[196:199], v[96:99]
	v_mfma_f32_16x16x32_bf16 v[84:87], v[172:175], v[204:207], v[84:87]
	v_mfma_f32_16x16x32_bf16 v[80:83], v[180:183], v[204:207], v[80:83]
	v_mfma_f32_16x16x32_bf16 v[68:71], v[172:175], v[212:215], v[68:71]
	v_mfma_f32_16x16x32_bf16 v[64:67], v[180:183], v[212:215], v[64:67]
	s_barrier
	s_setprio 0
	s_add_u32 s30, s28, 0x160000
	s_addc_u32 s31, s29, 0
	s_add_i32 s63, s63, s5
	s_mov_b32 m0, s63
	ds_read_b128 v[184:187], v151 offset:49152
	ds_read_b128 v[188:191], v151 offset:50176
	ds_read_b128 v[192:195], v151 offset:51200
	ds_read_b128 v[196:199], v151 offset:52224
	ds_read_b128 v[200:203], v151 offset:53248
	ds_read_b128 v[204:207], v151 offset:54272
	ds_read_b128 v[208:211], v151 offset:55296
	ds_read_b128 v[212:215], v151 offset:56320
	global_load_lds_dwordx4 v132, s[30:31]
	s_add_i32 m0, s63, 0x2000
	s_add_u32 s28, s28, 0x164000
	global_load_lds_dwordx4 v128, s[30:31]
	s_addc_u32 s29, s29, 0
	s_add_i32 s30, s66, s5
	s_mov_b32 m0, s30
	s_nop 0
	global_load_lds_dwordx4 v132, s[28:29]
	s_add_i32 m0, s30, 0x2000
	s_nop 0
	global_load_lds_dwordx4 v128, s[28:29]
	s_mov_b32 m0, s38
	s_nop 0
	global_load_lds_dwordx4 v134, s[26:27]
	s_mov_b32 m0, s39
	s_nop 0
	global_load_lds_dwordx4 v130, s[26:27]
	s_waitcnt vmcnt(8)
	s_waitcnt lgkmcnt(0)
	s_setprio 1
	s_barrier
	v_mfma_f32_16x16x32_bf16 v[60:63], v[152:155], v[184:187], v[60:63]
	v_mfma_f32_16x16x32_bf16 v[56:59], v[160:163], v[184:187], v[56:59]
	v_mfma_f32_16x16x32_bf16 v[44:47], v[152:155], v[192:195], v[44:47]
	v_mfma_f32_16x16x32_bf16 v[40:43], v[160:163], v[192:195], v[40:43]
	v_mfma_f32_16x16x32_bf16 v[28:31], v[152:155], v[200:203], v[28:31]
	v_mfma_f32_16x16x32_bf16 v[24:27], v[160:163], v[200:203], v[24:27]
	v_mfma_f32_16x16x32_bf16 v[12:15], v[152:155], v[208:211], v[12:15]
	v_mfma_f32_16x16x32_bf16 v[8:11], v[160:163], v[208:211], v[8:11]
	v_mfma_f32_16x16x32_bf16 v[60:63], v[156:159], v[188:191], v[60:63]
	v_mfma_f32_16x16x32_bf16 v[56:59], v[164:167], v[188:191], v[56:59]
	v_mfma_f32_16x16x32_bf16 v[44:47], v[156:159], v[196:199], v[44:47]
	v_mfma_f32_16x16x32_bf16 v[40:43], v[164:167], v[196:199], v[40:43]
	v_mfma_f32_16x16x32_bf16 v[28:31], v[156:159], v[204:207], v[28:31]
	v_mfma_f32_16x16x32_bf16 v[24:27], v[164:167], v[204:207], v[24:27]
	v_mfma_f32_16x16x32_bf16 v[12:15], v[156:159], v[212:215], v[12:15]
	v_mfma_f32_16x16x32_bf16 v[8:11], v[164:167], v[212:215], v[8:11]
	v_mfma_f32_16x16x32_bf16 v[52:55], v[168:171], v[184:187], v[52:55]
	v_mfma_f32_16x16x32_bf16 v[48:51], v[176:179], v[184:187], v[48:51]
	v_mfma_f32_16x16x32_bf16 v[36:39], v[168:171], v[192:195], v[36:39]
	v_mfma_f32_16x16x32_bf16 v[32:35], v[176:179], v[192:195], v[32:35]
	v_mfma_f32_16x16x32_bf16 v[20:23], v[168:171], v[200:203], v[20:23]
	v_mfma_f32_16x16x32_bf16 v[16:19], v[176:179], v[200:203], v[16:19]
	v_mfma_f32_16x16x32_bf16 v[4:7], v[168:171], v[208:211], v[4:7]
	v_mfma_f32_16x16x32_bf16 v[0:3], v[176:179], v[208:211], v[0:3]
	v_mfma_f32_16x16x32_bf16 v[52:55], v[172:175], v[188:191], v[52:55]
	v_mfma_f32_16x16x32_bf16 v[48:51], v[180:183], v[188:191], v[48:51]
	v_mfma_f32_16x16x32_bf16 v[36:39], v[172:175], v[196:199], v[36:39]
	v_mfma_f32_16x16x32_bf16 v[32:35], v[180:183], v[196:199], v[32:35]
	v_mfma_f32_16x16x32_bf16 v[20:23], v[172:175], v[204:207], v[20:23]
	v_mfma_f32_16x16x32_bf16 v[16:19], v[180:183], v[204:207], v[16:19]
	v_mfma_f32_16x16x32_bf16 v[4:7], v[172:175], v[212:215], v[4:7]
	v_mfma_f32_16x16x32_bf16 v[0:3], v[180:183], v[212:215], v[0:3]
	s_barrier
	s_setprio 0
	s_add_i32 s62, s62, 2
	s_add_u32 s56, s56, 0x2c0000
	s_addc_u32 s57, s57, 0
	s_add_u32 s24, s24, 0x800000
	s_addc_u32 s25, s25, 0
	s_cmp_gt_u32 s62, 29
	s_cbranch_scc0 .LBB0_553
	s_and_b64 vcc, exec, s[12:13]
	s_cbranch_vccz .LBB0_556
	s_barrier

.LBB0_630:
	s_mov_b32 s29, s15
	s_lshl_b64 s[30:31], s[28:29], 1
	s_add_u32 s30, s60, s30
	s_addc_u32 s31, s61, s31
	s_and_b64 s[36:37], exec, s[10:11]
	s_cselect_b32 s17, s31, s9
	s_cselect_b32 s29, s30, s8
	s_lshl_b64 s[34:35], s[34:35], 1
	s_add_u32 s34, s46, s34
	s_addc_u32 s35, s47, s35
	s_and_b64 s[10:11], exec, s[10:11]
	s_cselect_b32 s38, s35, s7
	s_cselect_b32 s39, s34, s6
	s_add_u32 s40, s6, 0x80000
	s_addc_u32 s41, s7, 0
	s_add_u32 s6, s8, 0x404000
	s_addc_u32 s7, s9, 0
	s_mov_b32 s42, -2
	ds_read_b128 v[128:131], v182
	ds_read_b128 v[132:135], v182 offset:1024
	ds_read_b128 v[136:139], v182 offset:2048
	ds_read_b128 v[140:143], v182 offset:3072
	ds_read_b128 v[144:147], v183
	ds_read_b128 v[148:151], v183 offset:1024
	ds_read_b128 v[152:155], v183 offset:2048
	ds_read_b128 v[156:159], v183 offset:3072
	s_add_u32 s8, s6, 0x3fc000
	s_addc_u32 s9, s7, 0
	s_cmpk_eq_i32 s42, 0x54
	s_cselect_b32 s36, s29, s8
	s_cselect_b32 s37, s17, s9
	s_cselect_b32 s10, s39, s40
	s_cselect_b32 s11, s38, s41
	s_add_u32 s8, s36, 0x400000
	s_addc_u32 s9, s37, 0
	s_add_i32 m0, s27, 0xc000
	ds_read_b128 v[174:177], v184
	ds_read_b128 v[188:191], v184 offset:1024
	ds_read_b128 v[192:195], v184 offset:2048
	ds_read_b128 v[196:199], v184 offset:3072
	ds_read_b128 v[200:203], v184 offset:4096
	ds_read_b128 v[204:207], v184 offset:5120
	ds_read_b128 v[208:211], v184 offset:6144
	ds_read_b128 v[212:215], v184 offset:7168
	global_load_lds_dwordx4 v168, s[6:7]
	s_add_i32 m0, s27, 0xe000
	s_nop 0
	global_load_lds_dwordx4 v170, s[6:7]
	s_waitcnt vmcnt(8)
	s_waitcnt lgkmcnt(0)
	s_setprio 1
	s_barrier
	v_mfma_f32_16x16x32_bf16 v[108:111], v[128:131], v[174:177], 0
	v_mfma_f32_16x16x32_bf16 v[104:107], v[136:139], v[174:177], 0
	v_mfma_f32_16x16x32_bf16 v[84:87], v[128:131], v[192:195], 0
	v_mfma_f32_16x16x32_bf16 v[80:83], v[136:139], v[192:195], 0
	v_mfma_f32_16x16x32_bf16 v[4:7], v[128:131], v[200:203], 0
	v_mfma_f32_16x16x32_bf16 v[0:3], v[136:139], v[200:203], 0
	v_mfma_f32_16x16x32_bf16 v[100:103], v[128:131], v[208:211], 0
	v_mfma_f32_16x16x32_bf16 v[96:99], v[136:139], v[208:211], 0
	v_mfma_f32_16x16x32_bf16 v[108:111], v[132:135], v[188:191], v[108:111]
	v_mfma_f32_16x16x32_bf16 v[104:107], v[140:143], v[188:191], v[104:107]
	v_mfma_f32_16x16x32_bf16 v[84:87], v[132:135], v[196:199], v[84:87]
	v_mfma_f32_16x16x32_bf16 v[80:83], v[140:143], v[196:199], v[80:83]
	v_mfma_f32_16x16x32_bf16 v[4:7], v[132:135], v[204:207], v[4:7]
	v_mfma_f32_16x16x32_bf16 v[0:3], v[140:143], v[204:207], v[0:3]
	v_mfma_f32_16x16x32_bf16 v[100:103], v[132:135], v[212:215], v[100:103]
	v_mfma_f32_16x16x32_bf16 v[96:99], v[140:143], v[212:215], v[96:99]
	v_mfma_f32_16x16x32_bf16 v[92:95], v[144:147], v[174:177], 0
	v_mfma_f32_16x16x32_bf16 v[88:91], v[152:155], v[174:177], 0
	v_mfma_f32_16x16x32_bf16 v[28:31], v[144:147], v[192:195], 0
	v_mfma_f32_16x16x32_bf16 v[24:27], v[152:155], v[192:195], 0
	v_mfma_f32_16x16x32_bf16 v[12:15], v[144:147], v[200:203], 0
	v_mfma_f32_16x16x32_bf16 v[8:11], v[152:155], v[200:203], 0
	v_mfma_f32_16x16x32_bf16 v[20:23], v[144:147], v[208:211], 0
	v_mfma_f32_16x16x32_bf16 v[16:19], v[152:155], v[208:211], 0
	v_mfma_f32_16x16x32_bf16 v[92:95], v[148:151], v[188:191], v[92:95]
	v_mfma_f32_16x16x32_bf16 v[88:91], v[156:159], v[188:191], v[88:91]
	v_mfma_f32_16x16x32_bf16 v[28:31], v[148:151], v[196:199], v[28:31]
	v_mfma_f32_16x16x32_bf16 v[24:27], v[156:159], v[196:199], v[24:27]
	v_mfma_f32_16x16x32_bf16 v[12:15], v[148:151], v[204:207], v[12:15]
	v_mfma_f32_16x16x32_bf16 v[8:11], v[156:159], v[204:207], v[8:11]
	v_mfma_f32_16x16x32_bf16 v[20:23], v[148:151], v[212:215], v[20:23]
	v_mfma_f32_16x16x32_bf16 v[16:19], v[156:159], v[212:215], v[16:19]
	s_barrier
	s_setprio 0
	s_add_i32 s43, s57, s4
	s_mov_b32 m0, s43
	ds_read_b128 v[174:177], v184 offset:16384
	ds_read_b128 v[188:191], v184 offset:17408
	ds_read_b128 v[192:195], v184 offset:18432
	ds_read_b128 v[196:199], v184 offset:19456
	ds_read_b128 v[200:203], v184 offset:20480
	ds_read_b128 v[204:207], v184 offset:21504
	ds_read_b128 v[208:211], v184 offset:22528
	ds_read_b128 v[212:215], v184 offset:23552
	global_load_lds_dwordx4 v162, s[10:11]
	s_add_i32 m0, s43, 0x2000
	s_add_u32 s44, s10, 0x4000
	s_addc_u32 s45, s11, 0
	s_add_i32 s43, s81, s4
	global_load_lds_dwordx4 v166, s[10:11]
	s_mov_b32 m0, s43
	s_nop 0
	global_load_lds_dwordx4 v162, s[44:45]
	s_add_i32 m0, s43, 0x2000
	s_nop 0
	global_load_lds_dwordx4 v166, s[44:45]
	s_mov_b32 m0, s27
	s_nop 0
	global_load_lds_dwordx4 v160, s[36:37]
	s_mov_b32 m0, s52
	s_nop 0
	global_load_lds_dwordx4 v164, s[36:37]
	s_waitcnt vmcnt(8)
	s_waitcnt lgkmcnt(0)
	s_setprio 1
	s_barrier
	v_mfma_f32_16x16x32_bf16 v[124:127], v[128:131], v[174:177], 0
	v_mfma_f32_16x16x32_bf16 v[120:123], v[136:139], v[174:177], 0
	v_mfma_f32_16x16x32_bf16 v[116:119], v[128:131], v[192:195], 0
	v_mfma_f32_16x16x32_bf16 v[112:115], v[136:139], v[192:195], 0
	v_mfma_f32_16x16x32_bf16 v[76:79], v[128:131], v[200:203], 0
	v_mfma_f32_16x16x32_bf16 v[72:75], v[136:139], v[200:203], 0
	v_mfma_f32_16x16x32_bf16 v[68:71], v[128:131], v[208:211], 0
	v_mfma_f32_16x16x32_bf16 v[64:67], v[136:139], v[208:211], 0
	v_mfma_f32_16x16x32_bf16 v[124:127], v[132:135], v[188:191], v[124:127]
	v_mfma_f32_16x16x32_bf16 v[120:123], v[140:143], v[188:191], v[120:123]
	v_mfma_f32_16x16x32_bf16 v[116:119], v[132:135], v[196:199], v[116:119]
	v_mfma_f32_16x16x32_bf16 v[112:115], v[140:143], v[196:199], v[112:115]
	v_mfma_f32_16x16x32_bf16 v[76:79], v[132:135], v[204:207], v[76:79]
	v_mfma_f32_16x16x32_bf16 v[72:75], v[140:143], v[204:207], v[72:75]
	v_mfma_f32_16x16x32_bf16 v[68:71], v[132:135], v[212:215], v[68:71]
	v_mfma_f32_16x16x32_bf16 v[64:67], v[140:143], v[212:215], v[64:67]
	v_mfma_f32_16x16x32_bf16 v[48:51], v[144:147], v[174:177], 0
	v_mfma_f32_16x16x32_bf16 v[36:39], v[152:155], v[174:177], 0
	v_mfma_f32_16x16x32_bf16 v[40:43], v[144:147], v[192:195], 0
	v_mfma_f32_16x16x32_bf16 v[32:35], v[152:155], v[192:195], 0
	v_mfma_f32_16x16x32_bf16 v[52:55], v[144:147], v[200:203], 0
	v_mfma_f32_16x16x32_bf16 v[44:47], v[152:155], v[200:203], 0
	v_mfma_f32_16x16x32_bf16 v[60:63], v[144:147], v[208:211], 0
	v_mfma_f32_16x16x32_bf16 v[56:59], v[152:155], v[208:211], 0
	v_mfma_f32_16x16x32_bf16 v[48:51], v[148:151], v[188:191], v[48:51]
	v_mfma_f32_16x16x32_bf16 v[36:39], v[156:159], v[188:191], v[36:39]
	v_mfma_f32_16x16x32_bf16 v[40:43], v[148:151], v[196:199], v[40:43]
	v_mfma_f32_16x16x32_bf16 v[32:35], v[156:159], v[196:199], v[32:35]
	v_mfma_f32_16x16x32_bf16 v[52:55], v[148:151], v[204:207], v[52:55]
	v_mfma_f32_16x16x32_bf16 v[44:47], v[156:159], v[204:207], v[44:47]
	v_mfma_f32_16x16x32_bf16 v[60:63], v[148:151], v[212:215], v[60:63]
	v_mfma_f32_16x16x32_bf16 v[56:59], v[156:159], v[212:215], v[56:59]
	s_barrier
	s_setprio 0
	s_branch .Lzmid2

.Lzmid2:
	s_add_i32 s82, 0, 0x18000
	s_add_i32 s83, 0, 0x1c000
	v_add_u32_e32 v140, s82, v181
	v_add_u32_e32 v156, s83, v181
	ds_read_b128 v[128:131], v140
	ds_read_b128 v[132:135], v140 offset:1024
	ds_read_b128 v[136:139], v140 offset:2048
	ds_read_b128 v[140:143], v140 offset:3072
	ds_read_b128 v[144:147], v156
	ds_read_b128 v[148:151], v156 offset:1024
	ds_read_b128 v[152:155], v156 offset:2048
	ds_read_b128 v[156:159], v156 offset:3072
	s_add_u32 s36, s36, 0x4000
	s_addc_u32 s37, s37, 0
	s_mov_b32 m0, s53
	ds_read_b128 v[174:177], v184 offset:32768
	ds_read_b128 v[188:191], v184 offset:33792
	ds_read_b128 v[192:195], v184 offset:34816
	ds_read_b128 v[196:199], v184 offset:35840
	ds_read_b128 v[200:203], v184 offset:36864
	ds_read_b128 v[204:207], v184 offset:37888
	ds_read_b128 v[208:211], v184 offset:38912
	ds_read_b128 v[212:215], v184 offset:39936
	global_load_lds_dwordx4 v160, s[36:37]
	s_mov_b32 m0, s54
	s_nop 0
	global_load_lds_dwordx4 v164, s[36:37]
	s_waitcnt vmcnt(8)
	s_waitcnt lgkmcnt(0)
	s_setprio 1
	s_barrier
	v_mfma_f32_16x16x32_bf16 v[108:111], v[128:131], v[174:177], v[108:111]
	v_mfma_f32_16x16x32_bf16 v[104:107], v[136:139], v[174:177], v[104:107]
	v_mfma_f32_16x16x32_bf16 v[84:87], v[128:131], v[192:195], v[84:87]
	v_mfma_f32_16x16x32_bf16 v[80:83], v[136:139], v[192:195], v[80:83]
	v_mfma_f32_16x16x32_bf16 v[4:7], v[128:131], v[200:203], v[4:7]
	v_mfma_f32_16x16x32_bf16 v[0:3], v[136:139], v[200:203], v[0:3]
	v_mfma_f32_16x16x32_bf16 v[100:103], v[128:131], v[208:211], v[100:103]
	v_mfma_f32_16x16x32_bf16 v[96:99], v[136:139], v[208:211], v[96:99]
	v_mfma_f32_16x16x32_bf16 v[108:111], v[132:135], v[188:191], v[108:111]
	v_mfma_f32_16x16x32_bf16 v[104:107], v[140:143], v[188:191], v[104:107]
	v_mfma_f32_16x16x32_bf16 v[84:87], v[132:135], v[196:199], v[84:87]
	v_mfma_f32_16x16x32_bf16 v[80:83], v[140:143], v[196:199], v[80:83]
	v_mfma_f32_16x16x32_bf16 v[4:7], v[132:135], v[204:207], v[4:7]
	v_mfma_f32_16x16x32_bf16 v[0:3], v[140:143], v[204:207], v[0:3]
	v_mfma_f32_16x16x32_bf16 v[100:103], v[132:135], v[212:215], v[100:103]
	v_mfma_f32_16x16x32_bf16 v[96:99], v[140:143], v[212:215], v[96:99]
	v_mfma_f32_16x16x32_bf16 v[92:95], v[144:147], v[174:177], v[92:95]
	v_mfma_f32_16x16x32_bf16 v[88:91], v[152:155], v[174:177], v[88:91]
	v_mfma_f32_16x16x32_bf16 v[28:31], v[144:147], v[192:195], v[28:31]
	v_mfma_f32_16x16x32_bf16 v[24:27], v[152:155], v[192:195], v[24:27]
	v_mfma_f32_16x16x32_bf16 v[12:15], v[144:147], v[200:203], v[12:15]
	v_mfma_f32_16x16x32_bf16 v[8:11], v[152:155], v[200:203], v[8:11]
	v_mfma_f32_16x16x32_bf16 v[20:23], v[144:147], v[208:211], v[20:23]
	v_mfma_f32_16x16x32_bf16 v[16:19], v[152:155], v[208:211], v[16:19]
	v_mfma_f32_16x16x32_bf16 v[92:95], v[148:151], v[188:191], v[92:95]
	v_mfma_f32_16x16x32_bf16 v[88:91], v[156:159], v[188:191], v[88:91]
	v_mfma_f32_16x16x32_bf16 v[28:31], v[148:151], v[196:199], v[28:31]
	v_mfma_f32_16x16x32_bf16 v[24:27], v[156:159], v[196:199], v[24:27]
	v_mfma_f32_16x16x32_bf16 v[12:15], v[148:151], v[204:207], v[12:15]
	v_mfma_f32_16x16x32_bf16 v[8:11], v[156:159], v[204:207], v[8:11]
	v_mfma_f32_16x16x32_bf16 v[20:23], v[148:151], v[212:215], v[20:23]
	v_mfma_f32_16x16x32_bf16 v[16:19], v[156:159], v[212:215], v[16:19]
	s_barrier
	s_setprio 0
	s_add_u32 s36, s10, 0x40000
	s_addc_u32 s37, s11, 0
	s_add_i32 s43, s82, s4
	s_mov_b32 m0, s43
	ds_read_b128 v[174:177], v184 offset:49152
	ds_read_b128 v[188:191], v184 offset:50176
	ds_read_b128 v[192:195], v184 offset:51200
	ds_read_b128 v[196:199], v184 offset:52224
	ds_read_b128 v[200:203], v184 offset:53248
	ds_read_b128 v[204:207], v184 offset:54272
	ds_read_b128 v[208:211], v184 offset:55296
	ds_read_b128 v[212:215], v184 offset:56320
	global_load_lds_dwordx4 v162, s[36:37]
	s_add_i32 m0, s43, 0x2000
	s_add_u32 s10, s10, 0x44000
	global_load_lds_dwordx4 v166, s[36:37]
	s_addc_u32 s11, s11, 0
	s_add_i32 s36, s83, s4
	s_mov_b32 m0, s36
	s_nop 0
	global_load_lds_dwordx4 v162, s[10:11]
	s_add_i32 m0, s36, 0x2000
	s_nop 0
	global_load_lds_dwordx4 v166, s[10:11]
	s_mov_b32 m0, s50
	s_nop 0
	global_load_lds_dwordx4 v160, s[8:9]
	s_mov_b32 m0, s51
	s_nop 0
	global_load_lds_dwordx4 v164, s[8:9]
	s_waitcnt vmcnt(8)
	s_waitcnt lgkmcnt(0)
	s_setprio 1
	s_barrier
	v_mfma_f32_16x16x32_bf16 v[124:127], v[128:131], v[174:177], v[124:127]
	v_mfma_f32_16x16x32_bf16 v[120:123], v[136:139], v[174:177], v[120:123]
	v_mfma_f32_16x16x32_bf16 v[116:119], v[128:131], v[192:195], v[116:119]
	v_mfma_f32_16x16x32_bf16 v[112:115], v[136:139], v[192:195], v[112:115]
	v_mfma_f32_16x16x32_bf16 v[76:79], v[128:131], v[200:203], v[76:79]
	v_mfma_f32_16x16x32_bf16 v[72:75], v[136:139], v[200:203], v[72:75]
	v_mfma_f32_16x16x32_bf16 v[68:71], v[128:131], v[208:211], v[68:71]
	v_mfma_f32_16x16x32_bf16 v[64:67], v[136:139], v[208:211], v[64:67]
	v_mfma_f32_16x16x32_bf16 v[124:127], v[132:135], v[188:191], v[124:127]
	v_mfma_f32_16x16x32_bf16 v[120:123], v[140:143], v[188:191], v[120:123]
	v_mfma_f32_16x16x32_bf16 v[116:119], v[132:135], v[196:199], v[116:119]
	v_mfma_f32_16x16x32_bf16 v[112:115], v[140:143], v[196:199], v[112:115]
	v_mfma_f32_16x16x32_bf16 v[76:79], v[132:135], v[204:207], v[76:79]
	v_mfma_f32_16x16x32_bf16 v[72:75], v[140:143], v[204:207], v[72:75]
	v_mfma_f32_16x16x32_bf16 v[68:71], v[132:135], v[212:215], v[68:71]
	v_mfma_f32_16x16x32_bf16 v[64:67], v[140:143], v[212:215], v[64:67]
	v_mfma_f32_16x16x32_bf16 v[48:51], v[144:147], v[174:177], v[48:51]
	v_mfma_f32_16x16x32_bf16 v[36:39], v[152:155], v[174:177], v[36:39]
	v_mfma_f32_16x16x32_bf16 v[40:43], v[144:147], v[192:195], v[40:43]
	v_mfma_f32_16x16x32_bf16 v[32:35], v[152:155], v[192:195], v[32:35]
	v_mfma_f32_16x16x32_bf16 v[52:55], v[144:147], v[200:203], v[52:55]
	v_mfma_f32_16x16x32_bf16 v[44:47], v[152:155], v[200:203], v[44:47]
	v_mfma_f32_16x16x32_bf16 v[60:63], v[144:147], v[208:211], v[60:63]
	v_mfma_f32_16x16x32_bf16 v[56:59], v[152:155], v[208:211], v[56:59]
	v_mfma_f32_16x16x32_bf16 v[48:51], v[148:151], v[188:191], v[48:51]
	v_mfma_f32_16x16x32_bf16 v[36:39], v[156:159], v[188:191], v[36:39]
	v_mfma_f32_16x16x32_bf16 v[40:43], v[148:151], v[196:199], v[40:43]
	v_mfma_f32_16x16x32_bf16 v[32:35], v[156:159], v[196:199], v[32:35]
	v_mfma_f32_16x16x32_bf16 v[52:55], v[148:151], v[204:207], v[52:55]
	v_mfma_f32_16x16x32_bf16 v[44:47], v[156:159], v[204:207], v[44:47]
	v_mfma_f32_16x16x32_bf16 v[60:63], v[148:151], v[212:215], v[60:63]
	v_mfma_f32_16x16x32_bf16 v[56:59], v[156:159], v[212:215], v[56:59]
	s_barrier
	s_setprio 0
	s_add_i32 s42, s42, 2
	s_add_u32 s40, s40, 0x80000
	s_addc_u32 s41, s41, 0
	s_add_u32 s6, s6, 0x800000
	s_addc_u32 s7, s7, 0
	s_cmpk_gt_u32 s42, 0x55
	s_cbranch_scc0 .LBB0_631
	s_and_b64 vcc, exec, s[24:25]
	s_cbranch_vccz .LBB0_634
	s_barrier

.LBB0_731:
	s_mov_b32 s17, s9
	s_lshl_b64 s[20:21], s[16:17], 1
	s_add_u32 s20, s58, s20
	s_addc_u32 s21, s59, s21
	s_and_b64 s[22:23], s[6:7], exec
	s_mov_b32 s19, s9
	s_cselect_b32 s17, s21, s27
	s_cselect_b32 s54, s20, s26
	s_lshl_b64 s[22:23], s[18:19], 1
	s_add_u32 s22, s72, s22
	s_addc_u32 s23, s73, s23
	s_and_b64 s[28:29], s[6:7], exec
	s_cselect_b32 s19, s23, s25
	s_cselect_b32 s55, s22, s24
	s_add_u32 s56, s24, 0x1b0000
	s_addc_u32 s74, s25, 0
	s_add_u32 s24, s26, 0x404000
	s_addc_u32 s25, s27, 0
	s_mov_b32 s75, -2
	ds_read_b128 v[144:147], v153
	ds_read_b128 v[156:159], v153 offset:1024
	ds_read_b128 v[160:163], v153 offset:2048
	ds_read_b128 v[164:167], v153 offset:3072
	ds_read_b128 v[168:171], v154
	ds_read_b128 v[172:175], v154 offset:1024
	ds_read_b128 v[176:179], v154 offset:2048
	ds_read_b128 v[180:183], v154 offset:3072
	s_add_u32 s26, s24, 0x3fc000
	s_addc_u32 s27, s25, 0
	s_cmp_eq_u32 s75, 28
	s_cselect_b32 s30, s54, s26
	s_cselect_b32 s31, s17, s27
	s_cselect_b32 s28, s55, s56
	s_cselect_b32 s29, s19, s74
	s_add_u32 s26, s30, 0x400000
	s_addc_u32 s27, s31, 0
	s_add_i32 m0, s33, 0xc000
	ds_read_b128 v[184:187], v155
	ds_read_b128 v[188:191], v155 offset:1024
	ds_read_b128 v[192:195], v155 offset:2048
	ds_read_b128 v[196:199], v155 offset:3072
	ds_read_b128 v[200:203], v155 offset:4096
	ds_read_b128 v[204:207], v155 offset:5120
	ds_read_b128 v[208:211], v155 offset:6144
	ds_read_b128 v[212:215], v155 offset:7168
	global_load_lds_dwordx4 v136, s[24:25]
	s_add_i32 m0, s33, 0xe000
	s_nop 0
	global_load_lds_dwordx4 v138, s[24:25]
	s_waitcnt vmcnt(8)
	s_waitcnt lgkmcnt(0)
	s_setprio 1
	s_barrier
	v_mfma_f32_16x16x32_bf16 v[76:79], v[144:147], v[184:187], 0
	v_mfma_f32_16x16x32_bf16 v[72:75], v[160:163], v[184:187], 0
	v_mfma_f32_16x16x32_bf16 v[68:71], v[144:147], v[192:195], 0
	v_mfma_f32_16x16x32_bf16 v[64:67], v[160:163], v[192:195], 0
	v_mfma_f32_16x16x32_bf16 v[56:59], v[144:147], v[200:203], 0
	v_mfma_f32_16x16x32_bf16 v[52:55], v[160:163], v[200:203], 0
	v_mfma_f32_16x16x32_bf16 v[44:47], v[144:147], v[208:211], 0
	v_mfma_f32_16x16x32_bf16 v[40:43], v[160:163], v[208:211], 0
	v_mfma_f32_16x16x32_bf16 v[76:79], v[156:159], v[188:191], v[76:79]
	v_mfma_f32_16x16x32_bf16 v[72:75], v[164:167], v[188:191], v[72:75]
	v_mfma_f32_16x16x32_bf16 v[68:71], v[156:159], v[196:199], v[68:71]
	v_mfma_f32_16x16x32_bf16 v[64:67], v[164:167], v[196:199], v[64:67]
	v_mfma_f32_16x16x32_bf16 v[56:59], v[156:159], v[204:207], v[56:59]
	v_mfma_f32_16x16x32_bf16 v[52:55], v[164:167], v[204:207], v[52:55]
	v_mfma_f32_16x16x32_bf16 v[44:47], v[156:159], v[212:215], v[44:47]
	v_mfma_f32_16x16x32_bf16 v[40:43], v[164:167], v[212:215], v[40:43]
	v_mfma_f32_16x16x32_bf16 v[124:127], v[168:171], v[184:187], 0
	v_mfma_f32_16x16x32_bf16 v[120:123], v[176:179], v[184:187], 0
	v_mfma_f32_16x16x32_bf16 v[116:119], v[168:171], v[192:195], 0
	v_mfma_f32_16x16x32_bf16 v[112:115], v[176:179], v[192:195], 0
	v_mfma_f32_16x16x32_bf16 v[108:111], v[168:171], v[200:203], 0
	v_mfma_f32_16x16x32_bf16 v[104:107], v[176:179], v[200:203], 0
	v_mfma_f32_16x16x32_bf16 v[100:103], v[168:171], v[208:211], 0
	v_mfma_f32_16x16x32_bf16 v[96:99], v[176:179], v[208:211], 0
	v_mfma_f32_16x16x32_bf16 v[124:127], v[172:175], v[188:191], v[124:127]
	v_mfma_f32_16x16x32_bf16 v[120:123], v[180:183], v[188:191], v[120:123]
	v_mfma_f32_16x16x32_bf16 v[116:119], v[172:175], v[196:199], v[116:119]
	v_mfma_f32_16x16x32_bf16 v[112:115], v[180:183], v[196:199], v[112:115]
	v_mfma_f32_16x16x32_bf16 v[108:111], v[172:175], v[204:207], v[108:111]
	v_mfma_f32_16x16x32_bf16 v[104:107], v[180:183], v[204:207], v[104:107]
	v_mfma_f32_16x16x32_bf16 v[100:103], v[172:175], v[212:215], v[100:103]
	v_mfma_f32_16x16x32_bf16 v[96:99], v[180:183], v[212:215], v[96:99]
	s_barrier
	s_setprio 0
	s_add_i32 s78, s57, s5
	s_mov_b32 m0, s78
	ds_read_b128 v[184:187], v155 offset:16384
	ds_read_b128 v[188:191], v155 offset:17408
	ds_read_b128 v[192:195], v155 offset:18432
	ds_read_b128 v[196:199], v155 offset:19456
	ds_read_b128 v[200:203], v155 offset:20480
	ds_read_b128 v[204:207], v155 offset:21504
	ds_read_b128 v[208:211], v155 offset:22528
	ds_read_b128 v[212:215], v155 offset:23552
	global_load_lds_dwordx4 v132, s[28:29]
	s_add_i32 m0, s78, 0x2000
	s_add_u32 s78, s28, 0x4000
	s_addc_u32 s79, s29, 0
	s_add_i32 s80, s81, s5
	global_load_lds_dwordx4 v128, s[28:29]
	s_mov_b32 m0, s80
	s_nop 0
	global_load_lds_dwordx4 v132, s[78:79]
	s_add_i32 m0, s80, 0x2000
	s_nop 0
	global_load_lds_dwordx4 v128, s[78:79]
	s_mov_b32 m0, s33
	s_nop 0
	global_load_lds_dwordx4 v134, s[30:31]
	s_mov_b32 m0, s34
	s_nop 0
	global_load_lds_dwordx4 v130, s[30:31]
	s_waitcnt vmcnt(8)
	s_waitcnt lgkmcnt(0)
	s_setprio 1
	s_barrier
	v_mfma_f32_16x16x32_bf16 v[28:31], v[144:147], v[184:187], 0
	v_mfma_f32_16x16x32_bf16 v[24:27], v[160:163], v[184:187], 0
	v_mfma_f32_16x16x32_bf16 v[20:23], v[144:147], v[192:195], 0
	v_mfma_f32_16x16x32_bf16 v[16:19], v[160:163], v[192:195], 0
	v_mfma_f32_16x16x32_bf16 v[12:15], v[144:147], v[200:203], 0
	v_mfma_f32_16x16x32_bf16 v[8:11], v[160:163], v[200:203], 0
	v_mfma_f32_16x16x32_bf16 v[4:7], v[144:147], v[208:211], 0
	v_mfma_f32_16x16x32_bf16 v[0:3], v[160:163], v[208:211], 0
	v_mfma_f32_16x16x32_bf16 v[28:31], v[156:159], v[188:191], v[28:31]
	v_mfma_f32_16x16x32_bf16 v[24:27], v[164:167], v[188:191], v[24:27]
	v_mfma_f32_16x16x32_bf16 v[20:23], v[156:159], v[196:199], v[20:23]
	v_mfma_f32_16x16x32_bf16 v[16:19], v[164:167], v[196:199], v[16:19]
	v_mfma_f32_16x16x32_bf16 v[12:15], v[156:159], v[204:207], v[12:15]
	v_mfma_f32_16x16x32_bf16 v[8:11], v[164:167], v[204:207], v[8:11]
	v_mfma_f32_16x16x32_bf16 v[4:7], v[156:159], v[212:215], v[4:7]
	v_mfma_f32_16x16x32_bf16 v[0:3], v[164:167], v[212:215], v[0:3]
	v_mfma_f32_16x16x32_bf16 v[92:95], v[168:171], v[184:187], 0
	v_mfma_f32_16x16x32_bf16 v[88:91], v[176:179], v[184:187], 0
	v_mfma_f32_16x16x32_bf16 v[84:87], v[168:171], v[192:195], 0
	v_mfma_f32_16x16x32_bf16 v[80:83], v[176:179], v[192:195], 0
	v_mfma_f32_16x16x32_bf16 v[60:63], v[168:171], v[200:203], 0
	v_mfma_f32_16x16x32_bf16 v[48:51], v[176:179], v[200:203], 0
	v_mfma_f32_16x16x32_bf16 v[36:39], v[168:171], v[208:211], 0
	v_mfma_f32_16x16x32_bf16 v[32:35], v[176:179], v[208:211], 0
	v_mfma_f32_16x16x32_bf16 v[92:95], v[172:175], v[188:191], v[92:95]
	v_mfma_f32_16x16x32_bf16 v[88:91], v[180:183], v[188:191], v[88:91]
	v_mfma_f32_16x16x32_bf16 v[84:87], v[172:175], v[196:199], v[84:87]
	v_mfma_f32_16x16x32_bf16 v[80:83], v[180:183], v[196:199], v[80:83]
	v_mfma_f32_16x16x32_bf16 v[60:63], v[172:175], v[204:207], v[60:63]
	v_mfma_f32_16x16x32_bf16 v[48:51], v[180:183], v[204:207], v[48:51]
	v_mfma_f32_16x16x32_bf16 v[36:39], v[172:175], v[212:215], v[36:39]
	v_mfma_f32_16x16x32_bf16 v[32:35], v[180:183], v[212:215], v[32:35]
	s_barrier
	s_setprio 0
	s_branch .Lzmid3

.Lzmid3:
	v_add_u32_e32 v148, s82, v152
	ds_read_b128 v[144:147], v148
	ds_read_b128 v[156:159], v148 offset:1024
	ds_read_b128 v[160:163], v148 offset:2048
	ds_read_b128 v[164:167], v148 offset:3072
	v_add_u32_e32 v148, s83, v152
	ds_read_b128 v[168:171], v148
	ds_read_b128 v[172:175], v148 offset:1024
	ds_read_b128 v[176:179], v148 offset:2048
	ds_read_b128 v[180:183], v148 offset:3072
	s_add_u32 s30, s30, 0x4000
	s_addc_u32 s31, s31, 0
	s_mov_b32 m0, s35
	ds_read_b128 v[184:187], v155 offset:32768
	ds_read_b128 v[188:191], v155 offset:33792
	ds_read_b128 v[192:195], v155 offset:34816
	ds_read_b128 v[196:199], v155 offset:35840
	ds_read_b128 v[200:203], v155 offset:36864
	ds_read_b128 v[204:207], v155 offset:37888
	ds_read_b128 v[208:211], v155 offset:38912
	ds_read_b128 v[212:215], v155 offset:39936
	global_load_lds_dwordx4 v134, s[30:31]
	s_mov_b32 m0, s36
	s_nop 0
	global_load_lds_dwordx4 v130, s[30:31]
	s_waitcnt vmcnt(8)
	s_waitcnt lgkmcnt(0)
	s_setprio 1
	s_barrier
	v_mfma_f32_16x16x32_bf16 v[76:79], v[144:147], v[184:187], v[76:79]
	v_mfma_f32_16x16x32_bf16 v[72:75], v[160:163], v[184:187], v[72:75]
	v_mfma_f32_16x16x32_bf16 v[68:71], v[144:147], v[192:195], v[68:71]
	v_mfma_f32_16x16x32_bf16 v[64:67], v[160:163], v[192:195], v[64:67]
	v_mfma_f32_16x16x32_bf16 v[56:59], v[144:147], v[200:203], v[56:59]
	v_mfma_f32_16x16x32_bf16 v[52:55], v[160:163], v[200:203], v[52:55]
	v_mfma_f32_16x16x32_bf16 v[44:47], v[144:147], v[208:211], v[44:47]
	v_mfma_f32_16x16x32_bf16 v[40:43], v[160:163], v[208:211], v[40:43]
	v_mfma_f32_16x16x32_bf16 v[76:79], v[156:159], v[188:191], v[76:79]
	v_mfma_f32_16x16x32_bf16 v[72:75], v[164:167], v[188:191], v[72:75]
	v_mfma_f32_16x16x32_bf16 v[68:71], v[156:159], v[196:199], v[68:71]
	v_mfma_f32_16x16x32_bf16 v[64:67], v[164:167], v[196:199], v[64:67]
	v_mfma_f32_16x16x32_bf16 v[56:59], v[156:159], v[204:207], v[56:59]
	v_mfma_f32_16x16x32_bf16 v[52:55], v[164:167], v[204:207], v[52:55]
	v_mfma_f32_16x16x32_bf16 v[44:47], v[156:159], v[212:215], v[44:47]
	v_mfma_f32_16x16x32_bf16 v[40:43], v[164:167], v[212:215], v[40:43]
	v_mfma_f32_16x16x32_bf16 v[124:127], v[168:171], v[184:187], v[124:127]
	v_mfma_f32_16x16x32_bf16 v[120:123], v[176:179], v[184:187], v[120:123]
	v_mfma_f32_16x16x32_bf16 v[116:119], v[168:171], v[192:195], v[116:119]
	v_mfma_f32_16x16x32_bf16 v[112:115], v[176:179], v[192:195], v[112:115]
	v_mfma_f32_16x16x32_bf16 v[108:111], v[168:171], v[200:203], v[108:111]
	v_mfma_f32_16x16x32_bf16 v[104:107], v[176:179], v[200:203], v[104:107]
	v_mfma_f32_16x16x32_bf16 v[100:103], v[168:171], v[208:211], v[100:103]
	v_mfma_f32_16x16x32_bf16 v[96:99], v[176:179], v[208:211], v[96:99]
	v_mfma_f32_16x16x32_bf16 v[124:127], v[172:175], v[188:191], v[124:127]
	v_mfma_f32_16x16x32_bf16 v[120:123], v[180:183], v[188:191], v[120:123]
	v_mfma_f32_16x16x32_bf16 v[116:119], v[172:175], v[196:199], v[116:119]
	v_mfma_f32_16x16x32_bf16 v[112:115], v[180:183], v[196:199], v[112:115]
	v_mfma_f32_16x16x32_bf16 v[108:111], v[172:175], v[204:207], v[108:111]
	v_mfma_f32_16x16x32_bf16 v[104:107], v[180:183], v[204:207], v[104:107]
	v_mfma_f32_16x16x32_bf16 v[100:103], v[172:175], v[212:215], v[100:103]
	v_mfma_f32_16x16x32_bf16 v[96:99], v[180:183], v[212:215], v[96:99]
	s_barrier
	s_setprio 0
	s_add_u32 s30, s28, 0xd8000
	s_addc_u32 s31, s29, 0
	s_add_i32 s78, s82, s5
	s_mov_b32 m0, s78
	ds_read_b128 v[184:187], v155 offset:49152
	ds_read_b128 v[188:191], v155 offset:50176
	ds_read_b128 v[192:195], v155 offset:51200
	ds_read_b128 v[196:199], v155 offset:52224
	ds_read_b128 v[200:203], v155 offset:53248
	ds_read_b128 v[204:207], v155 offset:54272
	ds_read_b128 v[208:211], v155 offset:55296
	ds_read_b128 v[212:215], v155 offset:56320
	global_load_lds_dwordx4 v132, s[30:31]
	s_add_i32 m0, s78, 0x2000
	s_add_u32 s28, s28, 0xdc000
	global_load_lds_dwordx4 v128, s[30:31]
	s_addc_u32 s29, s29, 0
	s_add_i32 s30, s83, s5
	s_mov_b32 m0, s30
	s_nop 0
	global_load_lds_dwordx4 v132, s[28:29]
	s_add_i32 m0, s30, 0x2000
	s_nop 0
	global_load_lds_dwordx4 v128, s[28:29]
	s_mov_b32 m0, s44
	s_nop 0
	global_load_lds_dwordx4 v134, s[26:27]
	s_mov_b32 m0, s45
	s_nop 0
	global_load_lds_dwordx4 v130, s[26:27]
	s_waitcnt vmcnt(8)
	s_waitcnt lgkmcnt(0)
	s_setprio 1
	s_barrier
	v_mfma_f32_16x16x32_bf16 v[28:31], v[144:147], v[184:187], v[28:31]
	v_mfma_f32_16x16x32_bf16 v[24:27], v[160:163], v[184:187], v[24:27]
	v_mfma_f32_16x16x32_bf16 v[20:23], v[144:147], v[192:195], v[20:23]
	v_mfma_f32_16x16x32_bf16 v[16:19], v[160:163], v[192:195], v[16:19]
	v_mfma_f32_16x16x32_bf16 v[12:15], v[144:147], v[200:203], v[12:15]
	v_mfma_f32_16x16x32_bf16 v[8:11], v[160:163], v[200:203], v[8:11]
	v_mfma_f32_16x16x32_bf16 v[4:7], v[144:147], v[208:211], v[4:7]
	v_mfma_f32_16x16x32_bf16 v[0:3], v[160:163], v[208:211], v[0:3]
	v_mfma_f32_16x16x32_bf16 v[28:31], v[156:159], v[188:191], v[28:31]
	v_mfma_f32_16x16x32_bf16 v[24:27], v[164:167], v[188:191], v[24:27]
	v_mfma_f32_16x16x32_bf16 v[20:23], v[156:159], v[196:199], v[20:23]
	v_mfma_f32_16x16x32_bf16 v[16:19], v[164:167], v[196:199], v[16:19]
	v_mfma_f32_16x16x32_bf16 v[12:15], v[156:159], v[204:207], v[12:15]
	v_mfma_f32_16x16x32_bf16 v[8:11], v[164:167], v[204:207], v[8:11]
	v_mfma_f32_16x16x32_bf16 v[4:7], v[156:159], v[212:215], v[4:7]
	v_mfma_f32_16x16x32_bf16 v[0:3], v[164:167], v[212:215], v[0:3]
	v_mfma_f32_16x16x32_bf16 v[92:95], v[168:171], v[184:187], v[92:95]
	v_mfma_f32_16x16x32_bf16 v[88:91], v[176:179], v[184:187], v[88:91]
	v_mfma_f32_16x16x32_bf16 v[84:87], v[168:171], v[192:195], v[84:87]
	v_mfma_f32_16x16x32_bf16 v[80:83], v[176:179], v[192:195], v[80:83]
	v_mfma_f32_16x16x32_bf16 v[60:63], v[168:171], v[200:203], v[60:63]
	v_mfma_f32_16x16x32_bf16 v[48:51], v[176:179], v[200:203], v[48:51]
	v_mfma_f32_16x16x32_bf16 v[36:39], v[168:171], v[208:211], v[36:39]
	v_mfma_f32_16x16x32_bf16 v[32:35], v[176:179], v[208:211], v[32:35]
	v_mfma_f32_16x16x32_bf16 v[92:95], v[172:175], v[188:191], v[92:95]
	v_mfma_f32_16x16x32_bf16 v[88:91], v[180:183], v[188:191], v[88:91]
	v_mfma_f32_16x16x32_bf16 v[84:87], v[172:175], v[196:199], v[84:87]
	v_mfma_f32_16x16x32_bf16 v[80:83], v[180:183], v[196:199], v[80:83]
	v_mfma_f32_16x16x32_bf16 v[60:63], v[172:175], v[204:207], v[60:63]
	v_mfma_f32_16x16x32_bf16 v[48:51], v[180:183], v[204:207], v[48:51]
	v_mfma_f32_16x16x32_bf16 v[36:39], v[172:175], v[212:215], v[36:39]
	v_mfma_f32_16x16x32_bf16 v[32:35], v[180:183], v[212:215], v[32:35]
	s_barrier
	s_setprio 0
	s_add_i32 s75, s75, 2
	s_add_u32 s56, s56, 0x1b0000
	s_addc_u32 s74, s74, 0
	s_add_u32 s24, s24, 0x800000
	s_addc_u32 s25, s25, 0
	s_cmp_gt_u32 s75, 29
	s_cbranch_scc0 .LBB0_732
	s_and_b64 vcc, exec, s[12:13]
	s_cbranch_vccz .LBB0_735
	s_barrier

.LBB0_1281:
	s_mov_b32 s31, s13
	s_lshl_b64 s[34:35], s[30:31], 1
	s_add_u32 s34, s64, s34
	s_addc_u32 s35, s65, s35
	s_and_b64 s[38:39], exec, s[10:11]
	s_cselect_b32 s12, s35, s9
	s_cselect_b32 s15, s34, s8
	s_lshl_b64 s[36:37], s[36:37], 1
	s_add_u32 s36, s91, s36
	s_addc_u32 s37, s92, s37
	s_and_b64 s[10:11], exec, s[10:11]
	s_cselect_b32 s31, s37, s7
	s_cselect_b32 s41, s36, s6
	s_add_u32 s42, s6, 0x80000
	s_addc_u32 s43, s7, 0
	s_add_u32 s6, s8, 0x404000
	s_addc_u32 s7, s9, 0
	s_mov_b32 s44, -2
	ds_read_b128 v[128:131], v180
	ds_read_b128 v[132:135], v180 offset:1024
	ds_read_b128 v[136:139], v180 offset:2048
	ds_read_b128 v[140:143], v180 offset:3072
	ds_read_b128 v[144:147], v181
	ds_read_b128 v[148:151], v181 offset:1024
	ds_read_b128 v[152:155], v181 offset:2048
	ds_read_b128 v[156:159], v181 offset:3072
	s_add_u32 s8, s6, 0x3fc000
	s_addc_u32 s9, s7, 0
	s_cmp_eq_u32 s44, 28
	s_cselect_b32 s38, s15, s8
	s_cselect_b32 s39, s12, s9
	s_cselect_b32 s10, s41, s42
	s_cselect_b32 s11, s31, s43
	s_add_u32 s8, s38, 0x400000
	s_addc_u32 s9, s39, 0
	s_add_i32 m0, s29, 0xc000
	ds_read_b128 v[186:189], v182
	ds_read_b128 v[190:193], v182 offset:1024
	ds_read_b128 v[194:197], v182 offset:2048
	ds_read_b128 v[198:201], v182 offset:3072
	ds_read_b128 v[202:205], v182 offset:4096
	ds_read_b128 v[206:209], v182 offset:5120
	ds_read_b128 v[210:213], v182 offset:6144
	ds_read_b128 v[214:217], v182 offset:7168
	global_load_lds_dwordx4 v168, s[6:7]
	s_add_i32 m0, s29, 0xe000
	s_nop 0
	global_load_lds_dwordx4 v170, s[6:7]
	s_waitcnt vmcnt(8)
	s_waitcnt lgkmcnt(0)
	s_setprio 1
	s_barrier
	v_mfma_f32_16x16x32_bf16 v[100:103], v[128:131], v[186:189], 0
	v_mfma_f32_16x16x32_bf16 v[88:91], v[136:139], v[186:189], 0
	v_mfma_f32_16x16x32_bf16 v[84:87], v[128:131], v[194:197], 0
	v_mfma_f32_16x16x32_bf16 v[80:83], v[136:139], v[194:197], 0
	v_mfma_f32_16x16x32_bf16 v[96:99], v[128:131], v[202:205], 0
	v_mfma_f32_16x16x32_bf16 v[92:95], v[136:139], v[202:205], 0
	v_mfma_f32_16x16x32_bf16 v[108:111], v[128:131], v[210:213], 0
	v_mfma_f32_16x16x32_bf16 v[104:107], v[136:139], v[210:213], 0
	v_mfma_f32_16x16x32_bf16 v[100:103], v[132:135], v[190:193], v[100:103]
	v_mfma_f32_16x16x32_bf16 v[88:91], v[140:143], v[190:193], v[88:91]
	v_mfma_f32_16x16x32_bf16 v[84:87], v[132:135], v[198:201], v[84:87]
	v_mfma_f32_16x16x32_bf16 v[80:83], v[140:143], v[198:201], v[80:83]
	v_mfma_f32_16x16x32_bf16 v[96:99], v[132:135], v[206:209], v[96:99]
	v_mfma_f32_16x16x32_bf16 v[92:95], v[140:143], v[206:209], v[92:95]
	v_mfma_f32_16x16x32_bf16 v[108:111], v[132:135], v[214:217], v[108:111]
	v_mfma_f32_16x16x32_bf16 v[104:107], v[140:143], v[214:217], v[104:107]
	v_mfma_f32_16x16x32_bf16 v[28:31], v[144:147], v[186:189], 0
	v_mfma_f32_16x16x32_bf16 v[16:19], v[152:155], v[186:189], 0
	v_mfma_f32_16x16x32_bf16 v[4:7], v[144:147], v[194:197], 0
	v_mfma_f32_16x16x32_bf16 v[0:3], v[152:155], v[194:197], 0
	v_mfma_f32_16x16x32_bf16 v[12:15], v[144:147], v[202:205], 0
	v_mfma_f32_16x16x32_bf16 v[8:11], v[152:155], v[202:205], 0
	v_mfma_f32_16x16x32_bf16 v[24:27], v[144:147], v[210:213], 0
	v_mfma_f32_16x16x32_bf16 v[20:23], v[152:155], v[210:213], 0
	v_mfma_f32_16x16x32_bf16 v[28:31], v[148:151], v[190:193], v[28:31]
	v_mfma_f32_16x16x32_bf16 v[16:19], v[156:159], v[190:193], v[16:19]
	v_mfma_f32_16x16x32_bf16 v[4:7], v[148:151], v[198:201], v[4:7]
	v_mfma_f32_16x16x32_bf16 v[0:3], v[156:159], v[198:201], v[0:3]
	v_mfma_f32_16x16x32_bf16 v[12:15], v[148:151], v[206:209], v[12:15]
	v_mfma_f32_16x16x32_bf16 v[8:11], v[156:159], v[206:209], v[8:11]
	v_mfma_f32_16x16x32_bf16 v[24:27], v[148:151], v[214:217], v[24:27]
	v_mfma_f32_16x16x32_bf16 v[20:23], v[156:159], v[214:217], v[20:23]
	s_barrier
	s_setprio 0
	s_add_i32 s45, s57, s4
	s_mov_b32 m0, s45
	ds_read_b128 v[186:189], v182 offset:16384
	ds_read_b128 v[190:193], v182 offset:17408
	ds_read_b128 v[194:197], v182 offset:18432
	ds_read_b128 v[198:201], v182 offset:19456
	ds_read_b128 v[202:205], v182 offset:20480
	ds_read_b128 v[206:209], v182 offset:21504
	ds_read_b128 v[210:213], v182 offset:22528
	ds_read_b128 v[214:217], v182 offset:23552
	global_load_lds_dwordx4 v162, s[10:11]
	s_add_i32 m0, s45, 0x2000
	s_add_u32 s46, s10, 0x4000
	s_addc_u32 s47, s11, 0
	s_add_i32 s45, s81, s4
	global_load_lds_dwordx4 v166, s[10:11]
	s_mov_b32 m0, s45
	s_nop 0
	global_load_lds_dwordx4 v162, s[46:47]
	s_add_i32 m0, s45, 0x2000
	s_nop 0
	global_load_lds_dwordx4 v166, s[46:47]
	s_mov_b32 m0, s29
	s_nop 0
	global_load_lds_dwordx4 v160, s[38:39]
	s_mov_b32 m0, s52
	s_nop 0
	global_load_lds_dwordx4 v164, s[38:39]
	s_waitcnt vmcnt(8)
	s_waitcnt lgkmcnt(0)
	s_setprio 1
	s_barrier
	v_mfma_f32_16x16x32_bf16 v[116:119], v[128:131], v[186:189], 0
	v_mfma_f32_16x16x32_bf16 v[112:115], v[136:139], v[186:189], 0
	v_mfma_f32_16x16x32_bf16 v[124:127], v[128:131], v[194:197], 0
	v_mfma_f32_16x16x32_bf16 v[120:123], v[136:139], v[194:197], 0
	v_mfma_f32_16x16x32_bf16 v[76:79], v[128:131], v[202:205], 0
	v_mfma_f32_16x16x32_bf16 v[72:75], v[136:139], v[202:205], 0
	v_mfma_f32_16x16x32_bf16 v[68:71], v[128:131], v[210:213], 0
	v_mfma_f32_16x16x32_bf16 v[64:67], v[136:139], v[210:213], 0
	v_mfma_f32_16x16x32_bf16 v[116:119], v[132:135], v[190:193], v[116:119]
	v_mfma_f32_16x16x32_bf16 v[112:115], v[140:143], v[190:193], v[112:115]
	v_mfma_f32_16x16x32_bf16 v[124:127], v[132:135], v[198:201], v[124:127]
	v_mfma_f32_16x16x32_bf16 v[120:123], v[140:143], v[198:201], v[120:123]
	v_mfma_f32_16x16x32_bf16 v[76:79], v[132:135], v[206:209], v[76:79]
	v_mfma_f32_16x16x32_bf16 v[72:75], v[140:143], v[206:209], v[72:75]
	v_mfma_f32_16x16x32_bf16 v[68:71], v[132:135], v[214:217], v[68:71]
	v_mfma_f32_16x16x32_bf16 v[64:67], v[140:143], v[214:217], v[64:67]
	v_mfma_f32_16x16x32_bf16 v[36:39], v[144:147], v[186:189], 0
	v_mfma_f32_16x16x32_bf16 v[32:35], v[152:155], v[186:189], 0
	v_mfma_f32_16x16x32_bf16 v[44:47], v[144:147], v[194:197], 0
	v_mfma_f32_16x16x32_bf16 v[40:43], v[152:155], v[194:197], 0
	v_mfma_f32_16x16x32_bf16 v[52:55], v[144:147], v[202:205], 0
	v_mfma_f32_16x16x32_bf16 v[48:51], v[152:155], v[202:205], 0
	v_mfma_f32_16x16x32_bf16 v[60:63], v[144:147], v[210:213], 0
	v_mfma_f32_16x16x32_bf16 v[56:59], v[152:155], v[210:213], 0
	v_mfma_f32_16x16x32_bf16 v[36:39], v[148:151], v[190:193], v[36:39]
	v_mfma_f32_16x16x32_bf16 v[32:35], v[156:159], v[190:193], v[32:35]
	v_mfma_f32_16x16x32_bf16 v[44:47], v[148:151], v[198:201], v[44:47]
	v_mfma_f32_16x16x32_bf16 v[40:43], v[156:159], v[198:201], v[40:43]
	v_mfma_f32_16x16x32_bf16 v[52:55], v[148:151], v[206:209], v[52:55]
	v_mfma_f32_16x16x32_bf16 v[48:51], v[156:159], v[206:209], v[48:51]
	v_mfma_f32_16x16x32_bf16 v[60:63], v[148:151], v[214:217], v[60:63]
	v_mfma_f32_16x16x32_bf16 v[56:59], v[156:159], v[214:217], v[56:59]
	s_barrier
	s_setprio 0
	s_branch .Lzmid4

.Lzmid4:
	v_add_u32_e32 v140, s82, v179
	v_add_u32_e32 v156, s83, v179
	ds_read_b128 v[128:131], v140
	ds_read_b128 v[132:135], v140 offset:1024
	ds_read_b128 v[136:139], v140 offset:2048
	ds_read_b128 v[140:143], v140 offset:3072
	ds_read_b128 v[144:147], v156
	ds_read_b128 v[148:151], v156 offset:1024
	ds_read_b128 v[152:155], v156 offset:2048
	ds_read_b128 v[156:159], v156 offset:3072
	s_add_u32 s38, s38, 0x4000
	s_addc_u32 s39, s39, 0
	s_mov_b32 m0, s53
	ds_read_b128 v[186:189], v182 offset:32768
	ds_read_b128 v[190:193], v182 offset:33792
	ds_read_b128 v[194:197], v182 offset:34816
	ds_read_b128 v[198:201], v182 offset:35840
	ds_read_b128 v[202:205], v182 offset:36864
	ds_read_b128 v[206:209], v182 offset:37888
	ds_read_b128 v[210:213], v182 offset:38912
	ds_read_b128 v[214:217], v182 offset:39936
	global_load_lds_dwordx4 v160, s[38:39]
	s_mov_b32 m0, s54
	s_nop 0
	global_load_lds_dwordx4 v164, s[38:39]
	s_waitcnt vmcnt(8)
	s_waitcnt lgkmcnt(0)
	s_setprio 1
	s_barrier
	v_mfma_f32_16x16x32_bf16 v[100:103], v[128:131], v[186:189], v[100:103]
	v_mfma_f32_16x16x32_bf16 v[88:91], v[136:139], v[186:189], v[88:91]
	v_mfma_f32_16x16x32_bf16 v[84:87], v[128:131], v[194:197], v[84:87]
	v_mfma_f32_16x16x32_bf16 v[80:83], v[136:139], v[194:197], v[80:83]
	v_mfma_f32_16x16x32_bf16 v[96:99], v[128:131], v[202:205], v[96:99]
	v_mfma_f32_16x16x32_bf16 v[92:95], v[136:139], v[202:205], v[92:95]
	v_mfma_f32_16x16x32_bf16 v[108:111], v[128:131], v[210:213], v[108:111]
	v_mfma_f32_16x16x32_bf16 v[104:107], v[136:139], v[210:213], v[104:107]
	v_mfma_f32_16x16x32_bf16 v[100:103], v[132:135], v[190:193], v[100:103]
	v_mfma_f32_16x16x32_bf16 v[88:91], v[140:143], v[190:193], v[88:91]
	v_mfma_f32_16x16x32_bf16 v[84:87], v[132:135], v[198:201], v[84:87]
	v_mfma_f32_16x16x32_bf16 v[80:83], v[140:143], v[198:201], v[80:83]
	v_mfma_f32_16x16x32_bf16 v[96:99], v[132:135], v[206:209], v[96:99]
	v_mfma_f32_16x16x32_bf16 v[92:95], v[140:143], v[206:209], v[92:95]
	v_mfma_f32_16x16x32_bf16 v[108:111], v[132:135], v[214:217], v[108:111]
	v_mfma_f32_16x16x32_bf16 v[104:107], v[140:143], v[214:217], v[104:107]
	v_mfma_f32_16x16x32_bf16 v[28:31], v[144:147], v[186:189], v[28:31]
	v_mfma_f32_16x16x32_bf16 v[16:19], v[152:155], v[186:189], v[16:19]
	v_mfma_f32_16x16x32_bf16 v[4:7], v[144:147], v[194:197], v[4:7]
	v_mfma_f32_16x16x32_bf16 v[0:3], v[152:155], v[194:197], v[0:3]
	v_mfma_f32_16x16x32_bf16 v[12:15], v[144:147], v[202:205], v[12:15]
	v_mfma_f32_16x16x32_bf16 v[8:11], v[152:155], v[202:205], v[8:11]
	v_mfma_f32_16x16x32_bf16 v[24:27], v[144:147], v[210:213], v[24:27]
	v_mfma_f32_16x16x32_bf16 v[20:23], v[152:155], v[210:213], v[20:23]
	v_mfma_f32_16x16x32_bf16 v[28:31], v[148:151], v[190:193], v[28:31]
	v_mfma_f32_16x16x32_bf16 v[16:19], v[156:159], v[190:193], v[16:19]
	v_mfma_f32_16x16x32_bf16 v[4:7], v[148:151], v[198:201], v[4:7]
	v_mfma_f32_16x16x32_bf16 v[0:3], v[156:159], v[198:201], v[0:3]
	v_mfma_f32_16x16x32_bf16 v[12:15], v[148:151], v[206:209], v[12:15]
	v_mfma_f32_16x16x32_bf16 v[8:11], v[156:159], v[206:209], v[8:11]
	v_mfma_f32_16x16x32_bf16 v[24:27], v[148:151], v[214:217], v[24:27]
	v_mfma_f32_16x16x32_bf16 v[20:23], v[156:159], v[214:217], v[20:23]
	s_barrier
	s_setprio 0
	s_add_u32 s38, s10, 0x40000
	s_addc_u32 s39, s11, 0
	s_add_i32 s45, s82, s4
	s_mov_b32 m0, s45
	ds_read_b128 v[186:189], v182 offset:49152
	ds_read_b128 v[190:193], v182 offset:50176
	ds_read_b128 v[194:197], v182 offset:51200
	ds_read_b128 v[198:201], v182 offset:52224
	ds_read_b128 v[202:205], v182 offset:53248
	ds_read_b128 v[206:209], v182 offset:54272
	ds_read_b128 v[210:213], v182 offset:55296
	ds_read_b128 v[214:217], v182 offset:56320
	global_load_lds_dwordx4 v162, s[38:39]
	s_add_i32 m0, s45, 0x2000
	s_add_u32 s10, s10, 0x44000
	global_load_lds_dwordx4 v166, s[38:39]
	s_addc_u32 s11, s11, 0
	s_add_i32 s38, s83, s4
	s_mov_b32 m0, s38
	s_nop 0
	global_load_lds_dwordx4 v162, s[10:11]
	s_add_i32 m0, s38, 0x2000
	s_nop 0
	global_load_lds_dwordx4 v166, s[10:11]
	s_mov_b32 m0, s2
	s_nop 0
	global_load_lds_dwordx4 v160, s[8:9]
	s_mov_b32 m0, s50
	s_nop 0
	global_load_lds_dwordx4 v164, s[8:9]
	s_waitcnt vmcnt(8)
	s_waitcnt lgkmcnt(0)
	s_setprio 1
	s_barrier
	v_mfma_f32_16x16x32_bf16 v[116:119], v[128:131], v[186:189], v[116:119]
	v_mfma_f32_16x16x32_bf16 v[112:115], v[136:139], v[186:189], v[112:115]
	v_mfma_f32_16x16x32_bf16 v[124:127], v[128:131], v[194:197], v[124:127]
	v_mfma_f32_16x16x32_bf16 v[120:123], v[136:139], v[194:197], v[120:123]
	v_mfma_f32_16x16x32_bf16 v[76:79], v[128:131], v[202:205], v[76:79]
	v_mfma_f32_16x16x32_bf16 v[72:75], v[136:139], v[202:205], v[72:75]
	v_mfma_f32_16x16x32_bf16 v[68:71], v[128:131], v[210:213], v[68:71]
	v_mfma_f32_16x16x32_bf16 v[64:67], v[136:139], v[210:213], v[64:67]
	v_mfma_f32_16x16x32_bf16 v[116:119], v[132:135], v[190:193], v[116:119]
	v_mfma_f32_16x16x32_bf16 v[112:115], v[140:143], v[190:193], v[112:115]
	v_mfma_f32_16x16x32_bf16 v[124:127], v[132:135], v[198:201], v[124:127]
	v_mfma_f32_16x16x32_bf16 v[120:123], v[140:143], v[198:201], v[120:123]
	v_mfma_f32_16x16x32_bf16 v[76:79], v[132:135], v[206:209], v[76:79]
	v_mfma_f32_16x16x32_bf16 v[72:75], v[140:143], v[206:209], v[72:75]
	v_mfma_f32_16x16x32_bf16 v[68:71], v[132:135], v[214:217], v[68:71]
	v_mfma_f32_16x16x32_bf16 v[64:67], v[140:143], v[214:217], v[64:67]
	v_mfma_f32_16x16x32_bf16 v[36:39], v[144:147], v[186:189], v[36:39]
	v_mfma_f32_16x16x32_bf16 v[32:35], v[152:155], v[186:189], v[32:35]
	v_mfma_f32_16x16x32_bf16 v[44:47], v[144:147], v[194:197], v[44:47]
	v_mfma_f32_16x16x32_bf16 v[40:43], v[152:155], v[194:197], v[40:43]
	v_mfma_f32_16x16x32_bf16 v[52:55], v[144:147], v[202:205], v[52:55]
	v_mfma_f32_16x16x32_bf16 v[48:51], v[152:155], v[202:205], v[48:51]
	v_mfma_f32_16x16x32_bf16 v[60:63], v[144:147], v[210:213], v[60:63]
	v_mfma_f32_16x16x32_bf16 v[56:59], v[152:155], v[210:213], v[56:59]
	v_mfma_f32_16x16x32_bf16 v[36:39], v[148:151], v[190:193], v[36:39]
	v_mfma_f32_16x16x32_bf16 v[32:35], v[156:159], v[190:193], v[32:35]
	v_mfma_f32_16x16x32_bf16 v[44:47], v[148:151], v[198:201], v[44:47]
	v_mfma_f32_16x16x32_bf16 v[40:43], v[156:159], v[198:201], v[40:43]
	v_mfma_f32_16x16x32_bf16 v[52:55], v[148:151], v[206:209], v[52:55]
	v_mfma_f32_16x16x32_bf16 v[48:51], v[156:159], v[206:209], v[48:51]
	v_mfma_f32_16x16x32_bf16 v[60:63], v[148:151], v[214:217], v[60:63]
	v_mfma_f32_16x16x32_bf16 v[56:59], v[156:159], v[214:217], v[56:59]
	s_barrier
	s_setprio 0
	s_add_i32 s44, s44, 2
	s_add_u32 s42, s42, 0x80000
	s_addc_u32 s43, s43, 0
	s_add_u32 s6, s6, 0x800000
	s_addc_u32 s7, s7, 0
	s_cmp_gt_u32 s44, 29
	s_cbranch_scc0 .LBB0_1282
	s_and_b64 vcc, exec, s[26:27]
	s_cbranch_vccz .LBB0_1285
	s_barrier

.LBB0_1403:
	s_mov_b32 s17, s9
	s_lshl_b64 s[20:21], s[16:17], 1
	s_add_u32 s20, s58, s20
	s_addc_u32 s21, s59, s21
	s_and_b64 s[22:23], s[6:7], exec
	s_mov_b32 s19, s9
	s_cselect_b32 s8, s21, s27
	s_cselect_b32 s17, s20, s26
	s_lshl_b64 s[22:23], s[18:19], 1
	v_readlane_b32 s19, v250, 17
	s_add_u32 s22, s19, s22
	v_readlane_b32 s19, v250, 4
	s_addc_u32 s23, s19, s23
	s_and_b64 s[28:29], s[6:7], exec
	s_cselect_b32 s19, s23, s25
	s_cselect_b32 s47, s22, s24
	s_add_u32 s50, s24, 0x100
	s_addc_u32 s51, s25, 0
	s_add_u32 s24, s26, 0x404000
	s_addc_u32 s25, s27, 0
	s_mov_b32 s52, -2
	ds_read_b128 v[152:155], v149
	ds_read_b128 v[156:159], v149 offset:1024
	ds_read_b128 v[160:163], v149 offset:2048
	ds_read_b128 v[164:167], v149 offset:3072
	ds_read_b128 v[168:171], v150
	ds_read_b128 v[172:175], v150 offset:1024
	ds_read_b128 v[176:179], v150 offset:2048
	ds_read_b128 v[180:183], v150 offset:3072
	s_add_u32 s26, s24, 0x3fc000
	s_addc_u32 s27, s25, 0
	s_cmp_eq_u32 s52, 28
	s_cselect_b32 s30, s17, s26
	s_cselect_b32 s31, s8, s27
	s_cselect_b32 s28, s47, s50
	s_cselect_b32 s29, s19, s51
	s_add_u32 s26, s30, 0x400000
	s_addc_u32 s27, s31, 0
	s_add_i32 m0, s33, 0xc000
	ds_read_b128 v[184:187], v151
	ds_read_b128 v[188:191], v151 offset:1024
	ds_read_b128 v[192:195], v151 offset:2048
	ds_read_b128 v[196:199], v151 offset:3072
	ds_read_b128 v[200:203], v151 offset:4096
	ds_read_b128 v[204:207], v151 offset:5120
	ds_read_b128 v[208:211], v151 offset:6144
	ds_read_b128 v[212:215], v151 offset:7168
	global_load_lds_dwordx4 v136, s[24:25]
	s_add_i32 m0, s33, 0xe000
	s_nop 0
	global_load_lds_dwordx4 v138, s[24:25]
	s_waitcnt vmcnt(8)
	s_waitcnt lgkmcnt(0)
	s_setprio 1
	s_barrier
	v_mfma_f32_16x16x32_bf16 v[124:127], v[152:155], v[184:187], 0
	v_mfma_f32_16x16x32_bf16 v[120:123], v[160:163], v[184:187], 0
	v_mfma_f32_16x16x32_bf16 v[108:111], v[152:155], v[192:195], 0
	v_mfma_f32_16x16x32_bf16 v[104:107], v[160:163], v[192:195], 0
	v_mfma_f32_16x16x32_bf16 v[92:95], v[152:155], v[200:203], 0
	v_mfma_f32_16x16x32_bf16 v[88:91], v[160:163], v[200:203], 0
	v_mfma_f32_16x16x32_bf16 v[76:79], v[152:155], v[208:211], 0
	v_mfma_f32_16x16x32_bf16 v[72:75], v[160:163], v[208:211], 0
	v_mfma_f32_16x16x32_bf16 v[124:127], v[156:159], v[188:191], v[124:127]
	v_mfma_f32_16x16x32_bf16 v[120:123], v[164:167], v[188:191], v[120:123]
	v_mfma_f32_16x16x32_bf16 v[108:111], v[156:159], v[196:199], v[108:111]
	v_mfma_f32_16x16x32_bf16 v[104:107], v[164:167], v[196:199], v[104:107]
	v_mfma_f32_16x16x32_bf16 v[92:95], v[156:159], v[204:207], v[92:95]
	v_mfma_f32_16x16x32_bf16 v[88:91], v[164:167], v[204:207], v[88:91]
	v_mfma_f32_16x16x32_bf16 v[76:79], v[156:159], v[212:215], v[76:79]
	v_mfma_f32_16x16x32_bf16 v[72:75], v[164:167], v[212:215], v[72:75]
	v_mfma_f32_16x16x32_bf16 v[116:119], v[168:171], v[184:187], 0
	v_mfma_f32_16x16x32_bf16 v[112:115], v[176:179], v[184:187], 0
	v_mfma_f32_16x16x32_bf16 v[100:103], v[168:171], v[192:195], 0
	v_mfma_f32_16x16x32_bf16 v[96:99], v[176:179], v[192:195], 0
	v_mfma_f32_16x16x32_bf16 v[84:87], v[168:171], v[200:203], 0
	v_mfma_f32_16x16x32_bf16 v[80:83], v[176:179], v[200:203], 0
	v_mfma_f32_16x16x32_bf16 v[68:71], v[168:171], v[208:211], 0
	v_mfma_f32_16x16x32_bf16 v[64:67], v[176:179], v[208:211], 0
	v_mfma_f32_16x16x32_bf16 v[116:119], v[172:175], v[188:191], v[116:119]
	v_mfma_f32_16x16x32_bf16 v[112:115], v[180:183], v[188:191], v[112:115]
	v_mfma_f32_16x16x32_bf16 v[100:103], v[172:175], v[196:199], v[100:103]
	v_mfma_f32_16x16x32_bf16 v[96:99], v[180:183], v[196:199], v[96:99]
	v_mfma_f32_16x16x32_bf16 v[84:87], v[172:175], v[204:207], v[84:87]
	v_mfma_f32_16x16x32_bf16 v[80:83], v[180:183], v[204:207], v[80:83]
	v_mfma_f32_16x16x32_bf16 v[68:71], v[172:175], v[212:215], v[68:71]
	v_mfma_f32_16x16x32_bf16 v[64:67], v[180:183], v[212:215], v[64:67]
	s_barrier
	s_setprio 0
	s_add_i32 s53, s57, s5
	v_lshl_add_u64 v[144:145], s[28:29], 0, v[130:131]
	s_mov_b32 m0, s53
	ds_read_b128 v[184:187], v151 offset:16384
	ds_read_b128 v[188:191], v151 offset:17408
	ds_read_b128 v[192:195], v151 offset:18432
	ds_read_b128 v[196:199], v151 offset:19456
	ds_read_b128 v[200:203], v151 offset:20480
	ds_read_b128 v[204:207], v151 offset:21504
	ds_read_b128 v[208:211], v151 offset:22528
	ds_read_b128 v[212:215], v151 offset:23552
	global_load_lds_dwordx4 v[144:145], off
	s_add_i32 m0, s53, 0x2000
	s_add_u32 s54, s28, 0x80000
	v_lshl_add_u64 v[216:217], s[28:29], 0, v[134:135]
	s_addc_u32 s55, s29, 0
	s_add_i32 s53, s81, s5
	global_load_lds_dwordx4 v[216:217], off
	s_mov_b32 m0, s53
	s_nop 0
	global_load_lds_dwordx4 v130, s[54:55]
	s_add_i32 m0, s53, 0x2000
	s_nop 0
	global_load_lds_dwordx4 v134, s[54:55]
	s_mov_b32 m0, s33
	s_nop 0
	global_load_lds_dwordx4 v128, s[30:31]
	s_mov_b32 m0, s34
	s_nop 0
	global_load_lds_dwordx4 v132, s[30:31]
	s_waitcnt vmcnt(8)
	s_waitcnt lgkmcnt(0)
	s_setprio 1
	s_barrier
	v_mfma_f32_16x16x32_bf16 v[60:63], v[152:155], v[184:187], 0
	v_mfma_f32_16x16x32_bf16 v[56:59], v[160:163], v[184:187], 0
	v_mfma_f32_16x16x32_bf16 v[44:47], v[152:155], v[192:195], 0
	v_mfma_f32_16x16x32_bf16 v[40:43], v[160:163], v[192:195], 0
	v_mfma_f32_16x16x32_bf16 v[28:31], v[152:155], v[200:203], 0
	v_mfma_f32_16x16x32_bf16 v[24:27], v[160:163], v[200:203], 0
	v_mfma_f32_16x16x32_bf16 v[12:15], v[152:155], v[208:211], 0
	v_mfma_f32_16x16x32_bf16 v[8:11], v[160:163], v[208:211], 0
	v_mfma_f32_16x16x32_bf16 v[60:63], v[156:159], v[188:191], v[60:63]
	v_mfma_f32_16x16x32_bf16 v[56:59], v[164:167], v[188:191], v[56:59]
	v_mfma_f32_16x16x32_bf16 v[44:47], v[156:159], v[196:199], v[44:47]
	v_mfma_f32_16x16x32_bf16 v[40:43], v[164:167], v[196:199], v[40:43]
	v_mfma_f32_16x16x32_bf16 v[28:31], v[156:159], v[204:207], v[28:31]
	v_mfma_f32_16x16x32_bf16 v[24:27], v[164:167], v[204:207], v[24:27]
	v_mfma_f32_16x16x32_bf16 v[12:15], v[156:159], v[212:215], v[12:15]
	v_mfma_f32_16x16x32_bf16 v[8:11], v[164:167], v[212:215], v[8:11]
	v_mfma_f32_16x16x32_bf16 v[52:55], v[168:171], v[184:187], 0
	v_mfma_f32_16x16x32_bf16 v[48:51], v[176:179], v[184:187], 0
	v_mfma_f32_16x16x32_bf16 v[36:39], v[168:171], v[192:195], 0
	v_mfma_f32_16x16x32_bf16 v[32:35], v[176:179], v[192:195], 0
	v_mfma_f32_16x16x32_bf16 v[20:23], v[168:171], v[200:203], 0
	v_mfma_f32_16x16x32_bf16 v[16:19], v[176:179], v[200:203], 0
	v_mfma_f32_16x16x32_bf16 v[4:7], v[168:171], v[208:211], 0
	v_mfma_f32_16x16x32_bf16 v[0:3], v[176:179], v[208:211], 0
	v_mfma_f32_16x16x32_bf16 v[52:55], v[172:175], v[188:191], v[52:55]
	v_mfma_f32_16x16x32_bf16 v[48:51], v[180:183], v[188:191], v[48:51]
	v_mfma_f32_16x16x32_bf16 v[36:39], v[172:175], v[196:199], v[36:39]
	v_mfma_f32_16x16x32_bf16 v[32:35], v[180:183], v[196:199], v[32:35]
	v_mfma_f32_16x16x32_bf16 v[20:23], v[172:175], v[204:207], v[20:23]
	v_mfma_f32_16x16x32_bf16 v[16:19], v[180:183], v[204:207], v[16:19]
	v_mfma_f32_16x16x32_bf16 v[4:7], v[172:175], v[212:215], v[4:7]
	v_mfma_f32_16x16x32_bf16 v[0:3], v[180:183], v[212:215], v[0:3]
	s_barrier
	s_setprio 0
	s_branch .Lzmid5

.Lzmid5:
	v_add_u32_e32 v164, s82, v148
	v_add_u32_e32 v180, s83, v148
	ds_read_b128 v[152:155], v164
	ds_read_b128 v[156:159], v164 offset:1024
	ds_read_b128 v[160:163], v164 offset:2048
	ds_read_b128 v[164:167], v164 offset:3072
	ds_read_b128 v[168:171], v180
	ds_read_b128 v[172:175], v180 offset:1024
	ds_read_b128 v[176:179], v180 offset:2048
	ds_read_b128 v[180:183], v180 offset:3072
	s_add_u32 s30, s30, 0x4000
	s_addc_u32 s31, s31, 0
	s_mov_b32 m0, s35
	ds_read_b128 v[184:187], v151 offset:32768
	ds_read_b128 v[188:191], v151 offset:33792
	ds_read_b128 v[192:195], v151 offset:34816
	ds_read_b128 v[196:199], v151 offset:35840
	ds_read_b128 v[200:203], v151 offset:36864
	ds_read_b128 v[204:207], v151 offset:37888
	ds_read_b128 v[208:211], v151 offset:38912
	ds_read_b128 v[212:215], v151 offset:39936
	global_load_lds_dwordx4 v128, s[30:31]
	v_lshl_add_u64 v[218:219], s[30:31], 0, v[132:133]
	s_mov_b32 m0, s36
	s_nop 0
	global_load_lds_dwordx4 v[218:219], off
	s_waitcnt vmcnt(8)
	s_waitcnt lgkmcnt(0)
	s_setprio 1
	s_barrier
	v_mfma_f32_16x16x32_bf16 v[124:127], v[152:155], v[184:187], v[124:127]
	v_mfma_f32_16x16x32_bf16 v[120:123], v[160:163], v[184:187], v[120:123]
	v_mfma_f32_16x16x32_bf16 v[108:111], v[152:155], v[192:195], v[108:111]
	v_mfma_f32_16x16x32_bf16 v[104:107], v[160:163], v[192:195], v[104:107]
	v_mfma_f32_16x16x32_bf16 v[92:95], v[152:155], v[200:203], v[92:95]
	v_mfma_f32_16x16x32_bf16 v[88:91], v[160:163], v[200:203], v[88:91]
	v_mfma_f32_16x16x32_bf16 v[76:79], v[152:155], v[208:211], v[76:79]
	v_mfma_f32_16x16x32_bf16 v[72:75], v[160:163], v[208:211], v[72:75]
	v_mfma_f32_16x16x32_bf16 v[124:127], v[156:159], v[188:191], v[124:127]
	v_mfma_f32_16x16x32_bf16 v[120:123], v[164:167], v[188:191], v[120:123]
	v_mfma_f32_16x16x32_bf16 v[108:111], v[156:159], v[196:199], v[108:111]
	v_mfma_f32_16x16x32_bf16 v[104:107], v[164:167], v[196:199], v[104:107]
	v_mfma_f32_16x16x32_bf16 v[92:95], v[156:159], v[204:207], v[92:95]
	v_mfma_f32_16x16x32_bf16 v[88:91], v[164:167], v[204:207], v[88:91]
	v_mfma_f32_16x16x32_bf16 v[76:79], v[156:159], v[212:215], v[76:79]
	v_mfma_f32_16x16x32_bf16 v[72:75], v[164:167], v[212:215], v[72:75]
	v_mfma_f32_16x16x32_bf16 v[116:119], v[168:171], v[184:187], v[116:119]
	v_mfma_f32_16x16x32_bf16 v[112:115], v[176:179], v[184:187], v[112:115]
	v_mfma_f32_16x16x32_bf16 v[100:103], v[168:171], v[192:195], v[100:103]
	v_mfma_f32_16x16x32_bf16 v[96:99], v[176:179], v[192:195], v[96:99]
	v_mfma_f32_16x16x32_bf16 v[84:87], v[168:171], v[200:203], v[84:87]
	v_mfma_f32_16x16x32_bf16 v[80:83], v[176:179], v[200:203], v[80:83]
	v_mfma_f32_16x16x32_bf16 v[68:71], v[168:171], v[208:211], v[68:71]
	v_mfma_f32_16x16x32_bf16 v[64:67], v[176:179], v[208:211], v[64:67]
	v_mfma_f32_16x16x32_bf16 v[116:119], v[172:175], v[188:191], v[116:119]
	v_mfma_f32_16x16x32_bf16 v[112:115], v[180:183], v[188:191], v[112:115]
	v_mfma_f32_16x16x32_bf16 v[100:103], v[172:175], v[196:199], v[100:103]
	v_mfma_f32_16x16x32_bf16 v[96:99], v[180:183], v[196:199], v[96:99]
	v_mfma_f32_16x16x32_bf16 v[84:87], v[172:175], v[204:207], v[84:87]
	v_mfma_f32_16x16x32_bf16 v[80:83], v[180:183], v[204:207], v[80:83]
	v_mfma_f32_16x16x32_bf16 v[68:71], v[172:175], v[212:215], v[68:71]
	v_mfma_f32_16x16x32_bf16 v[64:67], v[180:183], v[212:215], v[64:67]
	s_barrier
	s_setprio 0
	s_add_i32 s30, s82, s5
	v_lshl_add_u64 v[144:145], v[144:145], 0, s[12:13]
	s_mov_b32 m0, s30
	ds_read_b128 v[184:187], v151 offset:49152
	ds_read_b128 v[188:191], v151 offset:50176
	ds_read_b128 v[192:195], v151 offset:51200
	ds_read_b128 v[196:199], v151 offset:52224
	ds_read_b128 v[200:203], v151 offset:53248
	ds_read_b128 v[204:207], v151 offset:54272
	ds_read_b128 v[208:211], v151 offset:55296
	ds_read_b128 v[212:215], v151 offset:56320
	global_load_lds_dwordx4 v[144:145], off
	s_add_i32 m0, s30, 0x2000
	s_add_u32 s28, s28, 0x80080
	v_lshl_add_u64 v[144:145], v[216:217], 0, s[12:13]
	s_addc_u32 s29, s29, 0
	s_add_i32 s30, s83, s5
	global_load_lds_dwordx4 v[144:145], off
	s_mov_b32 m0, s30
	s_nop 0
	global_load_lds_dwordx4 v130, s[28:29]
	s_add_i32 m0, s30, 0x2000
	s_nop 0
	global_load_lds_dwordx4 v134, s[28:29]
	s_mov_b32 m0, s38
	s_nop 0
	global_load_lds_dwordx4 v128, s[26:27]
	s_mov_b32 m0, s39
	s_nop 0
	global_load_lds_dwordx4 v132, s[26:27]
	s_waitcnt vmcnt(8)
	s_waitcnt lgkmcnt(0)
	s_setprio 1
	s_barrier
	v_mfma_f32_16x16x32_bf16 v[60:63], v[152:155], v[184:187], v[60:63]
	v_mfma_f32_16x16x32_bf16 v[56:59], v[160:163], v[184:187], v[56:59]
	v_mfma_f32_16x16x32_bf16 v[44:47], v[152:155], v[192:195], v[44:47]
	v_mfma_f32_16x16x32_bf16 v[40:43], v[160:163], v[192:195], v[40:43]
	v_mfma_f32_16x16x32_bf16 v[28:31], v[152:155], v[200:203], v[28:31]
	v_mfma_f32_16x16x32_bf16 v[24:27], v[160:163], v[200:203], v[24:27]
	v_mfma_f32_16x16x32_bf16 v[12:15], v[152:155], v[208:211], v[12:15]
	v_mfma_f32_16x16x32_bf16 v[8:11], v[160:163], v[208:211], v[8:11]
	v_mfma_f32_16x16x32_bf16 v[60:63], v[156:159], v[188:191], v[60:63]
	v_mfma_f32_16x16x32_bf16 v[56:59], v[164:167], v[188:191], v[56:59]
	v_mfma_f32_16x16x32_bf16 v[44:47], v[156:159], v[196:199], v[44:47]
	v_mfma_f32_16x16x32_bf16 v[40:43], v[164:167], v[196:199], v[40:43]
	v_mfma_f32_16x16x32_bf16 v[28:31], v[156:159], v[204:207], v[28:31]
	v_mfma_f32_16x16x32_bf16 v[24:27], v[164:167], v[204:207], v[24:27]
	v_mfma_f32_16x16x32_bf16 v[12:15], v[156:159], v[212:215], v[12:15]
	v_mfma_f32_16x16x32_bf16 v[8:11], v[164:167], v[212:215], v[8:11]
	v_mfma_f32_16x16x32_bf16 v[52:55], v[168:171], v[184:187], v[52:55]
	v_mfma_f32_16x16x32_bf16 v[48:51], v[176:179], v[184:187], v[48:51]
	v_mfma_f32_16x16x32_bf16 v[36:39], v[168:171], v[192:195], v[36:39]
	v_mfma_f32_16x16x32_bf16 v[32:35], v[176:179], v[192:195], v[32:35]
	v_mfma_f32_16x16x32_bf16 v[20:23], v[168:171], v[200:203], v[20:23]
	v_mfma_f32_16x16x32_bf16 v[16:19], v[176:179], v[200:203], v[16:19]
	v_mfma_f32_16x16x32_bf16 v[4:7], v[168:171], v[208:211], v[4:7]
	v_mfma_f32_16x16x32_bf16 v[0:3], v[176:179], v[208:211], v[0:3]
	v_mfma_f32_16x16x32_bf16 v[52:55], v[172:175], v[188:191], v[52:55]
	v_mfma_f32_16x16x32_bf16 v[48:51], v[180:183], v[188:191], v[48:51]
	v_mfma_f32_16x16x32_bf16 v[36:39], v[172:175], v[196:199], v[36:39]
	v_mfma_f32_16x16x32_bf16 v[32:35], v[180:183], v[196:199], v[32:35]
	v_mfma_f32_16x16x32_bf16 v[20:23], v[172:175], v[204:207], v[20:23]
	v_mfma_f32_16x16x32_bf16 v[16:19], v[180:183], v[204:207], v[16:19]
	v_mfma_f32_16x16x32_bf16 v[4:7], v[172:175], v[212:215], v[4:7]
	v_mfma_f32_16x16x32_bf16 v[0:3], v[180:183], v[212:215], v[0:3]
	s_barrier
	s_setprio 0
	s_add_i32 s52, s52, 2
	s_add_u32 s50, s50, 0x100
	s_addc_u32 s51, s51, 0
	s_add_u32 s24, s24, 0x800000
	s_addc_u32 s25, s25, 0
	s_cmp_gt_u32 s52, 29
	s_cbranch_scc0 .LBB0_1404
	s_and_b64 vcc, exec, s[14:15]
	s_cbranch_vccz .LBB0_1407
	s_barrier

.LBB0_1511:
	s_mov_b32 s29, s13
	s_lshl_b64 s[34:35], s[28:29], 1
	s_add_u32 s34, s91, s34
	s_addc_u32 s35, s92, s35
	s_and_b64 s[36:37], s[10:11], exec
	s_mov_b32 s31, s13
	s_cselect_b32 s12, s35, s9
	s_cselect_b32 s15, s34, s8
	s_lshl_b64 s[36:37], s[30:31], 1
	s_add_u32 s36, s84, s36
	s_addc_u32 s37, s85, s37
	s_and_b64 s[10:11], s[10:11], exec
	s_cselect_b32 s29, s37, s7
	s_cselect_b32 s31, s36, s6
	s_add_u32 s41, s6, 0x100
	s_addc_u32 s42, s7, 0
	s_add_u32 s6, s8, 0x404000
	s_addc_u32 s7, s9, 0
	s_mov_b32 s43, -2
	ds_read_b128 v[128:131], v180
	ds_read_b128 v[132:135], v180 offset:1024
	ds_read_b128 v[136:139], v180 offset:2048
	ds_read_b128 v[140:143], v180 offset:3072
	ds_read_b128 v[144:147], v181
	ds_read_b128 v[148:151], v181 offset:1024
	ds_read_b128 v[152:155], v181 offset:2048
	ds_read_b128 v[156:159], v181 offset:3072
	s_add_u32 s8, s6, 0x3fc000
	s_addc_u32 s9, s7, 0
	s_cmp_eq_u32 s43, 12
	s_cselect_b32 s38, s15, s8
	s_cselect_b32 s39, s12, s9
	s_cselect_b32 s10, s31, s41
	s_cselect_b32 s11, s29, s42
	s_add_u32 s8, s38, 0x400000
	s_addc_u32 s9, s39, 0
	s_add_i32 m0, s52, 0xc000
	ds_read_b128 v[186:189], v182
	ds_read_b128 v[190:193], v182 offset:1024
	ds_read_b128 v[194:197], v182 offset:2048
	ds_read_b128 v[198:201], v182 offset:3072
	ds_read_b128 v[202:205], v182 offset:4096
	ds_read_b128 v[206:209], v182 offset:5120
	ds_read_b128 v[210:213], v182 offset:6144
	ds_read_b128 v[214:217], v182 offset:7168
	global_load_lds_dwordx4 v168, s[6:7]
	s_add_i32 m0, s52, 0xe000
	s_nop 0
	global_load_lds_dwordx4 v170, s[6:7]
	s_waitcnt vmcnt(8)
	s_waitcnt lgkmcnt(0)
	s_setprio 1
	s_barrier
	v_mfma_f32_16x16x32_bf16 v[100:103], v[128:131], v[186:189], 0
	v_mfma_f32_16x16x32_bf16 v[88:91], v[136:139], v[186:189], 0
	v_mfma_f32_16x16x32_bf16 v[84:87], v[128:131], v[194:197], 0
	v_mfma_f32_16x16x32_bf16 v[80:83], v[136:139], v[194:197], 0
	v_mfma_f32_16x16x32_bf16 v[96:99], v[128:131], v[202:205], 0
	v_mfma_f32_16x16x32_bf16 v[92:95], v[136:139], v[202:205], 0
	v_mfma_f32_16x16x32_bf16 v[108:111], v[128:131], v[210:213], 0
	v_mfma_f32_16x16x32_bf16 v[104:107], v[136:139], v[210:213], 0
	v_mfma_f32_16x16x32_bf16 v[100:103], v[132:135], v[190:193], v[100:103]
	v_mfma_f32_16x16x32_bf16 v[88:91], v[140:143], v[190:193], v[88:91]
	v_mfma_f32_16x16x32_bf16 v[84:87], v[132:135], v[198:201], v[84:87]
	v_mfma_f32_16x16x32_bf16 v[80:83], v[140:143], v[198:201], v[80:83]
	v_mfma_f32_16x16x32_bf16 v[96:99], v[132:135], v[206:209], v[96:99]
	v_mfma_f32_16x16x32_bf16 v[92:95], v[140:143], v[206:209], v[92:95]
	v_mfma_f32_16x16x32_bf16 v[108:111], v[132:135], v[214:217], v[108:111]
	v_mfma_f32_16x16x32_bf16 v[104:107], v[140:143], v[214:217], v[104:107]
	v_mfma_f32_16x16x32_bf16 v[28:31], v[144:147], v[186:189], 0
	v_mfma_f32_16x16x32_bf16 v[16:19], v[152:155], v[186:189], 0
	v_mfma_f32_16x16x32_bf16 v[4:7], v[144:147], v[194:197], 0
	v_mfma_f32_16x16x32_bf16 v[0:3], v[152:155], v[194:197], 0
	v_mfma_f32_16x16x32_bf16 v[12:15], v[144:147], v[202:205], 0
	v_mfma_f32_16x16x32_bf16 v[8:11], v[152:155], v[202:205], 0
	v_mfma_f32_16x16x32_bf16 v[24:27], v[144:147], v[210:213], 0
	v_mfma_f32_16x16x32_bf16 v[20:23], v[152:155], v[210:213], 0
	v_mfma_f32_16x16x32_bf16 v[28:31], v[148:151], v[190:193], v[28:31]
	v_mfma_f32_16x16x32_bf16 v[16:19], v[156:159], v[190:193], v[16:19]
	v_mfma_f32_16x16x32_bf16 v[4:7], v[148:151], v[198:201], v[4:7]
	v_mfma_f32_16x16x32_bf16 v[0:3], v[156:159], v[198:201], v[0:3]
	v_mfma_f32_16x16x32_bf16 v[12:15], v[148:151], v[206:209], v[12:15]
	v_mfma_f32_16x16x32_bf16 v[8:11], v[156:159], v[206:209], v[8:11]
	v_mfma_f32_16x16x32_bf16 v[24:27], v[148:151], v[214:217], v[24:27]
	v_mfma_f32_16x16x32_bf16 v[20:23], v[156:159], v[214:217], v[20:23]
	s_barrier
	s_setprio 0
	s_add_i32 s44, s57, s4
	v_lshl_add_u64 v[174:175], s[10:11], 0, v[162:163]
	s_mov_b32 m0, s44
	ds_read_b128 v[186:189], v182 offset:16384
	ds_read_b128 v[190:193], v182 offset:17408
	ds_read_b128 v[194:197], v182 offset:18432
	ds_read_b128 v[198:201], v182 offset:19456
	ds_read_b128 v[202:205], v182 offset:20480
	ds_read_b128 v[206:209], v182 offset:21504
	ds_read_b128 v[210:213], v182 offset:22528
	ds_read_b128 v[214:217], v182 offset:23552
	global_load_lds_dwordx4 v[174:175], off
	s_add_i32 m0, s44, 0x2000
	s_add_u32 s44, s10, 0x40000
	v_lshl_add_u64 v[218:219], s[10:11], 0, v[166:167]
	s_addc_u32 s45, s11, 0
	s_add_i32 s46, s81, s4
	global_load_lds_dwordx4 v[218:219], off
	s_mov_b32 m0, s46
	s_nop 0
	global_load_lds_dwordx4 v162, s[44:45]
	s_add_i32 m0, s46, 0x2000
	s_nop 0
	global_load_lds_dwordx4 v166, s[44:45]
	s_mov_b32 m0, s52
	s_nop 0
	global_load_lds_dwordx4 v160, s[38:39]
	s_mov_b32 m0, s33
	s_nop 0
	global_load_lds_dwordx4 v164, s[38:39]
	s_waitcnt vmcnt(8)
	s_waitcnt lgkmcnt(0)
	s_setprio 1
	s_barrier
	v_mfma_f32_16x16x32_bf16 v[116:119], v[128:131], v[186:189], 0
	v_mfma_f32_16x16x32_bf16 v[112:115], v[136:139], v[186:189], 0
	v_mfma_f32_16x16x32_bf16 v[124:127], v[128:131], v[194:197], 0
	v_mfma_f32_16x16x32_bf16 v[120:123], v[136:139], v[194:197], 0
	v_mfma_f32_16x16x32_bf16 v[76:79], v[128:131], v[202:205], 0
	v_mfma_f32_16x16x32_bf16 v[72:75], v[136:139], v[202:205], 0
	v_mfma_f32_16x16x32_bf16 v[68:71], v[128:131], v[210:213], 0
	v_mfma_f32_16x16x32_bf16 v[64:67], v[136:139], v[210:213], 0
	v_mfma_f32_16x16x32_bf16 v[116:119], v[132:135], v[190:193], v[116:119]
	v_mfma_f32_16x16x32_bf16 v[112:115], v[140:143], v[190:193], v[112:115]
	v_mfma_f32_16x16x32_bf16 v[124:127], v[132:135], v[198:201], v[124:127]
	v_mfma_f32_16x16x32_bf16 v[120:123], v[140:143], v[198:201], v[120:123]
	v_mfma_f32_16x16x32_bf16 v[76:79], v[132:135], v[206:209], v[76:79]
	v_mfma_f32_16x16x32_bf16 v[72:75], v[140:143], v[206:209], v[72:75]
	v_mfma_f32_16x16x32_bf16 v[68:71], v[132:135], v[214:217], v[68:71]
	v_mfma_f32_16x16x32_bf16 v[64:67], v[140:143], v[214:217], v[64:67]
	v_mfma_f32_16x16x32_bf16 v[36:39], v[144:147], v[186:189], 0
	v_mfma_f32_16x16x32_bf16 v[32:35], v[152:155], v[186:189], 0
	v_mfma_f32_16x16x32_bf16 v[44:47], v[144:147], v[194:197], 0
	v_mfma_f32_16x16x32_bf16 v[40:43], v[152:155], v[194:197], 0
	v_mfma_f32_16x16x32_bf16 v[52:55], v[144:147], v[202:205], 0
	v_mfma_f32_16x16x32_bf16 v[48:51], v[152:155], v[202:205], 0
	v_mfma_f32_16x16x32_bf16 v[60:63], v[144:147], v[210:213], 0
	v_mfma_f32_16x16x32_bf16 v[56:59], v[152:155], v[210:213], 0
	v_mfma_f32_16x16x32_bf16 v[36:39], v[148:151], v[190:193], v[36:39]
	v_mfma_f32_16x16x32_bf16 v[32:35], v[156:159], v[190:193], v[32:35]
	v_mfma_f32_16x16x32_bf16 v[44:47], v[148:151], v[198:201], v[44:47]
	v_mfma_f32_16x16x32_bf16 v[40:43], v[156:159], v[198:201], v[40:43]
	v_mfma_f32_16x16x32_bf16 v[52:55], v[148:151], v[206:209], v[52:55]
	v_mfma_f32_16x16x32_bf16 v[48:51], v[156:159], v[206:209], v[48:51]
	v_mfma_f32_16x16x32_bf16 v[60:63], v[148:151], v[214:217], v[60:63]
	v_mfma_f32_16x16x32_bf16 v[56:59], v[156:159], v[214:217], v[56:59]
	s_barrier
	s_setprio 0
	s_branch .Lzmid6

.Lzmid6:
	v_add_u32_e32 v140, s82, v179
	v_add_u32_e32 v156, s83, v179
	ds_read_b128 v[128:131], v140
	ds_read_b128 v[132:135], v140 offset:1024
	ds_read_b128 v[136:139], v140 offset:2048
	ds_read_b128 v[140:143], v140 offset:3072
	ds_read_b128 v[144:147], v156
	ds_read_b128 v[148:151], v156 offset:1024
	ds_read_b128 v[152:155], v156 offset:2048
	ds_read_b128 v[156:159], v156 offset:3072
	s_add_u32 s38, s38, 0x4000
	s_addc_u32 s39, s39, 0
	s_mov_b32 m0, s53
	ds_read_b128 v[186:189], v182 offset:32768
	ds_read_b128 v[190:193], v182 offset:33792
	ds_read_b128 v[194:197], v182 offset:34816
	ds_read_b128 v[198:201], v182 offset:35840
	ds_read_b128 v[202:205], v182 offset:36864
	ds_read_b128 v[206:209], v182 offset:37888
	ds_read_b128 v[210:213], v182 offset:38912
	ds_read_b128 v[214:217], v182 offset:39936
	global_load_lds_dwordx4 v160, s[38:39]
	v_lshl_add_u64 v[220:221], s[38:39], 0, v[164:165]
	s_mov_b32 m0, s54
	s_nop 0
	global_load_lds_dwordx4 v[220:221], off
	s_waitcnt vmcnt(8)
	s_waitcnt lgkmcnt(0)
	s_setprio 1
	s_barrier
	v_mfma_f32_16x16x32_bf16 v[100:103], v[128:131], v[186:189], v[100:103]
	v_mfma_f32_16x16x32_bf16 v[88:91], v[136:139], v[186:189], v[88:91]
	v_mfma_f32_16x16x32_bf16 v[84:87], v[128:131], v[194:197], v[84:87]
	v_mfma_f32_16x16x32_bf16 v[80:83], v[136:139], v[194:197], v[80:83]
	v_mfma_f32_16x16x32_bf16 v[96:99], v[128:131], v[202:205], v[96:99]
	v_mfma_f32_16x16x32_bf16 v[92:95], v[136:139], v[202:205], v[92:95]
	v_mfma_f32_16x16x32_bf16 v[108:111], v[128:131], v[210:213], v[108:111]
	v_mfma_f32_16x16x32_bf16 v[104:107], v[136:139], v[210:213], v[104:107]
	v_mfma_f32_16x16x32_bf16 v[100:103], v[132:135], v[190:193], v[100:103]
	v_mfma_f32_16x16x32_bf16 v[88:91], v[140:143], v[190:193], v[88:91]
	v_mfma_f32_16x16x32_bf16 v[84:87], v[132:135], v[198:201], v[84:87]
	v_mfma_f32_16x16x32_bf16 v[80:83], v[140:143], v[198:201], v[80:83]
	v_mfma_f32_16x16x32_bf16 v[96:99], v[132:135], v[206:209], v[96:99]
	v_mfma_f32_16x16x32_bf16 v[92:95], v[140:143], v[206:209], v[92:95]
	v_mfma_f32_16x16x32_bf16 v[108:111], v[132:135], v[214:217], v[108:111]
	v_mfma_f32_16x16x32_bf16 v[104:107], v[140:143], v[214:217], v[104:107]
	v_mfma_f32_16x16x32_bf16 v[28:31], v[144:147], v[186:189], v[28:31]
	v_mfma_f32_16x16x32_bf16 v[16:19], v[152:155], v[186:189], v[16:19]
	v_mfma_f32_16x16x32_bf16 v[4:7], v[144:147], v[194:197], v[4:7]
	v_mfma_f32_16x16x32_bf16 v[0:3], v[152:155], v[194:197], v[0:3]
	v_mfma_f32_16x16x32_bf16 v[12:15], v[144:147], v[202:205], v[12:15]
	v_mfma_f32_16x16x32_bf16 v[8:11], v[152:155], v[202:205], v[8:11]
	v_mfma_f32_16x16x32_bf16 v[24:27], v[144:147], v[210:213], v[24:27]
	v_mfma_f32_16x16x32_bf16 v[20:23], v[152:155], v[210:213], v[20:23]
	v_mfma_f32_16x16x32_bf16 v[28:31], v[148:151], v[190:193], v[28:31]
	v_mfma_f32_16x16x32_bf16 v[16:19], v[156:159], v[190:193], v[16:19]
	v_mfma_f32_16x16x32_bf16 v[4:7], v[148:151], v[198:201], v[4:7]
	v_mfma_f32_16x16x32_bf16 v[0:3], v[156:159], v[198:201], v[0:3]
	v_mfma_f32_16x16x32_bf16 v[12:15], v[148:151], v[206:209], v[12:15]
	v_mfma_f32_16x16x32_bf16 v[8:11], v[156:159], v[206:209], v[8:11]
	v_mfma_f32_16x16x32_bf16 v[24:27], v[148:151], v[214:217], v[24:27]
	v_mfma_f32_16x16x32_bf16 v[20:23], v[156:159], v[214:217], v[20:23]
	s_barrier
	s_setprio 0
	s_add_i32 s38, s82, s4
	v_lshl_add_u64 v[174:175], v[174:175], 0, s[22:23]
	s_mov_b32 m0, s38
	ds_read_b128 v[186:189], v182 offset:49152
	ds_read_b128 v[190:193], v182 offset:50176
	ds_read_b128 v[194:197], v182 offset:51200
	ds_read_b128 v[198:201], v182 offset:52224
	ds_read_b128 v[202:205], v182 offset:53248
	ds_read_b128 v[206:209], v182 offset:54272
	ds_read_b128 v[210:213], v182 offset:55296
	ds_read_b128 v[214:217], v182 offset:56320
	global_load_lds_dwordx4 v[174:175], off
	s_add_i32 m0, s38, 0x2000
	s_add_u32 s10, s10, 0x40080
	v_lshl_add_u64 v[174:175], v[218:219], 0, s[22:23]
	s_addc_u32 s11, s11, 0
	s_add_i32 s38, s83, s4
	global_load_lds_dwordx4 v[174:175], off
	s_mov_b32 m0, s38
	s_nop 0
	global_load_lds_dwordx4 v162, s[10:11]
	s_add_i32 m0, s38, 0x2000
	s_nop 0
	global_load_lds_dwordx4 v166, s[10:11]
	s_mov_b32 m0, s50
	s_nop 0
	global_load_lds_dwordx4 v160, s[8:9]
	s_mov_b32 m0, s51
	s_nop 0
	global_load_lds_dwordx4 v164, s[8:9]
	s_waitcnt vmcnt(8)
	s_waitcnt lgkmcnt(0)
	s_setprio 1
	s_barrier
	v_mfma_f32_16x16x32_bf16 v[116:119], v[128:131], v[186:189], v[116:119]
	v_mfma_f32_16x16x32_bf16 v[112:115], v[136:139], v[186:189], v[112:115]
	v_mfma_f32_16x16x32_bf16 v[124:127], v[128:131], v[194:197], v[124:127]
	v_mfma_f32_16x16x32_bf16 v[120:123], v[136:139], v[194:197], v[120:123]
	v_mfma_f32_16x16x32_bf16 v[76:79], v[128:131], v[202:205], v[76:79]
	v_mfma_f32_16x16x32_bf16 v[72:75], v[136:139], v[202:205], v[72:75]
	v_mfma_f32_16x16x32_bf16 v[68:71], v[128:131], v[210:213], v[68:71]
	v_mfma_f32_16x16x32_bf16 v[64:67], v[136:139], v[210:213], v[64:67]
	v_mfma_f32_16x16x32_bf16 v[116:119], v[132:135], v[190:193], v[116:119]
	v_mfma_f32_16x16x32_bf16 v[112:115], v[140:143], v[190:193], v[112:115]
	v_mfma_f32_16x16x32_bf16 v[124:127], v[132:135], v[198:201], v[124:127]
	v_mfma_f32_16x16x32_bf16 v[120:123], v[140:143], v[198:201], v[120:123]
	v_mfma_f32_16x16x32_bf16 v[76:79], v[132:135], v[206:209], v[76:79]
	v_mfma_f32_16x16x32_bf16 v[72:75], v[140:143], v[206:209], v[72:75]
	v_mfma_f32_16x16x32_bf16 v[68:71], v[132:135], v[214:217], v[68:71]
	v_mfma_f32_16x16x32_bf16 v[64:67], v[140:143], v[214:217], v[64:67]
	v_mfma_f32_16x16x32_bf16 v[36:39], v[144:147], v[186:189], v[36:39]
	v_mfma_f32_16x16x32_bf16 v[32:35], v[152:155], v[186:189], v[32:35]
	v_mfma_f32_16x16x32_bf16 v[44:47], v[144:147], v[194:197], v[44:47]
	v_mfma_f32_16x16x32_bf16 v[40:43], v[152:155], v[194:197], v[40:43]
	v_mfma_f32_16x16x32_bf16 v[52:55], v[144:147], v[202:205], v[52:55]
	v_mfma_f32_16x16x32_bf16 v[48:51], v[152:155], v[202:205], v[48:51]
	v_mfma_f32_16x16x32_bf16 v[60:63], v[144:147], v[210:213], v[60:63]
	v_mfma_f32_16x16x32_bf16 v[56:59], v[152:155], v[210:213], v[56:59]
	v_mfma_f32_16x16x32_bf16 v[36:39], v[148:151], v[190:193], v[36:39]
	v_mfma_f32_16x16x32_bf16 v[32:35], v[156:159], v[190:193], v[32:35]
	v_mfma_f32_16x16x32_bf16 v[44:47], v[148:151], v[198:201], v[44:47]
	v_mfma_f32_16x16x32_bf16 v[40:43], v[156:159], v[198:201], v[40:43]
	v_mfma_f32_16x16x32_bf16 v[52:55], v[148:151], v[206:209], v[52:55]
	v_mfma_f32_16x16x32_bf16 v[48:51], v[156:159], v[206:209], v[48:51]
	v_mfma_f32_16x16x32_bf16 v[60:63], v[148:151], v[214:217], v[60:63]
	v_mfma_f32_16x16x32_bf16 v[56:59], v[156:159], v[214:217], v[56:59]
	s_barrier
	s_setprio 0
	s_add_i32 s43, s43, 2
	s_add_u32 s41, s41, 0x100
	s_addc_u32 s42, s42, 0
	s_add_u32 s6, s6, 0x800000
	s_addc_u32 s7, s7, 0
	s_cmp_gt_u32 s43, 13
	s_cbranch_scc0 .LBB0_1512
	s_and_b64 vcc, exec, s[24:25]
	s_cbranch_vccz .LBB0_1515
	s_barrier

.LBB0_1627:
	s_mov_b32 s17, s9
	s_lshl_b64 s[20:21], s[16:17], 1
	s_add_u32 s20, s58, s20
	s_addc_u32 s21, s59, s21
	s_and_b64 s[22:23], s[6:7], exec
	s_mov_b32 s19, s9
	s_cselect_b32 s17, s21, s27
	s_cselect_b32 s46, s20, s26
	s_lshl_b64 s[22:23], s[18:19], 1
	s_add_u32 s22, s4, s22
	s_addc_u32 s23, s5, s23
	s_and_b64 s[28:29], s[6:7], exec
	s_cselect_b32 s19, s23, s25
	s_cselect_b32 s47, s22, s24
	s_add_u32 s50, s24, 0x2c0000
	s_addc_u32 s51, s25, 0
	s_add_u32 s24, s26, 0x404000
	s_addc_u32 s25, s27, 0
	s_mov_b32 s52, -2
	ds_read_b128 v[152:155], v149
	ds_read_b128 v[156:159], v149 offset:1024
	ds_read_b128 v[160:163], v149 offset:2048
	ds_read_b128 v[164:167], v149 offset:3072
	ds_read_b128 v[168:171], v150
	ds_read_b128 v[172:175], v150 offset:1024
	ds_read_b128 v[176:179], v150 offset:2048
	ds_read_b128 v[180:183], v150 offset:3072
	s_add_u32 s26, s24, 0x3fc000
	s_addc_u32 s27, s25, 0
	s_cmp_eq_u32 s52, 28
	s_cselect_b32 s30, s46, s26
	s_cselect_b32 s31, s17, s27
	s_cselect_b32 s28, s47, s50
	s_cselect_b32 s29, s19, s51
	s_add_u32 s26, s30, 0x400000
	s_addc_u32 s27, s31, 0
	s_add_i32 m0, s34, 0xc000
	ds_read_b128 v[184:187], v151
	ds_read_b128 v[188:191], v151 offset:1024
	ds_read_b128 v[192:195], v151 offset:2048
	ds_read_b128 v[196:199], v151 offset:3072
	ds_read_b128 v[200:203], v151 offset:4096
	ds_read_b128 v[204:207], v151 offset:5120
	ds_read_b128 v[208:211], v151 offset:6144
	ds_read_b128 v[212:215], v151 offset:7168
	global_load_lds_dwordx4 v136, s[24:25]
	s_add_i32 m0, s34, 0xe000
	s_nop 0
	global_load_lds_dwordx4 v138, s[24:25]
	s_waitcnt vmcnt(8)
	s_waitcnt lgkmcnt(0)
	s_setprio 1
	s_barrier
	v_mfma_f32_16x16x32_bf16 v[124:127], v[152:155], v[184:187], 0
	v_mfma_f32_16x16x32_bf16 v[120:123], v[160:163], v[184:187], 0
	v_mfma_f32_16x16x32_bf16 v[108:111], v[152:155], v[192:195], 0
	v_mfma_f32_16x16x32_bf16 v[104:107], v[160:163], v[192:195], 0
	v_mfma_f32_16x16x32_bf16 v[92:95], v[152:155], v[200:203], 0
	v_mfma_f32_16x16x32_bf16 v[88:91], v[160:163], v[200:203], 0
	v_mfma_f32_16x16x32_bf16 v[76:79], v[152:155], v[208:211], 0
	v_mfma_f32_16x16x32_bf16 v[72:75], v[160:163], v[208:211], 0
	v_mfma_f32_16x16x32_bf16 v[124:127], v[156:159], v[188:191], v[124:127]
	v_mfma_f32_16x16x32_bf16 v[120:123], v[164:167], v[188:191], v[120:123]
	v_mfma_f32_16x16x32_bf16 v[108:111], v[156:159], v[196:199], v[108:111]
	v_mfma_f32_16x16x32_bf16 v[104:107], v[164:167], v[196:199], v[104:107]
	v_mfma_f32_16x16x32_bf16 v[92:95], v[156:159], v[204:207], v[92:95]
	v_mfma_f32_16x16x32_bf16 v[88:91], v[164:167], v[204:207], v[88:91]
	v_mfma_f32_16x16x32_bf16 v[76:79], v[156:159], v[212:215], v[76:79]
	v_mfma_f32_16x16x32_bf16 v[72:75], v[164:167], v[212:215], v[72:75]
	v_mfma_f32_16x16x32_bf16 v[116:119], v[168:171], v[184:187], 0
	v_mfma_f32_16x16x32_bf16 v[112:115], v[176:179], v[184:187], 0
	v_mfma_f32_16x16x32_bf16 v[100:103], v[168:171], v[192:195], 0
	v_mfma_f32_16x16x32_bf16 v[96:99], v[176:179], v[192:195], 0
	v_mfma_f32_16x16x32_bf16 v[84:87], v[168:171], v[200:203], 0
	v_mfma_f32_16x16x32_bf16 v[80:83], v[176:179], v[200:203], 0
	v_mfma_f32_16x16x32_bf16 v[68:71], v[168:171], v[208:211], 0
	v_mfma_f32_16x16x32_bf16 v[64:67], v[176:179], v[208:211], 0
	v_mfma_f32_16x16x32_bf16 v[116:119], v[172:175], v[188:191], v[116:119]
	v_mfma_f32_16x16x32_bf16 v[112:115], v[180:183], v[188:191], v[112:115]
	v_mfma_f32_16x16x32_bf16 v[100:103], v[172:175], v[196:199], v[100:103]
	v_mfma_f32_16x16x32_bf16 v[96:99], v[180:183], v[196:199], v[96:99]
	v_mfma_f32_16x16x32_bf16 v[84:87], v[172:175], v[204:207], v[84:87]
	v_mfma_f32_16x16x32_bf16 v[80:83], v[180:183], v[204:207], v[80:83]
	v_mfma_f32_16x16x32_bf16 v[68:71], v[172:175], v[212:215], v[68:71]
	v_mfma_f32_16x16x32_bf16 v[64:67], v[180:183], v[212:215], v[64:67]
	s_barrier
	s_setprio 0
	s_add_i32 s53, s57, s33
	s_mov_b32 m0, s53
	ds_read_b128 v[184:187], v151 offset:16384
	ds_read_b128 v[188:191], v151 offset:17408
	ds_read_b128 v[192:195], v151 offset:18432
	ds_read_b128 v[196:199], v151 offset:19456
	ds_read_b128 v[200:203], v151 offset:20480
	ds_read_b128 v[204:207], v151 offset:21504
	ds_read_b128 v[208:211], v151 offset:22528
	ds_read_b128 v[212:215], v151 offset:23552
	global_load_lds_dwordx4 v132, s[28:29]
	s_add_i32 m0, s53, 0x2000
	s_add_u32 s54, s28, 0x4000
	s_addc_u32 s55, s29, 0
	s_add_i32 s53, s81, s33
	global_load_lds_dwordx4 v128, s[28:29]
	s_mov_b32 m0, s53
	s_nop 0
	global_load_lds_dwordx4 v132, s[54:55]
	s_add_i32 m0, s53, 0x2000
	s_nop 0
	global_load_lds_dwordx4 v128, s[54:55]
	s_mov_b32 m0, s34
	s_nop 0
	global_load_lds_dwordx4 v134, s[30:31]
	s_mov_b32 m0, s35
	s_nop 0
	global_load_lds_dwordx4 v130, s[30:31]
	s_waitcnt vmcnt(8)
	s_waitcnt lgkmcnt(0)
	s_setprio 1
	s_barrier
	v_mfma_f32_16x16x32_bf16 v[60:63], v[152:155], v[184:187], 0
	v_mfma_f32_16x16x32_bf16 v[56:59], v[160:163], v[184:187], 0
	v_mfma_f32_16x16x32_bf16 v[44:47], v[152:155], v[192:195], 0
	v_mfma_f32_16x16x32_bf16 v[40:43], v[160:163], v[192:195], 0
	v_mfma_f32_16x16x32_bf16 v[28:31], v[152:155], v[200:203], 0
	v_mfma_f32_16x16x32_bf16 v[24:27], v[160:163], v[200:203], 0
	v_mfma_f32_16x16x32_bf16 v[12:15], v[152:155], v[208:211], 0
	v_mfma_f32_16x16x32_bf16 v[8:11], v[160:163], v[208:211], 0
	v_mfma_f32_16x16x32_bf16 v[60:63], v[156:159], v[188:191], v[60:63]
	v_mfma_f32_16x16x32_bf16 v[56:59], v[164:167], v[188:191], v[56:59]
	v_mfma_f32_16x16x32_bf16 v[44:47], v[156:159], v[196:199], v[44:47]
	v_mfma_f32_16x16x32_bf16 v[40:43], v[164:167], v[196:199], v[40:43]
	v_mfma_f32_16x16x32_bf16 v[28:31], v[156:159], v[204:207], v[28:31]
	v_mfma_f32_16x16x32_bf16 v[24:27], v[164:167], v[204:207], v[24:27]
	v_mfma_f32_16x16x32_bf16 v[12:15], v[156:159], v[212:215], v[12:15]
	v_mfma_f32_16x16x32_bf16 v[8:11], v[164:167], v[212:215], v[8:11]
	v_mfma_f32_16x16x32_bf16 v[52:55], v[168:171], v[184:187], 0
	v_mfma_f32_16x16x32_bf16 v[48:51], v[176:179], v[184:187], 0
	v_mfma_f32_16x16x32_bf16 v[36:39], v[168:171], v[192:195], 0
	v_mfma_f32_16x16x32_bf16 v[32:35], v[176:179], v[192:195], 0
	v_mfma_f32_16x16x32_bf16 v[20:23], v[168:171], v[200:203], 0
	v_mfma_f32_16x16x32_bf16 v[16:19], v[176:179], v[200:203], 0
	v_mfma_f32_16x16x32_bf16 v[4:7], v[168:171], v[208:211], 0
	v_mfma_f32_16x16x32_bf16 v[0:3], v[176:179], v[208:211], 0
	v_mfma_f32_16x16x32_bf16 v[52:55], v[172:175], v[188:191], v[52:55]
	v_mfma_f32_16x16x32_bf16 v[48:51], v[180:183], v[188:191], v[48:51]
	v_mfma_f32_16x16x32_bf16 v[36:39], v[172:175], v[196:199], v[36:39]
	v_mfma_f32_16x16x32_bf16 v[32:35], v[180:183], v[196:199], v[32:35]
	v_mfma_f32_16x16x32_bf16 v[20:23], v[172:175], v[204:207], v[20:23]
	v_mfma_f32_16x16x32_bf16 v[16:19], v[180:183], v[204:207], v[16:19]
	v_mfma_f32_16x16x32_bf16 v[4:7], v[172:175], v[212:215], v[4:7]
	v_mfma_f32_16x16x32_bf16 v[0:3], v[180:183], v[212:215], v[0:3]
	s_barrier
	s_setprio 0
	s_branch .Lzmid7

.Lzmid7:
	v_add_u32_e32 v144, s82, v148
	ds_read_b128 v[152:155], v144
	ds_read_b128 v[156:159], v144 offset:1024
	ds_read_b128 v[160:163], v144 offset:2048
	ds_read_b128 v[164:167], v144 offset:3072
	v_add_u32_e32 v144, s83, v148
	ds_read_b128 v[168:171], v144
	ds_read_b128 v[172:175], v144 offset:1024
	ds_read_b128 v[176:179], v144 offset:2048
	ds_read_b128 v[180:183], v144 offset:3072
	s_add_u32 s30, s30, 0x4000
	s_addc_u32 s31, s31, 0
	s_mov_b32 m0, s36
	ds_read_b128 v[184:187], v151 offset:32768
	ds_read_b128 v[188:191], v151 offset:33792
	ds_read_b128 v[192:195], v151 offset:34816
	ds_read_b128 v[196:199], v151 offset:35840
	ds_read_b128 v[200:203], v151 offset:36864
	ds_read_b128 v[204:207], v151 offset:37888
	ds_read_b128 v[208:211], v151 offset:38912
	ds_read_b128 v[212:215], v151 offset:39936
	global_load_lds_dwordx4 v134, s[30:31]
	s_mov_b32 m0, s37
	s_nop 0
	global_load_lds_dwordx4 v130, s[30:31]
	s_waitcnt vmcnt(8)
	s_waitcnt lgkmcnt(0)
	s_setprio 1
	s_barrier
	v_mfma_f32_16x16x32_bf16 v[124:127], v[152:155], v[184:187], v[124:127]
	v_mfma_f32_16x16x32_bf16 v[120:123], v[160:163], v[184:187], v[120:123]
	v_mfma_f32_16x16x32_bf16 v[108:111], v[152:155], v[192:195], v[108:111]
	v_mfma_f32_16x16x32_bf16 v[104:107], v[160:163], v[192:195], v[104:107]
	v_mfma_f32_16x16x32_bf16 v[92:95], v[152:155], v[200:203], v[92:95]
	v_mfma_f32_16x16x32_bf16 v[88:91], v[160:163], v[200:203], v[88:91]
	v_mfma_f32_16x16x32_bf16 v[76:79], v[152:155], v[208:211], v[76:79]
	v_mfma_f32_16x16x32_bf16 v[72:75], v[160:163], v[208:211], v[72:75]
	v_mfma_f32_16x16x32_bf16 v[124:127], v[156:159], v[188:191], v[124:127]
	v_mfma_f32_16x16x32_bf16 v[120:123], v[164:167], v[188:191], v[120:123]
	v_mfma_f32_16x16x32_bf16 v[108:111], v[156:159], v[196:199], v[108:111]
	v_mfma_f32_16x16x32_bf16 v[104:107], v[164:167], v[196:199], v[104:107]
	v_mfma_f32_16x16x32_bf16 v[92:95], v[156:159], v[204:207], v[92:95]
	v_mfma_f32_16x16x32_bf16 v[88:91], v[164:167], v[204:207], v[88:91]
	v_mfma_f32_16x16x32_bf16 v[76:79], v[156:159], v[212:215], v[76:79]
	v_mfma_f32_16x16x32_bf16 v[72:75], v[164:167], v[212:215], v[72:75]
	v_mfma_f32_16x16x32_bf16 v[116:119], v[168:171], v[184:187], v[116:119]
	v_mfma_f32_16x16x32_bf16 v[112:115], v[176:179], v[184:187], v[112:115]
	v_mfma_f32_16x16x32_bf16 v[100:103], v[168:171], v[192:195], v[100:103]
	v_mfma_f32_16x16x32_bf16 v[96:99], v[176:179], v[192:195], v[96:99]
	v_mfma_f32_16x16x32_bf16 v[84:87], v[168:171], v[200:203], v[84:87]
	v_mfma_f32_16x16x32_bf16 v[80:83], v[176:179], v[200:203], v[80:83]
	v_mfma_f32_16x16x32_bf16 v[68:71], v[168:171], v[208:211], v[68:71]
	v_mfma_f32_16x16x32_bf16 v[64:67], v[176:179], v[208:211], v[64:67]
	v_mfma_f32_16x16x32_bf16 v[116:119], v[172:175], v[188:191], v[116:119]
	v_mfma_f32_16x16x32_bf16 v[112:115], v[180:183], v[188:191], v[112:115]
	v_mfma_f32_16x16x32_bf16 v[100:103], v[172:175], v[196:199], v[100:103]
	v_mfma_f32_16x16x32_bf16 v[96:99], v[180:183], v[196:199], v[96:99]
	v_mfma_f32_16x16x32_bf16 v[84:87], v[172:175], v[204:207], v[84:87]
	v_mfma_f32_16x16x32_bf16 v[80:83], v[180:183], v[204:207], v[80:83]
	v_mfma_f32_16x16x32_bf16 v[68:71], v[172:175], v[212:215], v[68:71]
	v_mfma_f32_16x16x32_bf16 v[64:67], v[180:183], v[212:215], v[64:67]
	s_barrier
	s_setprio 0
	s_add_u32 s30, s28, 0x160000
	s_addc_u32 s31, s29, 0
	s_add_i32 s53, s82, s33
	s_mov_b32 m0, s53
	ds_read_b128 v[184:187], v151 offset:49152
	ds_read_b128 v[188:191], v151 offset:50176
	ds_read_b128 v[192:195], v151 offset:51200
	ds_read_b128 v[196:199], v151 offset:52224
	ds_read_b128 v[200:203], v151 offset:53248
	ds_read_b128 v[204:207], v151 offset:54272
	ds_read_b128 v[208:211], v151 offset:55296
	ds_read_b128 v[212:215], v151 offset:56320
	global_load_lds_dwordx4 v132, s[30:31]
	s_add_i32 m0, s53, 0x2000
	s_add_u32 s28, s28, 0x164000
	global_load_lds_dwordx4 v128, s[30:31]
	s_addc_u32 s29, s29, 0
	s_add_i32 s30, s83, s33
	s_mov_b32 m0, s30
	s_nop 0
	global_load_lds_dwordx4 v132, s[28:29]
	s_add_i32 m0, s30, 0x2000
	s_nop 0
	global_load_lds_dwordx4 v128, s[28:29]
	s_mov_b32 m0, s39
	s_nop 0
	global_load_lds_dwordx4 v134, s[26:27]
	s_mov_b32 m0, s40
	s_nop 0
	global_load_lds_dwordx4 v130, s[26:27]
	s_waitcnt vmcnt(8)
	s_waitcnt lgkmcnt(0)
	s_setprio 1
	s_barrier
	v_mfma_f32_16x16x32_bf16 v[60:63], v[152:155], v[184:187], v[60:63]
	v_mfma_f32_16x16x32_bf16 v[56:59], v[160:163], v[184:187], v[56:59]
	v_mfma_f32_16x16x32_bf16 v[44:47], v[152:155], v[192:195], v[44:47]
	v_mfma_f32_16x16x32_bf16 v[40:43], v[160:163], v[192:195], v[40:43]
	v_mfma_f32_16x16x32_bf16 v[28:31], v[152:155], v[200:203], v[28:31]
	v_mfma_f32_16x16x32_bf16 v[24:27], v[160:163], v[200:203], v[24:27]
	v_mfma_f32_16x16x32_bf16 v[12:15], v[152:155], v[208:211], v[12:15]
	v_mfma_f32_16x16x32_bf16 v[8:11], v[160:163], v[208:211], v[8:11]
	v_mfma_f32_16x16x32_bf16 v[60:63], v[156:159], v[188:191], v[60:63]
	v_mfma_f32_16x16x32_bf16 v[56:59], v[164:167], v[188:191], v[56:59]
	v_mfma_f32_16x16x32_bf16 v[44:47], v[156:159], v[196:199], v[44:47]
	v_mfma_f32_16x16x32_bf16 v[40:43], v[164:167], v[196:199], v[40:43]
	v_mfma_f32_16x16x32_bf16 v[28:31], v[156:159], v[204:207], v[28:31]
	v_mfma_f32_16x16x32_bf16 v[24:27], v[164:167], v[204:207], v[24:27]
	v_mfma_f32_16x16x32_bf16 v[12:15], v[156:159], v[212:215], v[12:15]
	v_mfma_f32_16x16x32_bf16 v[8:11], v[164:167], v[212:215], v[8:11]
	v_mfma_f32_16x16x32_bf16 v[52:55], v[168:171], v[184:187], v[52:55]
	v_mfma_f32_16x16x32_bf16 v[48:51], v[176:179], v[184:187], v[48:51]
	v_mfma_f32_16x16x32_bf16 v[36:39], v[168:171], v[192:195], v[36:39]
	v_mfma_f32_16x16x32_bf16 v[32:35], v[176:179], v[192:195], v[32:35]
	v_mfma_f32_16x16x32_bf16 v[20:23], v[168:171], v[200:203], v[20:23]
	v_mfma_f32_16x16x32_bf16 v[16:19], v[176:179], v[200:203], v[16:19]
	v_mfma_f32_16x16x32_bf16 v[4:7], v[168:171], v[208:211], v[4:7]
	v_mfma_f32_16x16x32_bf16 v[0:3], v[176:179], v[208:211], v[0:3]
	v_mfma_f32_16x16x32_bf16 v[52:55], v[172:175], v[188:191], v[52:55]
	v_mfma_f32_16x16x32_bf16 v[48:51], v[180:183], v[188:191], v[48:51]
	v_mfma_f32_16x16x32_bf16 v[36:39], v[172:175], v[196:199], v[36:39]
	v_mfma_f32_16x16x32_bf16 v[32:35], v[180:183], v[196:199], v[32:35]
	v_mfma_f32_16x16x32_bf16 v[20:23], v[172:175], v[204:207], v[20:23]
	v_mfma_f32_16x16x32_bf16 v[16:19], v[180:183], v[204:207], v[16:19]
	v_mfma_f32_16x16x32_bf16 v[4:7], v[172:175], v[212:215], v[4:7]
	v_mfma_f32_16x16x32_bf16 v[0:3], v[180:183], v[212:215], v[0:3]
	s_barrier
	s_setprio 0
	s_add_i32 s52, s52, 2
	s_add_u32 s50, s50, 0x2c0000
	s_addc_u32 s51, s51, 0
	s_add_u32 s24, s24, 0x800000
	s_addc_u32 s25, s25, 0
	s_cmp_gt_u32 s52, 29
	s_cbranch_scc0 .LBB0_1628
	s_and_b64 vcc, exec, s[12:13]
	s_cbranch_vccz .LBB0_1631
	s_barrier

.LBB0_1705:
	s_mov_b32 s31, s13
	s_lshl_b64 s[34:35], s[30:31], 1
	s_add_u32 s34, s60, s34
	s_addc_u32 s35, s61, s35
	s_and_b64 s[38:39], exec, s[10:11]
	s_cselect_b32 s12, s35, s9
	s_cselect_b32 s15, s34, s8
	s_lshl_b64 s[36:37], s[36:37], 1
	s_add_u32 s36, s29, s36
	s_addc_u32 s37, s54, s37
	s_and_b64 s[10:11], exec, s[10:11]
	s_cselect_b32 s31, s37, s7
	s_cselect_b32 s41, s36, s6
	s_add_u32 s42, s6, 0x80000
	s_addc_u32 s43, s7, 0
	s_add_u32 s6, s8, 0x404000
	s_addc_u32 s7, s9, 0
	s_mov_b32 s44, -2
	ds_read_b128 v[128:131], v180
	ds_read_b128 v[132:135], v180 offset:1024
	ds_read_b128 v[136:139], v180 offset:2048
	ds_read_b128 v[140:143], v180 offset:3072
	ds_read_b128 v[144:147], v181
	ds_read_b128 v[148:151], v181 offset:1024
	ds_read_b128 v[152:155], v181 offset:2048
	ds_read_b128 v[156:159], v181 offset:3072
	s_add_u32 s8, s6, 0x3fc000
	s_addc_u32 s9, s7, 0
	s_cmpk_eq_i32 s44, 0x54
	s_cselect_b32 s38, s15, s8
	s_cselect_b32 s39, s12, s9
	s_cselect_b32 s10, s41, s42
	s_cselect_b32 s11, s31, s43
	s_add_u32 s8, s38, 0x400000
	s_addc_u32 s9, s39, 0
	s_add_i32 m0, s74, 0xc000
	ds_read_b128 v[186:189], v182
	ds_read_b128 v[190:193], v182 offset:1024
	ds_read_b128 v[194:197], v182 offset:2048
	ds_read_b128 v[198:201], v182 offset:3072
	ds_read_b128 v[202:205], v182 offset:4096
	ds_read_b128 v[206:209], v182 offset:5120
	ds_read_b128 v[210:213], v182 offset:6144
	ds_read_b128 v[214:217], v182 offset:7168
	global_load_lds_dwordx4 v168, s[6:7]
	s_add_i32 m0, s74, 0xe000
	s_nop 0
	global_load_lds_dwordx4 v170, s[6:7]
	s_waitcnt vmcnt(8)
	s_waitcnt lgkmcnt(0)
	s_setprio 1
	s_barrier
	v_mfma_f32_16x16x32_bf16 v[92:95], v[128:131], v[186:189], 0
	v_mfma_f32_16x16x32_bf16 v[88:91], v[136:139], v[186:189], 0
	v_mfma_f32_16x16x32_bf16 v[12:15], v[128:131], v[194:197], 0
	v_mfma_f32_16x16x32_bf16 v[8:11], v[136:139], v[194:197], 0
	v_mfma_f32_16x16x32_bf16 v[100:103], v[128:131], v[202:205], 0
	v_mfma_f32_16x16x32_bf16 v[96:99], v[136:139], v[202:205], 0
	v_mfma_f32_16x16x32_bf16 v[108:111], v[128:131], v[210:213], 0
	v_mfma_f32_16x16x32_bf16 v[104:107], v[136:139], v[210:213], 0
	v_mfma_f32_16x16x32_bf16 v[92:95], v[132:135], v[190:193], v[92:95]
	v_mfma_f32_16x16x32_bf16 v[88:91], v[140:143], v[190:193], v[88:91]
	v_mfma_f32_16x16x32_bf16 v[12:15], v[132:135], v[198:201], v[12:15]
	v_mfma_f32_16x16x32_bf16 v[8:11], v[140:143], v[198:201], v[8:11]
	v_mfma_f32_16x16x32_bf16 v[100:103], v[132:135], v[206:209], v[100:103]
	v_mfma_f32_16x16x32_bf16 v[96:99], v[140:143], v[206:209], v[96:99]
	v_mfma_f32_16x16x32_bf16 v[108:111], v[132:135], v[214:217], v[108:111]
	v_mfma_f32_16x16x32_bf16 v[104:107], v[140:143], v[214:217], v[104:107]
	v_mfma_f32_16x16x32_bf16 v[84:87], v[144:147], v[186:189], 0
	v_mfma_f32_16x16x32_bf16 v[80:83], v[152:155], v[186:189], 0
	v_mfma_f32_16x16x32_bf16 v[4:7], v[144:147], v[194:197], 0
	v_mfma_f32_16x16x32_bf16 v[0:3], v[152:155], v[194:197], 0
	v_mfma_f32_16x16x32_bf16 v[20:23], v[144:147], v[202:205], 0
	v_mfma_f32_16x16x32_bf16 v[16:19], v[152:155], v[202:205], 0
	v_mfma_f32_16x16x32_bf16 v[28:31], v[144:147], v[210:213], 0
	v_mfma_f32_16x16x32_bf16 v[24:27], v[152:155], v[210:213], 0
	v_mfma_f32_16x16x32_bf16 v[84:87], v[148:151], v[190:193], v[84:87]
	v_mfma_f32_16x16x32_bf16 v[80:83], v[156:159], v[190:193], v[80:83]
	v_mfma_f32_16x16x32_bf16 v[4:7], v[148:151], v[198:201], v[4:7]
	v_mfma_f32_16x16x32_bf16 v[0:3], v[156:159], v[198:201], v[0:3]
	v_mfma_f32_16x16x32_bf16 v[20:23], v[148:151], v[206:209], v[20:23]
	v_mfma_f32_16x16x32_bf16 v[16:19], v[156:159], v[206:209], v[16:19]
	v_mfma_f32_16x16x32_bf16 v[28:31], v[148:151], v[214:217], v[28:31]
	v_mfma_f32_16x16x32_bf16 v[24:27], v[156:159], v[214:217], v[24:27]
	s_barrier
	s_setprio 0
	s_add_i32 s45, s57, s72
	s_mov_b32 m0, s45
	ds_read_b128 v[186:189], v182 offset:16384
	ds_read_b128 v[190:193], v182 offset:17408
	ds_read_b128 v[194:197], v182 offset:18432
	ds_read_b128 v[198:201], v182 offset:19456
	ds_read_b128 v[202:205], v182 offset:20480
	ds_read_b128 v[206:209], v182 offset:21504
	ds_read_b128 v[210:213], v182 offset:22528
	ds_read_b128 v[214:217], v182 offset:23552
	global_load_lds_dwordx4 v162, s[10:11]
	s_add_i32 m0, s45, 0x2000
	s_add_u32 s46, s10, 0x4000
	s_addc_u32 s47, s11, 0
	s_add_i32 s45, s81, s72
	global_load_lds_dwordx4 v166, s[10:11]
	s_mov_b32 m0, s45
	s_nop 0
	global_load_lds_dwordx4 v162, s[46:47]
	s_add_i32 m0, s45, 0x2000
	s_nop 0
	global_load_lds_dwordx4 v166, s[46:47]
	s_mov_b32 m0, s74
	s_nop 0
	global_load_lds_dwordx4 v160, s[38:39]
	s_mov_b32 m0, s75
	s_nop 0
	global_load_lds_dwordx4 v164, s[38:39]
	s_waitcnt vmcnt(8)
	s_waitcnt lgkmcnt(0)
	s_setprio 1
	s_barrier
	v_mfma_f32_16x16x32_bf16 v[116:119], v[128:131], v[186:189], 0
	v_mfma_f32_16x16x32_bf16 v[112:115], v[136:139], v[186:189], 0
	v_mfma_f32_16x16x32_bf16 v[124:127], v[128:131], v[194:197], 0
	v_mfma_f32_16x16x32_bf16 v[120:123], v[136:139], v[194:197], 0
	v_mfma_f32_16x16x32_bf16 v[76:79], v[128:131], v[202:205], 0
	v_mfma_f32_16x16x32_bf16 v[72:75], v[136:139], v[202:205], 0
	v_mfma_f32_16x16x32_bf16 v[68:71], v[128:131], v[210:213], 0
	v_mfma_f32_16x16x32_bf16 v[64:67], v[136:139], v[210:213], 0
	v_mfma_f32_16x16x32_bf16 v[116:119], v[132:135], v[190:193], v[116:119]
	v_mfma_f32_16x16x32_bf16 v[112:115], v[140:143], v[190:193], v[112:115]
	v_mfma_f32_16x16x32_bf16 v[124:127], v[132:135], v[198:201], v[124:127]
	v_mfma_f32_16x16x32_bf16 v[120:123], v[140:143], v[198:201], v[120:123]
	v_mfma_f32_16x16x32_bf16 v[76:79], v[132:135], v[206:209], v[76:79]
	v_mfma_f32_16x16x32_bf16 v[72:75], v[140:143], v[206:209], v[72:75]
	v_mfma_f32_16x16x32_bf16 v[68:71], v[132:135], v[214:217], v[68:71]
	v_mfma_f32_16x16x32_bf16 v[64:67], v[140:143], v[214:217], v[64:67]
	v_mfma_f32_16x16x32_bf16 v[36:39], v[144:147], v[186:189], 0
	v_mfma_f32_16x16x32_bf16 v[32:35], v[152:155], v[186:189], 0
	v_mfma_f32_16x16x32_bf16 v[44:47], v[144:147], v[194:197], 0
	v_mfma_f32_16x16x32_bf16 v[40:43], v[152:155], v[194:197], 0
	v_mfma_f32_16x16x32_bf16 v[52:55], v[144:147], v[202:205], 0
	v_mfma_f32_16x16x32_bf16 v[48:51], v[152:155], v[202:205], 0
	v_mfma_f32_16x16x32_bf16 v[60:63], v[144:147], v[210:213], 0
	v_mfma_f32_16x16x32_bf16 v[56:59], v[152:155], v[210:213], 0
	v_mfma_f32_16x16x32_bf16 v[36:39], v[148:151], v[190:193], v[36:39]
	v_mfma_f32_16x16x32_bf16 v[32:35], v[156:159], v[190:193], v[32:35]
	v_mfma_f32_16x16x32_bf16 v[44:47], v[148:151], v[198:201], v[44:47]
	v_mfma_f32_16x16x32_bf16 v[40:43], v[156:159], v[198:201], v[40:43]
	v_mfma_f32_16x16x32_bf16 v[52:55], v[148:151], v[206:209], v[52:55]
	v_mfma_f32_16x16x32_bf16 v[48:51], v[156:159], v[206:209], v[48:51]
	v_mfma_f32_16x16x32_bf16 v[60:63], v[148:151], v[214:217], v[60:63]
	v_mfma_f32_16x16x32_bf16 v[56:59], v[156:159], v[214:217], v[56:59]
	s_barrier
	s_setprio 0
	s_branch .Lzmid8

.Lzmid8:
	v_add_u32_e32 v140, s82, v179
	v_add_u32_e32 v156, s83, v179
	ds_read_b128 v[128:131], v140
	ds_read_b128 v[132:135], v140 offset:1024
	ds_read_b128 v[136:139], v140 offset:2048
	ds_read_b128 v[140:143], v140 offset:3072
	ds_read_b128 v[144:147], v156
	ds_read_b128 v[148:151], v156 offset:1024
	ds_read_b128 v[152:155], v156 offset:2048
	ds_read_b128 v[156:159], v156 offset:3072
	s_add_u32 s38, s38, 0x4000
	s_addc_u32 s39, s39, 0
	s_mov_b32 m0, s96
	ds_read_b128 v[186:189], v182 offset:32768
	ds_read_b128 v[190:193], v182 offset:33792
	ds_read_b128 v[194:197], v182 offset:34816
	ds_read_b128 v[198:201], v182 offset:35840
	ds_read_b128 v[202:205], v182 offset:36864
	ds_read_b128 v[206:209], v182 offset:37888
	ds_read_b128 v[210:213], v182 offset:38912
	ds_read_b128 v[214:217], v182 offset:39936
	global_load_lds_dwordx4 v160, s[38:39]
	s_mov_b32 m0, s97
	s_nop 0
	global_load_lds_dwordx4 v164, s[38:39]
	s_waitcnt vmcnt(8)
	s_waitcnt lgkmcnt(0)
	s_setprio 1
	s_barrier
	v_mfma_f32_16x16x32_bf16 v[92:95], v[128:131], v[186:189], v[92:95]
	v_mfma_f32_16x16x32_bf16 v[88:91], v[136:139], v[186:189], v[88:91]
	v_mfma_f32_16x16x32_bf16 v[12:15], v[128:131], v[194:197], v[12:15]
	v_mfma_f32_16x16x32_bf16 v[8:11], v[136:139], v[194:197], v[8:11]
	v_mfma_f32_16x16x32_bf16 v[100:103], v[128:131], v[202:205], v[100:103]
	v_mfma_f32_16x16x32_bf16 v[96:99], v[136:139], v[202:205], v[96:99]
	v_mfma_f32_16x16x32_bf16 v[108:111], v[128:131], v[210:213], v[108:111]
	v_mfma_f32_16x16x32_bf16 v[104:107], v[136:139], v[210:213], v[104:107]
	v_mfma_f32_16x16x32_bf16 v[92:95], v[132:135], v[190:193], v[92:95]
	v_mfma_f32_16x16x32_bf16 v[88:91], v[140:143], v[190:193], v[88:91]
	v_mfma_f32_16x16x32_bf16 v[12:15], v[132:135], v[198:201], v[12:15]
	v_mfma_f32_16x16x32_bf16 v[8:11], v[140:143], v[198:201], v[8:11]
	v_mfma_f32_16x16x32_bf16 v[100:103], v[132:135], v[206:209], v[100:103]
	v_mfma_f32_16x16x32_bf16 v[96:99], v[140:143], v[206:209], v[96:99]
	v_mfma_f32_16x16x32_bf16 v[108:111], v[132:135], v[214:217], v[108:111]
	v_mfma_f32_16x16x32_bf16 v[104:107], v[140:143], v[214:217], v[104:107]
	v_mfma_f32_16x16x32_bf16 v[84:87], v[144:147], v[186:189], v[84:87]
	v_mfma_f32_16x16x32_bf16 v[80:83], v[152:155], v[186:189], v[80:83]
	v_mfma_f32_16x16x32_bf16 v[4:7], v[144:147], v[194:197], v[4:7]
	v_mfma_f32_16x16x32_bf16 v[0:3], v[152:155], v[194:197], v[0:3]
	v_mfma_f32_16x16x32_bf16 v[20:23], v[144:147], v[202:205], v[20:23]
	v_mfma_f32_16x16x32_bf16 v[16:19], v[152:155], v[202:205], v[16:19]
	v_mfma_f32_16x16x32_bf16 v[28:31], v[144:147], v[210:213], v[28:31]
	v_mfma_f32_16x16x32_bf16 v[24:27], v[152:155], v[210:213], v[24:27]
	v_mfma_f32_16x16x32_bf16 v[84:87], v[148:151], v[190:193], v[84:87]
	v_mfma_f32_16x16x32_bf16 v[80:83], v[156:159], v[190:193], v[80:83]
	v_mfma_f32_16x16x32_bf16 v[4:7], v[148:151], v[198:201], v[4:7]
	v_mfma_f32_16x16x32_bf16 v[0:3], v[156:159], v[198:201], v[0:3]
	v_mfma_f32_16x16x32_bf16 v[20:23], v[148:151], v[206:209], v[20:23]
	v_mfma_f32_16x16x32_bf16 v[16:19], v[156:159], v[206:209], v[16:19]
	v_mfma_f32_16x16x32_bf16 v[28:31], v[148:151], v[214:217], v[28:31]
	v_mfma_f32_16x16x32_bf16 v[24:27], v[156:159], v[214:217], v[24:27]
	s_barrier
	s_setprio 0
	s_add_u32 s38, s10, 0x40000
	s_addc_u32 s39, s11, 0
	s_add_i32 s45, s82, s72
	s_mov_b32 m0, s45
	ds_read_b128 v[186:189], v182 offset:49152
	ds_read_b128 v[190:193], v182 offset:50176
	ds_read_b128 v[194:197], v182 offset:51200
	ds_read_b128 v[198:201], v182 offset:52224
	ds_read_b128 v[202:205], v182 offset:53248
	ds_read_b128 v[206:209], v182 offset:54272
	ds_read_b128 v[210:213], v182 offset:55296
	ds_read_b128 v[214:217], v182 offset:56320
	global_load_lds_dwordx4 v162, s[38:39]
	s_add_i32 m0, s45, 0x2000
	s_add_u32 s10, s10, 0x44000
	global_load_lds_dwordx4 v166, s[38:39]
	s_addc_u32 s11, s11, 0
	s_add_i32 s38, s83, s72
	s_mov_b32 m0, s38
	s_nop 0
	global_load_lds_dwordx4 v162, s[10:11]
	s_add_i32 m0, s38, 0x2000
	s_nop 0
	global_load_lds_dwordx4 v166, s[10:11]
	s_mov_b32 m0, s5
	s_nop 0
	global_load_lds_dwordx4 v160, s[8:9]
	s_mov_b32 m0, s68
	s_nop 0
	global_load_lds_dwordx4 v164, s[8:9]
	s_waitcnt vmcnt(8)
	s_waitcnt lgkmcnt(0)
	s_setprio 1
	s_barrier
	v_mfma_f32_16x16x32_bf16 v[116:119], v[128:131], v[186:189], v[116:119]
	v_mfma_f32_16x16x32_bf16 v[112:115], v[136:139], v[186:189], v[112:115]
	v_mfma_f32_16x16x32_bf16 v[124:127], v[128:131], v[194:197], v[124:127]
	v_mfma_f32_16x16x32_bf16 v[120:123], v[136:139], v[194:197], v[120:123]
	v_mfma_f32_16x16x32_bf16 v[76:79], v[128:131], v[202:205], v[76:79]
	v_mfma_f32_16x16x32_bf16 v[72:75], v[136:139], v[202:205], v[72:75]
	v_mfma_f32_16x16x32_bf16 v[68:71], v[128:131], v[210:213], v[68:71]
	v_mfma_f32_16x16x32_bf16 v[64:67], v[136:139], v[210:213], v[64:67]
	v_mfma_f32_16x16x32_bf16 v[116:119], v[132:135], v[190:193], v[116:119]
	v_mfma_f32_16x16x32_bf16 v[112:115], v[140:143], v[190:193], v[112:115]
	v_mfma_f32_16x16x32_bf16 v[124:127], v[132:135], v[198:201], v[124:127]
	v_mfma_f32_16x16x32_bf16 v[120:123], v[140:143], v[198:201], v[120:123]
	v_mfma_f32_16x16x32_bf16 v[76:79], v[132:135], v[206:209], v[76:79]
	v_mfma_f32_16x16x32_bf16 v[72:75], v[140:143], v[206:209], v[72:75]
	v_mfma_f32_16x16x32_bf16 v[68:71], v[132:135], v[214:217], v[68:71]
	v_mfma_f32_16x16x32_bf16 v[64:67], v[140:143], v[214:217], v[64:67]
	v_mfma_f32_16x16x32_bf16 v[36:39], v[144:147], v[186:189], v[36:39]
	v_mfma_f32_16x16x32_bf16 v[32:35], v[152:155], v[186:189], v[32:35]
	v_mfma_f32_16x16x32_bf16 v[44:47], v[144:147], v[194:197], v[44:47]
	v_mfma_f32_16x16x32_bf16 v[40:43], v[152:155], v[194:197], v[40:43]
	v_mfma_f32_16x16x32_bf16 v[52:55], v[144:147], v[202:205], v[52:55]
	v_mfma_f32_16x16x32_bf16 v[48:51], v[152:155], v[202:205], v[48:51]
	v_mfma_f32_16x16x32_bf16 v[60:63], v[144:147], v[210:213], v[60:63]
	v_mfma_f32_16x16x32_bf16 v[56:59], v[152:155], v[210:213], v[56:59]
	v_mfma_f32_16x16x32_bf16 v[36:39], v[148:151], v[190:193], v[36:39]
	v_mfma_f32_16x16x32_bf16 v[32:35], v[156:159], v[190:193], v[32:35]
	v_mfma_f32_16x16x32_bf16 v[44:47], v[148:151], v[198:201], v[44:47]
	v_mfma_f32_16x16x32_bf16 v[40:43], v[156:159], v[198:201], v[40:43]
	v_mfma_f32_16x16x32_bf16 v[52:55], v[148:151], v[206:209], v[52:55]
	v_mfma_f32_16x16x32_bf16 v[48:51], v[156:159], v[206:209], v[48:51]
	v_mfma_f32_16x16x32_bf16 v[60:63], v[148:151], v[214:217], v[60:63]
	v_mfma_f32_16x16x32_bf16 v[56:59], v[156:159], v[214:217], v[56:59]
	s_barrier
	s_setprio 0
	s_add_i32 s44, s44, 2
	s_add_u32 s42, s42, 0x80000
	s_addc_u32 s43, s43, 0
	s_add_u32 s6, s6, 0x800000
	s_addc_u32 s7, s7, 0
	s_cmpk_gt_u32 s44, 0x55
	s_cbranch_scc0 .LBB0_1706
	s_and_b64 vcc, exec, s[26:27]
	s_cbranch_vccz .LBB0_1709
	s_barrier

.Lzmid10:
	v_add_u32_e32 v140, s82, v179
	v_add_u32_e32 v156, s83, v179
	ds_read_b128 v[128:131], v140
	ds_read_b128 v[132:135], v140 offset:1024
	ds_read_b128 v[136:139], v140 offset:2048
	ds_read_b128 v[140:143], v140 offset:3072
	ds_read_b128 v[144:147], v156
	ds_read_b128 v[148:151], v156 offset:1024
	ds_read_b128 v[152:155], v156 offset:2048
	ds_read_b128 v[156:159], v156 offset:3072
	s_add_u32 s38, s38, 0x4000
	s_addc_u32 s39, s39, 0
	s_mov_b32 m0, s96
	ds_read_b128 v[186:189], v182 offset:32768
	ds_read_b128 v[190:193], v182 offset:33792
	ds_read_b128 v[194:197], v182 offset:34816
	ds_read_b128 v[198:201], v182 offset:35840
	ds_read_b128 v[202:205], v182 offset:36864
	ds_read_b128 v[206:209], v182 offset:37888
	ds_read_b128 v[210:213], v182 offset:38912
	ds_read_b128 v[214:217], v182 offset:39936
	global_load_lds_dwordx4 v160, s[38:39]
	s_mov_b32 m0, s97
	s_nop 0
	global_load_lds_dwordx4 v164, s[38:39]
	s_waitcnt vmcnt(8)
	s_waitcnt lgkmcnt(0)
	s_setprio 1
	s_barrier
	v_mfma_f32_16x16x32_bf16 v[92:95], v[128:131], v[186:189], v[92:95]
	v_mfma_f32_16x16x32_bf16 v[88:91], v[136:139], v[186:189], v[88:91]
	v_mfma_f32_16x16x32_bf16 v[12:15], v[128:131], v[194:197], v[12:15]
	v_mfma_f32_16x16x32_bf16 v[8:11], v[136:139], v[194:197], v[8:11]
	v_mfma_f32_16x16x32_bf16 v[100:103], v[128:131], v[202:205], v[100:103]
	v_mfma_f32_16x16x32_bf16 v[96:99], v[136:139], v[202:205], v[96:99]
	v_mfma_f32_16x16x32_bf16 v[108:111], v[128:131], v[210:213], v[108:111]
	v_mfma_f32_16x16x32_bf16 v[104:107], v[136:139], v[210:213], v[104:107]
	v_mfma_f32_16x16x32_bf16 v[92:95], v[132:135], v[190:193], v[92:95]
	v_mfma_f32_16x16x32_bf16 v[88:91], v[140:143], v[190:193], v[88:91]
	v_mfma_f32_16x16x32_bf16 v[12:15], v[132:135], v[198:201], v[12:15]
	v_mfma_f32_16x16x32_bf16 v[8:11], v[140:143], v[198:201], v[8:11]
	v_mfma_f32_16x16x32_bf16 v[100:103], v[132:135], v[206:209], v[100:103]
	v_mfma_f32_16x16x32_bf16 v[96:99], v[140:143], v[206:209], v[96:99]
	v_mfma_f32_16x16x32_bf16 v[108:111], v[132:135], v[214:217], v[108:111]
	v_mfma_f32_16x16x32_bf16 v[104:107], v[140:143], v[214:217], v[104:107]
	v_mfma_f32_16x16x32_bf16 v[84:87], v[144:147], v[186:189], v[84:87]
	v_mfma_f32_16x16x32_bf16 v[80:83], v[152:155], v[186:189], v[80:83]
	v_mfma_f32_16x16x32_bf16 v[4:7], v[144:147], v[194:197], v[4:7]
	v_mfma_f32_16x16x32_bf16 v[0:3], v[152:155], v[194:197], v[0:3]
	v_mfma_f32_16x16x32_bf16 v[20:23], v[144:147], v[202:205], v[20:23]
	v_mfma_f32_16x16x32_bf16 v[16:19], v[152:155], v[202:205], v[16:19]
	v_mfma_f32_16x16x32_bf16 v[28:31], v[144:147], v[210:213], v[28:31]
	v_mfma_f32_16x16x32_bf16 v[24:27], v[152:155], v[210:213], v[24:27]
	v_mfma_f32_16x16x32_bf16 v[84:87], v[148:151], v[190:193], v[84:87]
	v_mfma_f32_16x16x32_bf16 v[80:83], v[156:159], v[190:193], v[80:83]
	v_mfma_f32_16x16x32_bf16 v[4:7], v[148:151], v[198:201], v[4:7]
	v_mfma_f32_16x16x32_bf16 v[0:3], v[156:159], v[198:201], v[0:3]
	v_mfma_f32_16x16x32_bf16 v[20:23], v[148:151], v[206:209], v[20:23]
	v_mfma_f32_16x16x32_bf16 v[16:19], v[156:159], v[206:209], v[16:19]
	v_mfma_f32_16x16x32_bf16 v[28:31], v[148:151], v[214:217], v[28:31]
	v_mfma_f32_16x16x32_bf16 v[24:27], v[156:159], v[214:217], v[24:27]
	s_barrier
	s_setprio 0
	s_add_u32 s38, s10, 0x40000
	s_addc_u32 s39, s11, 0
	s_add_i32 s45, s82, s72
	s_mov_b32 m0, s45
	ds_read_b128 v[186:189], v182 offset:49152
	ds_read_b128 v[190:193], v182 offset:50176
	ds_read_b128 v[194:197], v182 offset:51200
	ds_read_b128 v[198:201], v182 offset:52224
	ds_read_b128 v[202:205], v182 offset:53248
	ds_read_b128 v[206:209], v182 offset:54272
	ds_read_b128 v[210:213], v182 offset:55296
	ds_read_b128 v[214:217], v182 offset:56320
	global_load_lds_dwordx4 v162, s[38:39]
	s_add_i32 m0, s45, 0x2000
	s_add_u32 s10, s10, 0x44000
	global_load_lds_dwordx4 v166, s[38:39]
	s_addc_u32 s11, s11, 0
	s_add_i32 s38, s83, s72
	s_mov_b32 m0, s38
	s_nop 0
	global_load_lds_dwordx4 v162, s[10:11]
	s_add_i32 m0, s38, 0x2000
	s_nop 0
	global_load_lds_dwordx4 v166, s[10:11]
	s_mov_b32 m0, s4
	s_nop 0
	global_load_lds_dwordx4 v160, s[8:9]
	s_mov_b32 m0, s5
	s_nop 0
	global_load_lds_dwordx4 v164, s[8:9]
	s_waitcnt vmcnt(8)
	s_waitcnt lgkmcnt(0)
	s_setprio 1
	s_barrier
	v_mfma_f32_16x16x32_bf16 v[116:119], v[128:131], v[186:189], v[116:119]
	v_mfma_f32_16x16x32_bf16 v[112:115], v[136:139], v[186:189], v[112:115]
	v_mfma_f32_16x16x32_bf16 v[124:127], v[128:131], v[194:197], v[124:127]
	v_mfma_f32_16x16x32_bf16 v[120:123], v[136:139], v[194:197], v[120:123]
	v_mfma_f32_16x16x32_bf16 v[76:79], v[128:131], v[202:205], v[76:79]
	v_mfma_f32_16x16x32_bf16 v[72:75], v[136:139], v[202:205], v[72:75]
	v_mfma_f32_16x16x32_bf16 v[68:71], v[128:131], v[210:213], v[68:71]
	v_mfma_f32_16x16x32_bf16 v[64:67], v[136:139], v[210:213], v[64:67]
	v_mfma_f32_16x16x32_bf16 v[116:119], v[132:135], v[190:193], v[116:119]
	v_mfma_f32_16x16x32_bf16 v[112:115], v[140:143], v[190:193], v[112:115]
	v_mfma_f32_16x16x32_bf16 v[124:127], v[132:135], v[198:201], v[124:127]
	v_mfma_f32_16x16x32_bf16 v[120:123], v[140:143], v[198:201], v[120:123]
	v_mfma_f32_16x16x32_bf16 v[76:79], v[132:135], v[206:209], v[76:79]
	v_mfma_f32_16x16x32_bf16 v[72:75], v[140:143], v[206:209], v[72:75]
	v_mfma_f32_16x16x32_bf16 v[68:71], v[132:135], v[214:217], v[68:71]
	v_mfma_f32_16x16x32_bf16 v[64:67], v[140:143], v[214:217], v[64:67]
	v_mfma_f32_16x16x32_bf16 v[36:39], v[144:147], v[186:189], v[36:39]
	v_mfma_f32_16x16x32_bf16 v[32:35], v[152:155], v[186:189], v[32:35]
	v_mfma_f32_16x16x32_bf16 v[44:47], v[144:147], v[194:197], v[44:47]
	v_mfma_f32_16x16x32_bf16 v[40:43], v[152:155], v[194:197], v[40:43]
	v_mfma_f32_16x16x32_bf16 v[52:55], v[144:147], v[202:205], v[52:55]
	v_mfma_f32_16x16x32_bf16 v[48:51], v[152:155], v[202:205], v[48:51]
	v_mfma_f32_16x16x32_bf16 v[60:63], v[144:147], v[210:213], v[60:63]
	v_mfma_f32_16x16x32_bf16 v[56:59], v[152:155], v[210:213], v[56:59]
	v_mfma_f32_16x16x32_bf16 v[36:39], v[148:151], v[190:193], v[36:39]
	v_mfma_f32_16x16x32_bf16 v[32:35], v[156:159], v[190:193], v[32:35]
	v_mfma_f32_16x16x32_bf16 v[44:47], v[148:151], v[198:201], v[44:47]
	v_mfma_f32_16x16x32_bf16 v[40:43], v[156:159], v[198:201], v[40:43]
	v_mfma_f32_16x16x32_bf16 v[52:55], v[148:151], v[206:209], v[52:55]
	v_mfma_f32_16x16x32_bf16 v[48:51], v[156:159], v[206:209], v[48:51]
	v_mfma_f32_16x16x32_bf16 v[60:63], v[148:151], v[214:217], v[60:63]
	v_mfma_f32_16x16x32_bf16 v[56:59], v[156:159], v[214:217], v[56:59]
	s_barrier
	s_setprio 0
	s_add_i32 s44, s44, 2
	s_add_u32 s42, s42, 0x80000
	s_addc_u32 s43, s43, 0
	s_add_u32 s6, s6, 0x800000
	s_addc_u32 s7, s7, 0
	s_cmpk_gt_u32 s44, 0x55
	s_cbranch_scc0 .LBB0_1900
	s_and_b64 vcc, exec, s[26:27]
	s_cbranch_vccz .LBB0_1903
	s_barrier

.LBB0_1998:
	s_mov_b32 s17, s9
	s_lshl_b64 s[20:21], s[16:17], 1
	s_add_u32 s20, s58, s20
	s_addc_u32 s21, s59, s21
	s_and_b64 s[22:23], s[6:7], exec
	s_mov_b32 s19, s9
	s_cselect_b32 s17, s21, s27
	s_cselect_b32 s51, s20, s26
	s_lshl_b64 s[22:23], s[18:19], 1
	s_add_u32 s22, s4, s22
	s_addc_u32 s23, s5, s23
	s_and_b64 s[28:29], s[6:7], exec
	s_cselect_b32 s19, s23, s25
	s_cselect_b32 s52, s22, s24
	s_add_u32 s53, s24, 0x1b0000
	s_addc_u32 s54, s25, 0
	s_add_u32 s24, s26, 0x404000
	s_addc_u32 s25, s27, 0
	s_mov_b32 s55, -2
	ds_read_b128 v[144:147], v153
	ds_read_b128 v[156:159], v153 offset:1024
	ds_read_b128 v[160:163], v153 offset:2048
	ds_read_b128 v[164:167], v153 offset:3072
	ds_read_b128 v[168:171], v154
	ds_read_b128 v[172:175], v154 offset:1024
	ds_read_b128 v[176:179], v154 offset:2048
	ds_read_b128 v[180:183], v154 offset:3072
	s_add_u32 s26, s24, 0x3fc000
	s_addc_u32 s27, s25, 0
	s_cmp_eq_u32 s55, 28
	s_cselect_b32 s30, s51, s26
	s_cselect_b32 s31, s17, s27
	s_cselect_b32 s28, s52, s53
	s_cselect_b32 s29, s19, s54
	s_add_u32 s26, s30, 0x400000
	s_addc_u32 s27, s31, 0
	s_add_i32 m0, s35, 0xc000
	ds_read_b128 v[184:187], v155
	ds_read_b128 v[188:191], v155 offset:1024
	ds_read_b128 v[192:195], v155 offset:2048
	ds_read_b128 v[196:199], v155 offset:3072
	ds_read_b128 v[200:203], v155 offset:4096
	ds_read_b128 v[204:207], v155 offset:5120
	ds_read_b128 v[208:211], v155 offset:6144
	ds_read_b128 v[212:215], v155 offset:7168
	global_load_lds_dwordx4 v136, s[24:25]
	s_add_i32 m0, s35, 0xe000
	s_nop 0
	global_load_lds_dwordx4 v138, s[24:25]
	s_waitcnt vmcnt(8)
	s_waitcnt lgkmcnt(0)
	s_setprio 1
	s_barrier
	v_mfma_f32_16x16x32_bf16 v[76:79], v[144:147], v[184:187], 0
	v_mfma_f32_16x16x32_bf16 v[72:75], v[160:163], v[184:187], 0
	v_mfma_f32_16x16x32_bf16 v[68:71], v[144:147], v[192:195], 0
	v_mfma_f32_16x16x32_bf16 v[64:67], v[160:163], v[192:195], 0
	v_mfma_f32_16x16x32_bf16 v[56:59], v[144:147], v[200:203], 0
	v_mfma_f32_16x16x32_bf16 v[52:55], v[160:163], v[200:203], 0
	v_mfma_f32_16x16x32_bf16 v[44:47], v[144:147], v[208:211], 0
	v_mfma_f32_16x16x32_bf16 v[40:43], v[160:163], v[208:211], 0
	v_mfma_f32_16x16x32_bf16 v[76:79], v[156:159], v[188:191], v[76:79]
	v_mfma_f32_16x16x32_bf16 v[72:75], v[164:167], v[188:191], v[72:75]
	v_mfma_f32_16x16x32_bf16 v[68:71], v[156:159], v[196:199], v[68:71]
	v_mfma_f32_16x16x32_bf16 v[64:67], v[164:167], v[196:199], v[64:67]
	v_mfma_f32_16x16x32_bf16 v[56:59], v[156:159], v[204:207], v[56:59]
	v_mfma_f32_16x16x32_bf16 v[52:55], v[164:167], v[204:207], v[52:55]
	v_mfma_f32_16x16x32_bf16 v[44:47], v[156:159], v[212:215], v[44:47]
	v_mfma_f32_16x16x32_bf16 v[40:43], v[164:167], v[212:215], v[40:43]
	v_mfma_f32_16x16x32_bf16 v[124:127], v[168:171], v[184:187], 0
	v_mfma_f32_16x16x32_bf16 v[120:123], v[176:179], v[184:187], 0
	v_mfma_f32_16x16x32_bf16 v[116:119], v[168:171], v[192:195], 0
	v_mfma_f32_16x16x32_bf16 v[112:115], v[176:179], v[192:195], 0
	v_mfma_f32_16x16x32_bf16 v[108:111], v[168:171], v[200:203], 0
	v_mfma_f32_16x16x32_bf16 v[104:107], v[176:179], v[200:203], 0
	v_mfma_f32_16x16x32_bf16 v[100:103], v[168:171], v[208:211], 0
	v_mfma_f32_16x16x32_bf16 v[96:99], v[176:179], v[208:211], 0
	v_mfma_f32_16x16x32_bf16 v[124:127], v[172:175], v[188:191], v[124:127]
	v_mfma_f32_16x16x32_bf16 v[120:123], v[180:183], v[188:191], v[120:123]
	v_mfma_f32_16x16x32_bf16 v[116:119], v[172:175], v[196:199], v[116:119]
	v_mfma_f32_16x16x32_bf16 v[112:115], v[180:183], v[196:199], v[112:115]
	v_mfma_f32_16x16x32_bf16 v[108:111], v[172:175], v[204:207], v[108:111]
	v_mfma_f32_16x16x32_bf16 v[104:107], v[180:183], v[204:207], v[104:107]
	v_mfma_f32_16x16x32_bf16 v[100:103], v[172:175], v[212:215], v[100:103]
	v_mfma_f32_16x16x32_bf16 v[96:99], v[180:183], v[212:215], v[96:99]
	s_barrier
	s_setprio 0
	s_add_i32 s56, s57, s34
	s_mov_b32 m0, s56
	ds_read_b128 v[184:187], v155 offset:16384
	ds_read_b128 v[188:191], v155 offset:17408
	ds_read_b128 v[192:195], v155 offset:18432
	ds_read_b128 v[196:199], v155 offset:19456
	ds_read_b128 v[200:203], v155 offset:20480
	ds_read_b128 v[204:207], v155 offset:21504
	ds_read_b128 v[208:211], v155 offset:22528
	ds_read_b128 v[212:215], v155 offset:23552
	global_load_lds_dwordx4 v132, s[28:29]
	s_add_i32 m0, s56, 0x2000
	s_add_u32 s68, s28, 0x4000
	s_addc_u32 s69, s29, 0
	s_add_i32 s56, s81, s34
	global_load_lds_dwordx4 v128, s[28:29]
	s_mov_b32 m0, s56
	s_nop 0
	global_load_lds_dwordx4 v132, s[68:69]
	s_add_i32 m0, s56, 0x2000
	s_nop 0
	global_load_lds_dwordx4 v128, s[68:69]
	s_mov_b32 m0, s35
	s_nop 0
	global_load_lds_dwordx4 v134, s[30:31]
	s_mov_b32 m0, s36
	s_nop 0
	global_load_lds_dwordx4 v130, s[30:31]
	s_waitcnt vmcnt(8)
	s_waitcnt lgkmcnt(0)
	s_setprio 1
	s_barrier
	v_mfma_f32_16x16x32_bf16 v[28:31], v[144:147], v[184:187], 0
	v_mfma_f32_16x16x32_bf16 v[24:27], v[160:163], v[184:187], 0
	v_mfma_f32_16x16x32_bf16 v[20:23], v[144:147], v[192:195], 0
	v_mfma_f32_16x16x32_bf16 v[16:19], v[160:163], v[192:195], 0
	v_mfma_f32_16x16x32_bf16 v[12:15], v[144:147], v[200:203], 0
	v_mfma_f32_16x16x32_bf16 v[8:11], v[160:163], v[200:203], 0
	v_mfma_f32_16x16x32_bf16 v[4:7], v[144:147], v[208:211], 0
	v_mfma_f32_16x16x32_bf16 v[0:3], v[160:163], v[208:211], 0
	v_mfma_f32_16x16x32_bf16 v[28:31], v[156:159], v[188:191], v[28:31]
	v_mfma_f32_16x16x32_bf16 v[24:27], v[164:167], v[188:191], v[24:27]
	v_mfma_f32_16x16x32_bf16 v[20:23], v[156:159], v[196:199], v[20:23]
	v_mfma_f32_16x16x32_bf16 v[16:19], v[164:167], v[196:199], v[16:19]
	v_mfma_f32_16x16x32_bf16 v[12:15], v[156:159], v[204:207], v[12:15]
	v_mfma_f32_16x16x32_bf16 v[8:11], v[164:167], v[204:207], v[8:11]
	v_mfma_f32_16x16x32_bf16 v[4:7], v[156:159], v[212:215], v[4:7]
	v_mfma_f32_16x16x32_bf16 v[0:3], v[164:167], v[212:215], v[0:3]
	v_mfma_f32_16x16x32_bf16 v[92:95], v[168:171], v[184:187], 0
	v_mfma_f32_16x16x32_bf16 v[88:91], v[176:179], v[184:187], 0
	v_mfma_f32_16x16x32_bf16 v[84:87], v[168:171], v[192:195], 0
	v_mfma_f32_16x16x32_bf16 v[80:83], v[176:179], v[192:195], 0
	v_mfma_f32_16x16x32_bf16 v[60:63], v[168:171], v[200:203], 0
	v_mfma_f32_16x16x32_bf16 v[48:51], v[176:179], v[200:203], 0
	v_mfma_f32_16x16x32_bf16 v[36:39], v[168:171], v[208:211], 0
	v_mfma_f32_16x16x32_bf16 v[32:35], v[176:179], v[208:211], 0
	v_mfma_f32_16x16x32_bf16 v[92:95], v[172:175], v[188:191], v[92:95]
	v_mfma_f32_16x16x32_bf16 v[88:91], v[180:183], v[188:191], v[88:91]
	v_mfma_f32_16x16x32_bf16 v[84:87], v[172:175], v[196:199], v[84:87]
	v_mfma_f32_16x16x32_bf16 v[80:83], v[180:183], v[196:199], v[80:83]
	v_mfma_f32_16x16x32_bf16 v[60:63], v[172:175], v[204:207], v[60:63]
	v_mfma_f32_16x16x32_bf16 v[48:51], v[180:183], v[204:207], v[48:51]
	v_mfma_f32_16x16x32_bf16 v[36:39], v[172:175], v[212:215], v[36:39]
	v_mfma_f32_16x16x32_bf16 v[32:35], v[180:183], v[212:215], v[32:35]
	s_barrier
	s_setprio 0
	s_branch .Lzmid11

.Lzmid11:
	v_add_u32_e32 v148, s82, v152
	ds_read_b128 v[144:147], v148
	ds_read_b128 v[156:159], v148 offset:1024
	ds_read_b128 v[160:163], v148 offset:2048
	ds_read_b128 v[164:167], v148 offset:3072
	v_add_u32_e32 v148, s83, v152
	ds_read_b128 v[168:171], v148
	ds_read_b128 v[172:175], v148 offset:1024
	ds_read_b128 v[176:179], v148 offset:2048
	ds_read_b128 v[180:183], v148 offset:3072
	s_add_u32 s30, s30, 0x4000
	s_addc_u32 s31, s31, 0
	s_mov_b32 m0, s37
	ds_read_b128 v[184:187], v155 offset:32768
	ds_read_b128 v[188:191], v155 offset:33792
	ds_read_b128 v[192:195], v155 offset:34816
	ds_read_b128 v[196:199], v155 offset:35840
	ds_read_b128 v[200:203], v155 offset:36864
	ds_read_b128 v[204:207], v155 offset:37888
	ds_read_b128 v[208:211], v155 offset:38912
	ds_read_b128 v[212:215], v155 offset:39936
	global_load_lds_dwordx4 v134, s[30:31]
	s_mov_b32 m0, s38
	s_nop 0
	global_load_lds_dwordx4 v130, s[30:31]
	s_waitcnt vmcnt(8)
	s_waitcnt lgkmcnt(0)
	s_setprio 1
	s_barrier
	v_mfma_f32_16x16x32_bf16 v[76:79], v[144:147], v[184:187], v[76:79]
	v_mfma_f32_16x16x32_bf16 v[72:75], v[160:163], v[184:187], v[72:75]
	v_mfma_f32_16x16x32_bf16 v[68:71], v[144:147], v[192:195], v[68:71]
	v_mfma_f32_16x16x32_bf16 v[64:67], v[160:163], v[192:195], v[64:67]
	v_mfma_f32_16x16x32_bf16 v[56:59], v[144:147], v[200:203], v[56:59]
	v_mfma_f32_16x16x32_bf16 v[52:55], v[160:163], v[200:203], v[52:55]
	v_mfma_f32_16x16x32_bf16 v[44:47], v[144:147], v[208:211], v[44:47]
	v_mfma_f32_16x16x32_bf16 v[40:43], v[160:163], v[208:211], v[40:43]
	v_mfma_f32_16x16x32_bf16 v[76:79], v[156:159], v[188:191], v[76:79]
	v_mfma_f32_16x16x32_bf16 v[72:75], v[164:167], v[188:191], v[72:75]
	v_mfma_f32_16x16x32_bf16 v[68:71], v[156:159], v[196:199], v[68:71]
	v_mfma_f32_16x16x32_bf16 v[64:67], v[164:167], v[196:199], v[64:67]
	v_mfma_f32_16x16x32_bf16 v[56:59], v[156:159], v[204:207], v[56:59]
	v_mfma_f32_16x16x32_bf16 v[52:55], v[164:167], v[204:207], v[52:55]
	v_mfma_f32_16x16x32_bf16 v[44:47], v[156:159], v[212:215], v[44:47]
	v_mfma_f32_16x16x32_bf16 v[40:43], v[164:167], v[212:215], v[40:43]
	v_mfma_f32_16x16x32_bf16 v[124:127], v[168:171], v[184:187], v[124:127]
	v_mfma_f32_16x16x32_bf16 v[120:123], v[176:179], v[184:187], v[120:123]
	v_mfma_f32_16x16x32_bf16 v[116:119], v[168:171], v[192:195], v[116:119]
	v_mfma_f32_16x16x32_bf16 v[112:115], v[176:179], v[192:195], v[112:115]
	v_mfma_f32_16x16x32_bf16 v[108:111], v[168:171], v[200:203], v[108:111]
	v_mfma_f32_16x16x32_bf16 v[104:107], v[176:179], v[200:203], v[104:107]
	v_mfma_f32_16x16x32_bf16 v[100:103], v[168:171], v[208:211], v[100:103]
	v_mfma_f32_16x16x32_bf16 v[96:99], v[176:179], v[208:211], v[96:99]
	v_mfma_f32_16x16x32_bf16 v[124:127], v[172:175], v[188:191], v[124:127]
	v_mfma_f32_16x16x32_bf16 v[120:123], v[180:183], v[188:191], v[120:123]
	v_mfma_f32_16x16x32_bf16 v[116:119], v[172:175], v[196:199], v[116:119]
	v_mfma_f32_16x16x32_bf16 v[112:115], v[180:183], v[196:199], v[112:115]
	v_mfma_f32_16x16x32_bf16 v[108:111], v[172:175], v[204:207], v[108:111]
	v_mfma_f32_16x16x32_bf16 v[104:107], v[180:183], v[204:207], v[104:107]
	v_mfma_f32_16x16x32_bf16 v[100:103], v[172:175], v[212:215], v[100:103]
	v_mfma_f32_16x16x32_bf16 v[96:99], v[180:183], v[212:215], v[96:99]
	s_barrier
	s_setprio 0
	s_add_u32 s30, s28, 0xd8000
	s_addc_u32 s31, s29, 0
	s_add_i32 s56, s82, s34
	s_mov_b32 m0, s56
	ds_read_b128 v[184:187], v155 offset:49152
	ds_read_b128 v[188:191], v155 offset:50176
	ds_read_b128 v[192:195], v155 offset:51200
	ds_read_b128 v[196:199], v155 offset:52224
	ds_read_b128 v[200:203], v155 offset:53248
	ds_read_b128 v[204:207], v155 offset:54272
	ds_read_b128 v[208:211], v155 offset:55296
	ds_read_b128 v[212:215], v155 offset:56320
	global_load_lds_dwordx4 v132, s[30:31]
	s_add_i32 m0, s56, 0x2000
	s_add_u32 s28, s28, 0xdc000
	global_load_lds_dwordx4 v128, s[30:31]
	s_addc_u32 s29, s29, 0
	s_add_i32 s30, s83, s34
	s_mov_b32 m0, s30
	s_nop 0
	global_load_lds_dwordx4 v132, s[28:29]
	s_add_i32 m0, s30, 0x2000
	s_nop 0
	global_load_lds_dwordx4 v128, s[28:29]
	s_mov_b32 m0, s42
	s_nop 0
	global_load_lds_dwordx4 v134, s[26:27]
	s_mov_b32 m0, s43
	s_nop 0
	global_load_lds_dwordx4 v130, s[26:27]
	s_waitcnt vmcnt(8)
	s_waitcnt lgkmcnt(0)
	s_setprio 1
	s_barrier
	v_mfma_f32_16x16x32_bf16 v[28:31], v[144:147], v[184:187], v[28:31]
	v_mfma_f32_16x16x32_bf16 v[24:27], v[160:163], v[184:187], v[24:27]
	v_mfma_f32_16x16x32_bf16 v[20:23], v[144:147], v[192:195], v[20:23]
	v_mfma_f32_16x16x32_bf16 v[16:19], v[160:163], v[192:195], v[16:19]
	v_mfma_f32_16x16x32_bf16 v[12:15], v[144:147], v[200:203], v[12:15]
	v_mfma_f32_16x16x32_bf16 v[8:11], v[160:163], v[200:203], v[8:11]
	v_mfma_f32_16x16x32_bf16 v[4:7], v[144:147], v[208:211], v[4:7]
	v_mfma_f32_16x16x32_bf16 v[0:3], v[160:163], v[208:211], v[0:3]
	v_mfma_f32_16x16x32_bf16 v[28:31], v[156:159], v[188:191], v[28:31]
	v_mfma_f32_16x16x32_bf16 v[24:27], v[164:167], v[188:191], v[24:27]
	v_mfma_f32_16x16x32_bf16 v[20:23], v[156:159], v[196:199], v[20:23]
	v_mfma_f32_16x16x32_bf16 v[16:19], v[164:167], v[196:199], v[16:19]
	v_mfma_f32_16x16x32_bf16 v[12:15], v[156:159], v[204:207], v[12:15]
	v_mfma_f32_16x16x32_bf16 v[8:11], v[164:167], v[204:207], v[8:11]
	v_mfma_f32_16x16x32_bf16 v[4:7], v[156:159], v[212:215], v[4:7]
	v_mfma_f32_16x16x32_bf16 v[0:3], v[164:167], v[212:215], v[0:3]
	v_mfma_f32_16x16x32_bf16 v[92:95], v[168:171], v[184:187], v[92:95]
	v_mfma_f32_16x16x32_bf16 v[88:91], v[176:179], v[184:187], v[88:91]
	v_mfma_f32_16x16x32_bf16 v[84:87], v[168:171], v[192:195], v[84:87]
	v_mfma_f32_16x16x32_bf16 v[80:83], v[176:179], v[192:195], v[80:83]
	v_mfma_f32_16x16x32_bf16 v[60:63], v[168:171], v[200:203], v[60:63]
	v_mfma_f32_16x16x32_bf16 v[48:51], v[176:179], v[200:203], v[48:51]
	v_mfma_f32_16x16x32_bf16 v[36:39], v[168:171], v[208:211], v[36:39]
	v_mfma_f32_16x16x32_bf16 v[32:35], v[176:179], v[208:211], v[32:35]
	v_mfma_f32_16x16x32_bf16 v[92:95], v[172:175], v[188:191], v[92:95]
	v_mfma_f32_16x16x32_bf16 v[88:91], v[180:183], v[188:191], v[88:91]
	v_mfma_f32_16x16x32_bf16 v[84:87], v[172:175], v[196:199], v[84:87]
	v_mfma_f32_16x16x32_bf16 v[80:83], v[180:183], v[196:199], v[80:83]
	v_mfma_f32_16x16x32_bf16 v[60:63], v[172:175], v[204:207], v[60:63]
	v_mfma_f32_16x16x32_bf16 v[48:51], v[180:183], v[204:207], v[48:51]
	v_mfma_f32_16x16x32_bf16 v[36:39], v[172:175], v[212:215], v[36:39]
	v_mfma_f32_16x16x32_bf16 v[32:35], v[180:183], v[212:215], v[32:35]
	s_barrier
	s_setprio 0
	s_add_i32 s55, s55, 2
	s_add_u32 s53, s53, 0x1b0000
	s_addc_u32 s54, s54, 0
	s_add_u32 s24, s24, 0x800000
	s_addc_u32 s25, s25, 0
	s_cmp_gt_u32 s55, 29
	s_cbranch_scc0 .LBB0_1999
	s_and_b64 vcc, exec, s[12:13]
	s_cbranch_vccz .LBB0_2002
	s_barrier

.LBB0_2541:
	s_mov_b32 s29, s11
	s_lshl_b64 s[30:31], s[28:29], 1
	s_add_u32 s30, s64, s30
	s_addc_u32 s31, s65, s31
	s_and_b64 s[36:37], exec, s[8:9]
	s_cselect_b32 s10, s31, s7
	s_cselect_b32 s13, s30, s6
	s_lshl_b64 s[34:35], s[34:35], 1
	s_add_u32 s34, s2, s34
	s_addc_u32 s35, s3, s35
	s_and_b64 s[8:9], exec, s[8:9]
	s_cselect_b32 s29, s35, s1
	s_cselect_b32 s39, s34, s0
	s_add_u32 s40, s0, 0x80000
	s_addc_u32 s41, s1, 0
	s_add_u32 s0, s6, 0x404000
	s_addc_u32 s1, s7, 0
	s_mov_b32 s42, -2
	ds_read_b128 v[128:131], v180
	ds_read_b128 v[132:135], v180 offset:1024
	ds_read_b128 v[136:139], v180 offset:2048
	ds_read_b128 v[140:143], v180 offset:3072
	ds_read_b128 v[144:147], v181
	ds_read_b128 v[148:151], v181 offset:1024
	ds_read_b128 v[152:155], v181 offset:2048
	ds_read_b128 v[156:159], v181 offset:3072
	s_add_u32 s6, s0, 0x3fc000
	s_addc_u32 s7, s1, 0
	s_cmp_eq_u32 s42, 28
	s_cselect_b32 s36, s13, s6
	s_cselect_b32 s37, s10, s7
	s_cselect_b32 s8, s39, s40
	s_cselect_b32 s9, s29, s41
	s_add_u32 s6, s36, 0x400000
	s_addc_u32 s7, s37, 0
	s_add_i32 m0, s33, 0xc000
	ds_read_b128 v[186:189], v182
	ds_read_b128 v[190:193], v182 offset:1024
	ds_read_b128 v[194:197], v182 offset:2048
	ds_read_b128 v[198:201], v182 offset:3072
	ds_read_b128 v[202:205], v182 offset:4096
	ds_read_b128 v[206:209], v182 offset:5120
	ds_read_b128 v[210:213], v182 offset:6144
	ds_read_b128 v[214:217], v182 offset:7168
	global_load_lds_dwordx4 v168, s[0:1]
	s_add_i32 m0, s33, 0xe000
	s_nop 0
	global_load_lds_dwordx4 v170, s[0:1]
	s_waitcnt vmcnt(8)
	s_waitcnt lgkmcnt(0)
	s_setprio 1
	s_barrier
	v_mfma_f32_16x16x32_bf16 v[104:107], v[128:131], v[186:189], 0
	v_mfma_f32_16x16x32_bf16 v[96:99], v[136:139], v[186:189], 0
	v_mfma_f32_16x16x32_bf16 v[84:87], v[128:131], v[194:197], 0
	v_mfma_f32_16x16x32_bf16 v[80:83], v[136:139], v[194:197], 0
	v_mfma_f32_16x16x32_bf16 v[92:95], v[128:131], v[202:205], 0
	v_mfma_f32_16x16x32_bf16 v[88:91], v[136:139], v[202:205], 0
	v_mfma_f32_16x16x32_bf16 v[108:111], v[128:131], v[210:213], 0
	v_mfma_f32_16x16x32_bf16 v[100:103], v[136:139], v[210:213], 0
	v_mfma_f32_16x16x32_bf16 v[104:107], v[132:135], v[190:193], v[104:107]
	v_mfma_f32_16x16x32_bf16 v[96:99], v[140:143], v[190:193], v[96:99]
	v_mfma_f32_16x16x32_bf16 v[84:87], v[132:135], v[198:201], v[84:87]
	v_mfma_f32_16x16x32_bf16 v[80:83], v[140:143], v[198:201], v[80:83]
	v_mfma_f32_16x16x32_bf16 v[92:95], v[132:135], v[206:209], v[92:95]
	v_mfma_f32_16x16x32_bf16 v[88:91], v[140:143], v[206:209], v[88:91]
	v_mfma_f32_16x16x32_bf16 v[108:111], v[132:135], v[214:217], v[108:111]
	v_mfma_f32_16x16x32_bf16 v[100:103], v[140:143], v[214:217], v[100:103]
	v_mfma_f32_16x16x32_bf16 v[28:31], v[144:147], v[186:189], 0
	v_mfma_f32_16x16x32_bf16 v[16:19], v[152:155], v[186:189], 0
	v_mfma_f32_16x16x32_bf16 v[4:7], v[144:147], v[194:197], 0
	v_mfma_f32_16x16x32_bf16 v[0:3], v[152:155], v[194:197], 0
	v_mfma_f32_16x16x32_bf16 v[12:15], v[144:147], v[202:205], 0
	v_mfma_f32_16x16x32_bf16 v[8:11], v[152:155], v[202:205], 0
	v_mfma_f32_16x16x32_bf16 v[24:27], v[144:147], v[210:213], 0
	v_mfma_f32_16x16x32_bf16 v[20:23], v[152:155], v[210:213], 0
	v_mfma_f32_16x16x32_bf16 v[28:31], v[148:151], v[190:193], v[28:31]
	v_mfma_f32_16x16x32_bf16 v[16:19], v[156:159], v[190:193], v[16:19]
	v_mfma_f32_16x16x32_bf16 v[4:7], v[148:151], v[198:201], v[4:7]
	v_mfma_f32_16x16x32_bf16 v[0:3], v[156:159], v[198:201], v[0:3]
	v_mfma_f32_16x16x32_bf16 v[12:15], v[148:151], v[206:209], v[12:15]
	v_mfma_f32_16x16x32_bf16 v[8:11], v[156:159], v[206:209], v[8:11]
	v_mfma_f32_16x16x32_bf16 v[24:27], v[148:151], v[214:217], v[24:27]
	v_mfma_f32_16x16x32_bf16 v[20:23], v[156:159], v[214:217], v[20:23]
	s_barrier
	s_setprio 0
	s_add_i32 s43, s57, s5
	s_mov_b32 m0, s43
	ds_read_b128 v[186:189], v182 offset:16384
	ds_read_b128 v[190:193], v182 offset:17408
	ds_read_b128 v[194:197], v182 offset:18432
	ds_read_b128 v[198:201], v182 offset:19456
	ds_read_b128 v[202:205], v182 offset:20480
	ds_read_b128 v[206:209], v182 offset:21504
	ds_read_b128 v[210:213], v182 offset:22528
	ds_read_b128 v[214:217], v182 offset:23552
	global_load_lds_dwordx4 v162, s[8:9]
	s_add_i32 m0, s43, 0x2000
	s_add_u32 s44, s8, 0x4000
	s_addc_u32 s45, s9, 0
	s_add_i32 s43, s81, s5
	global_load_lds_dwordx4 v166, s[8:9]
	s_mov_b32 m0, s43
	s_nop 0
	global_load_lds_dwordx4 v162, s[44:45]
	s_add_i32 m0, s43, 0x2000
	s_nop 0
	global_load_lds_dwordx4 v166, s[44:45]
	s_mov_b32 m0, s33
	s_nop 0
	global_load_lds_dwordx4 v160, s[36:37]
	s_mov_b32 m0, s46
	s_nop 0
	global_load_lds_dwordx4 v164, s[36:37]
	s_waitcnt vmcnt(8)
	s_waitcnt lgkmcnt(0)
	s_setprio 1
	s_barrier
	v_mfma_f32_16x16x32_bf16 v[116:119], v[128:131], v[186:189], 0
	v_mfma_f32_16x16x32_bf16 v[112:115], v[136:139], v[186:189], 0
	v_mfma_f32_16x16x32_bf16 v[124:127], v[128:131], v[194:197], 0
	v_mfma_f32_16x16x32_bf16 v[120:123], v[136:139], v[194:197], 0
	v_mfma_f32_16x16x32_bf16 v[76:79], v[128:131], v[202:205], 0
	v_mfma_f32_16x16x32_bf16 v[72:75], v[136:139], v[202:205], 0
	v_mfma_f32_16x16x32_bf16 v[68:71], v[128:131], v[210:213], 0
	v_mfma_f32_16x16x32_bf16 v[64:67], v[136:139], v[210:213], 0
	v_mfma_f32_16x16x32_bf16 v[116:119], v[132:135], v[190:193], v[116:119]
	v_mfma_f32_16x16x32_bf16 v[112:115], v[140:143], v[190:193], v[112:115]
	v_mfma_f32_16x16x32_bf16 v[124:127], v[132:135], v[198:201], v[124:127]
	v_mfma_f32_16x16x32_bf16 v[120:123], v[140:143], v[198:201], v[120:123]
	v_mfma_f32_16x16x32_bf16 v[76:79], v[132:135], v[206:209], v[76:79]
	v_mfma_f32_16x16x32_bf16 v[72:75], v[140:143], v[206:209], v[72:75]
	v_mfma_f32_16x16x32_bf16 v[68:71], v[132:135], v[214:217], v[68:71]
	v_mfma_f32_16x16x32_bf16 v[64:67], v[140:143], v[214:217], v[64:67]
	v_mfma_f32_16x16x32_bf16 v[36:39], v[144:147], v[186:189], 0
	v_mfma_f32_16x16x32_bf16 v[32:35], v[152:155], v[186:189], 0
	v_mfma_f32_16x16x32_bf16 v[44:47], v[144:147], v[194:197], 0
	v_mfma_f32_16x16x32_bf16 v[40:43], v[152:155], v[194:197], 0
	v_mfma_f32_16x16x32_bf16 v[52:55], v[144:147], v[202:205], 0
	v_mfma_f32_16x16x32_bf16 v[48:51], v[152:155], v[202:205], 0
	v_mfma_f32_16x16x32_bf16 v[60:63], v[144:147], v[210:213], 0
	v_mfma_f32_16x16x32_bf16 v[56:59], v[152:155], v[210:213], 0
	v_mfma_f32_16x16x32_bf16 v[36:39], v[148:151], v[190:193], v[36:39]
	v_mfma_f32_16x16x32_bf16 v[32:35], v[156:159], v[190:193], v[32:35]
	v_mfma_f32_16x16x32_bf16 v[44:47], v[148:151], v[198:201], v[44:47]
	v_mfma_f32_16x16x32_bf16 v[40:43], v[156:159], v[198:201], v[40:43]
	v_mfma_f32_16x16x32_bf16 v[52:55], v[148:151], v[206:209], v[52:55]
	v_mfma_f32_16x16x32_bf16 v[48:51], v[156:159], v[206:209], v[48:51]
	v_mfma_f32_16x16x32_bf16 v[60:63], v[148:151], v[214:217], v[60:63]
	v_mfma_f32_16x16x32_bf16 v[56:59], v[156:159], v[214:217], v[56:59]
	s_barrier
	s_setprio 0
	s_branch .Lzmid12

.Lzmid12:
	v_add_u32_e32 v140, s82, v179
	v_add_u32_e32 v156, s83, v179
	ds_read_b128 v[128:131], v140
	ds_read_b128 v[132:135], v140 offset:1024
	ds_read_b128 v[136:139], v140 offset:2048
	ds_read_b128 v[140:143], v140 offset:3072
	ds_read_b128 v[144:147], v156
	ds_read_b128 v[148:151], v156 offset:1024
	ds_read_b128 v[152:155], v156 offset:2048
	ds_read_b128 v[156:159], v156 offset:3072
	s_add_u32 s36, s36, 0x4000
	s_addc_u32 s37, s37, 0
	s_mov_b32 m0, s47
	ds_read_b128 v[186:189], v182 offset:32768
	ds_read_b128 v[190:193], v182 offset:33792
	ds_read_b128 v[194:197], v182 offset:34816
	ds_read_b128 v[198:201], v182 offset:35840
	ds_read_b128 v[202:205], v182 offset:36864
	ds_read_b128 v[206:209], v182 offset:37888
	ds_read_b128 v[210:213], v182 offset:38912
	ds_read_b128 v[214:217], v182 offset:39936
	global_load_lds_dwordx4 v160, s[36:37]
	s_mov_b32 m0, s50
	s_nop 0
	global_load_lds_dwordx4 v164, s[36:37]
	s_waitcnt vmcnt(8)
	s_waitcnt lgkmcnt(0)
	s_setprio 1
	s_barrier
	v_mfma_f32_16x16x32_bf16 v[104:107], v[128:131], v[186:189], v[104:107]
	v_mfma_f32_16x16x32_bf16 v[96:99], v[136:139], v[186:189], v[96:99]
	v_mfma_f32_16x16x32_bf16 v[84:87], v[128:131], v[194:197], v[84:87]
	v_mfma_f32_16x16x32_bf16 v[80:83], v[136:139], v[194:197], v[80:83]
	v_mfma_f32_16x16x32_bf16 v[92:95], v[128:131], v[202:205], v[92:95]
	v_mfma_f32_16x16x32_bf16 v[88:91], v[136:139], v[202:205], v[88:91]
	v_mfma_f32_16x16x32_bf16 v[108:111], v[128:131], v[210:213], v[108:111]
	v_mfma_f32_16x16x32_bf16 v[100:103], v[136:139], v[210:213], v[100:103]
	v_mfma_f32_16x16x32_bf16 v[104:107], v[132:135], v[190:193], v[104:107]
	v_mfma_f32_16x16x32_bf16 v[96:99], v[140:143], v[190:193], v[96:99]
	v_mfma_f32_16x16x32_bf16 v[84:87], v[132:135], v[198:201], v[84:87]
	v_mfma_f32_16x16x32_bf16 v[80:83], v[140:143], v[198:201], v[80:83]
	v_mfma_f32_16x16x32_bf16 v[92:95], v[132:135], v[206:209], v[92:95]
	v_mfma_f32_16x16x32_bf16 v[88:91], v[140:143], v[206:209], v[88:91]
	v_mfma_f32_16x16x32_bf16 v[108:111], v[132:135], v[214:217], v[108:111]
	v_mfma_f32_16x16x32_bf16 v[100:103], v[140:143], v[214:217], v[100:103]
	v_mfma_f32_16x16x32_bf16 v[28:31], v[144:147], v[186:189], v[28:31]
	v_mfma_f32_16x16x32_bf16 v[16:19], v[152:155], v[186:189], v[16:19]
	v_mfma_f32_16x16x32_bf16 v[4:7], v[144:147], v[194:197], v[4:7]
	v_mfma_f32_16x16x32_bf16 v[0:3], v[152:155], v[194:197], v[0:3]
	v_mfma_f32_16x16x32_bf16 v[12:15], v[144:147], v[202:205], v[12:15]
	v_mfma_f32_16x16x32_bf16 v[8:11], v[152:155], v[202:205], v[8:11]
	v_mfma_f32_16x16x32_bf16 v[24:27], v[144:147], v[210:213], v[24:27]
	v_mfma_f32_16x16x32_bf16 v[20:23], v[152:155], v[210:213], v[20:23]
	v_mfma_f32_16x16x32_bf16 v[28:31], v[148:151], v[190:193], v[28:31]
	v_mfma_f32_16x16x32_bf16 v[16:19], v[156:159], v[190:193], v[16:19]
	v_mfma_f32_16x16x32_bf16 v[4:7], v[148:151], v[198:201], v[4:7]
	v_mfma_f32_16x16x32_bf16 v[0:3], v[156:159], v[198:201], v[0:3]
	v_mfma_f32_16x16x32_bf16 v[12:15], v[148:151], v[206:209], v[12:15]
	v_mfma_f32_16x16x32_bf16 v[8:11], v[156:159], v[206:209], v[8:11]
	v_mfma_f32_16x16x32_bf16 v[24:27], v[148:151], v[214:217], v[24:27]
	v_mfma_f32_16x16x32_bf16 v[20:23], v[156:159], v[214:217], v[20:23]
	s_barrier
	s_setprio 0
	s_add_u32 s36, s8, 0x40000
	s_addc_u32 s37, s9, 0
	s_add_i32 s43, s82, s5
	s_mov_b32 m0, s43
	ds_read_b128 v[186:189], v182 offset:49152
	ds_read_b128 v[190:193], v182 offset:50176
	ds_read_b128 v[194:197], v182 offset:51200
	ds_read_b128 v[198:201], v182 offset:52224
	ds_read_b128 v[202:205], v182 offset:53248
	ds_read_b128 v[206:209], v182 offset:54272
	ds_read_b128 v[210:213], v182 offset:55296
	ds_read_b128 v[214:217], v182 offset:56320
	global_load_lds_dwordx4 v162, s[36:37]
	s_add_i32 m0, s43, 0x2000
	s_add_u32 s8, s8, 0x44000
	global_load_lds_dwordx4 v166, s[36:37]
	s_addc_u32 s9, s9, 0
	s_add_i32 s36, s83, s5
	s_mov_b32 m0, s36
	s_nop 0
	global_load_lds_dwordx4 v162, s[8:9]
	s_add_i32 m0, s36, 0x2000
	s_nop 0
	global_load_lds_dwordx4 v166, s[8:9]
	s_mov_b32 m0, s55
	s_nop 0
	global_load_lds_dwordx4 v160, s[6:7]
	s_mov_b32 m0, s56
	s_nop 0
	global_load_lds_dwordx4 v164, s[6:7]
	s_waitcnt vmcnt(8)
	s_waitcnt lgkmcnt(0)
	s_setprio 1
	s_barrier
	v_mfma_f32_16x16x32_bf16 v[116:119], v[128:131], v[186:189], v[116:119]
	v_mfma_f32_16x16x32_bf16 v[112:115], v[136:139], v[186:189], v[112:115]
	v_mfma_f32_16x16x32_bf16 v[124:127], v[128:131], v[194:197], v[124:127]
	v_mfma_f32_16x16x32_bf16 v[120:123], v[136:139], v[194:197], v[120:123]
	v_mfma_f32_16x16x32_bf16 v[76:79], v[128:131], v[202:205], v[76:79]
	v_mfma_f32_16x16x32_bf16 v[72:75], v[136:139], v[202:205], v[72:75]
	v_mfma_f32_16x16x32_bf16 v[68:71], v[128:131], v[210:213], v[68:71]
	v_mfma_f32_16x16x32_bf16 v[64:67], v[136:139], v[210:213], v[64:67]
	v_mfma_f32_16x16x32_bf16 v[116:119], v[132:135], v[190:193], v[116:119]
	v_mfma_f32_16x16x32_bf16 v[112:115], v[140:143], v[190:193], v[112:115]
	v_mfma_f32_16x16x32_bf16 v[124:127], v[132:135], v[198:201], v[124:127]
	v_mfma_f32_16x16x32_bf16 v[120:123], v[140:143], v[198:201], v[120:123]
	v_mfma_f32_16x16x32_bf16 v[76:79], v[132:135], v[206:209], v[76:79]
	v_mfma_f32_16x16x32_bf16 v[72:75], v[140:143], v[206:209], v[72:75]
	v_mfma_f32_16x16x32_bf16 v[68:71], v[132:135], v[214:217], v[68:71]
	v_mfma_f32_16x16x32_bf16 v[64:67], v[140:143], v[214:217], v[64:67]
	v_mfma_f32_16x16x32_bf16 v[36:39], v[144:147], v[186:189], v[36:39]
	v_mfma_f32_16x16x32_bf16 v[32:35], v[152:155], v[186:189], v[32:35]
	v_mfma_f32_16x16x32_bf16 v[44:47], v[144:147], v[194:197], v[44:47]
	v_mfma_f32_16x16x32_bf16 v[40:43], v[152:155], v[194:197], v[40:43]
	v_mfma_f32_16x16x32_bf16 v[52:55], v[144:147], v[202:205], v[52:55]
	v_mfma_f32_16x16x32_bf16 v[48:51], v[152:155], v[202:205], v[48:51]
	v_mfma_f32_16x16x32_bf16 v[60:63], v[144:147], v[210:213], v[60:63]
	v_mfma_f32_16x16x32_bf16 v[56:59], v[152:155], v[210:213], v[56:59]
	v_mfma_f32_16x16x32_bf16 v[36:39], v[148:151], v[190:193], v[36:39]
	v_mfma_f32_16x16x32_bf16 v[32:35], v[156:159], v[190:193], v[32:35]
	v_mfma_f32_16x16x32_bf16 v[44:47], v[148:151], v[198:201], v[44:47]
	v_mfma_f32_16x16x32_bf16 v[40:43], v[156:159], v[198:201], v[40:43]
	v_mfma_f32_16x16x32_bf16 v[52:55], v[148:151], v[206:209], v[52:55]
	v_mfma_f32_16x16x32_bf16 v[48:51], v[156:159], v[206:209], v[48:51]
	v_mfma_f32_16x16x32_bf16 v[60:63], v[148:151], v[214:217], v[60:63]
	v_mfma_f32_16x16x32_bf16 v[56:59], v[156:159], v[214:217], v[56:59]
	s_barrier
	s_setprio 0
	s_add_i32 s42, s42, 2
	s_add_u32 s40, s40, 0x80000
	s_addc_u32 s41, s41, 0
	s_add_u32 s0, s0, 0x800000
	s_addc_u32 s1, s1, 0
	s_cmp_gt_u32 s42, 29
	s_cbranch_scc0 .LBB0_2542
	s_and_b64 vcc, exec, s[24:25]
	s_cbranch_vccz .LBB0_2545
	s_barrier

.LBB0_2663:
	s_mov_b32 s15, s7
	s_lshl_b64 s[18:19], s[14:15], 1
	s_add_u32 s18, s58, s18
	s_addc_u32 s19, s59, s19
	s_and_b64 s[20:21], s[0:1], exec
	s_mov_b32 s17, s7
	s_cselect_b32 s6, s19, s25
	s_cselect_b32 s15, s18, s24
	s_lshl_b64 s[20:21], s[16:17], 1
	s_add_u32 s20, s79, s20
	v_readlane_b32 s17, v250, 4
	s_addc_u32 s21, s17, s21
	s_and_b64 s[26:27], s[0:1], exec
	s_cselect_b32 s17, s21, s23
	s_cselect_b32 s54, s20, s22
	s_add_u32 s55, s22, 0x100
	s_addc_u32 s56, s23, 0
	s_add_u32 s22, s24, 0x404000
	s_addc_u32 s23, s25, 0
	s_mov_b32 s64, -2
	ds_read_b128 v[152:155], v149
	ds_read_b128 v[156:159], v149 offset:1024
	ds_read_b128 v[160:163], v149 offset:2048
	ds_read_b128 v[164:167], v149 offset:3072
	ds_read_b128 v[168:171], v150
	ds_read_b128 v[172:175], v150 offset:1024
	ds_read_b128 v[176:179], v150 offset:2048
	ds_read_b128 v[180:183], v150 offset:3072
	s_add_u32 s24, s22, 0x3fc000
	s_addc_u32 s25, s23, 0
	s_cmp_eq_u32 s64, 28
	s_cselect_b32 s28, s15, s24
	s_cselect_b32 s29, s6, s25
	s_cselect_b32 s26, s54, s55
	s_cselect_b32 s27, s17, s56
	s_add_u32 s24, s28, 0x400000
	s_addc_u32 s25, s29, 0
	s_add_i32 m0, s30, 0xc000
	ds_read_b128 v[184:187], v151
	ds_read_b128 v[188:191], v151 offset:1024
	ds_read_b128 v[192:195], v151 offset:2048
	ds_read_b128 v[196:199], v151 offset:3072
	ds_read_b128 v[200:203], v151 offset:4096
	ds_read_b128 v[204:207], v151 offset:5120
	ds_read_b128 v[208:211], v151 offset:6144
	ds_read_b128 v[212:215], v151 offset:7168
	global_load_lds_dwordx4 v136, s[22:23]
	s_add_i32 m0, s30, 0xe000
	s_nop 0
	global_load_lds_dwordx4 v138, s[22:23]
	s_waitcnt vmcnt(8)
	s_waitcnt lgkmcnt(0)
	s_setprio 1
	s_barrier
	v_mfma_f32_16x16x32_bf16 v[124:127], v[152:155], v[184:187], 0
	v_mfma_f32_16x16x32_bf16 v[120:123], v[160:163], v[184:187], 0
	v_mfma_f32_16x16x32_bf16 v[108:111], v[152:155], v[192:195], 0
	v_mfma_f32_16x16x32_bf16 v[104:107], v[160:163], v[192:195], 0
	v_mfma_f32_16x16x32_bf16 v[92:95], v[152:155], v[200:203], 0
	v_mfma_f32_16x16x32_bf16 v[88:91], v[160:163], v[200:203], 0
	v_mfma_f32_16x16x32_bf16 v[76:79], v[152:155], v[208:211], 0
	v_mfma_f32_16x16x32_bf16 v[72:75], v[160:163], v[208:211], 0
	v_mfma_f32_16x16x32_bf16 v[124:127], v[156:159], v[188:191], v[124:127]
	v_mfma_f32_16x16x32_bf16 v[120:123], v[164:167], v[188:191], v[120:123]
	v_mfma_f32_16x16x32_bf16 v[108:111], v[156:159], v[196:199], v[108:111]
	v_mfma_f32_16x16x32_bf16 v[104:107], v[164:167], v[196:199], v[104:107]
	v_mfma_f32_16x16x32_bf16 v[92:95], v[156:159], v[204:207], v[92:95]
	v_mfma_f32_16x16x32_bf16 v[88:91], v[164:167], v[204:207], v[88:91]
	v_mfma_f32_16x16x32_bf16 v[76:79], v[156:159], v[212:215], v[76:79]
	v_mfma_f32_16x16x32_bf16 v[72:75], v[164:167], v[212:215], v[72:75]
	v_mfma_f32_16x16x32_bf16 v[116:119], v[168:171], v[184:187], 0
	v_mfma_f32_16x16x32_bf16 v[112:115], v[176:179], v[184:187], 0
	v_mfma_f32_16x16x32_bf16 v[100:103], v[168:171], v[192:195], 0
	v_mfma_f32_16x16x32_bf16 v[96:99], v[176:179], v[192:195], 0
	v_mfma_f32_16x16x32_bf16 v[84:87], v[168:171], v[200:203], 0
	v_mfma_f32_16x16x32_bf16 v[80:83], v[176:179], v[200:203], 0
	v_mfma_f32_16x16x32_bf16 v[68:71], v[168:171], v[208:211], 0
	v_mfma_f32_16x16x32_bf16 v[64:67], v[176:179], v[208:211], 0
	v_mfma_f32_16x16x32_bf16 v[116:119], v[172:175], v[188:191], v[116:119]
	v_mfma_f32_16x16x32_bf16 v[112:115], v[180:183], v[188:191], v[112:115]
	v_mfma_f32_16x16x32_bf16 v[100:103], v[172:175], v[196:199], v[100:103]
	v_mfma_f32_16x16x32_bf16 v[96:99], v[180:183], v[196:199], v[96:99]
	v_mfma_f32_16x16x32_bf16 v[84:87], v[172:175], v[204:207], v[84:87]
	v_mfma_f32_16x16x32_bf16 v[80:83], v[180:183], v[204:207], v[80:83]
	v_mfma_f32_16x16x32_bf16 v[68:71], v[172:175], v[212:215], v[68:71]
	v_mfma_f32_16x16x32_bf16 v[64:67], v[180:183], v[212:215], v[64:67]
	s_barrier
	s_setprio 0
	s_add_i32 s65, s57, s5
	v_lshl_add_u64 v[144:145], s[26:27], 0, v[130:131]
	s_mov_b32 m0, s65
	ds_read_b128 v[184:187], v151 offset:16384
	ds_read_b128 v[188:191], v151 offset:17408
	ds_read_b128 v[192:195], v151 offset:18432
	ds_read_b128 v[196:199], v151 offset:19456
	ds_read_b128 v[200:203], v151 offset:20480
	ds_read_b128 v[204:207], v151 offset:21504
	ds_read_b128 v[208:211], v151 offset:22528
	ds_read_b128 v[212:215], v151 offset:23552
	global_load_lds_dwordx4 v[144:145], off
	s_add_i32 m0, s65, 0x2000
	s_add_u32 s66, s26, 0x80000
	v_lshl_add_u64 v[216:217], s[26:27], 0, v[134:135]
	s_addc_u32 s67, s27, 0
	s_add_i32 s65, s81, s5
	global_load_lds_dwordx4 v[216:217], off
	s_mov_b32 m0, s65
	s_nop 0
	global_load_lds_dwordx4 v130, s[66:67]
	s_add_i32 m0, s65, 0x2000
	s_nop 0
	global_load_lds_dwordx4 v134, s[66:67]
	s_mov_b32 m0, s30
	s_nop 0
	global_load_lds_dwordx4 v128, s[28:29]
	s_mov_b32 m0, s31
	s_nop 0
	global_load_lds_dwordx4 v132, s[28:29]
	s_waitcnt vmcnt(8)
	s_waitcnt lgkmcnt(0)
	s_setprio 1
	s_barrier
	v_mfma_f32_16x16x32_bf16 v[60:63], v[152:155], v[184:187], 0
	v_mfma_f32_16x16x32_bf16 v[56:59], v[160:163], v[184:187], 0
	v_mfma_f32_16x16x32_bf16 v[44:47], v[152:155], v[192:195], 0
	v_mfma_f32_16x16x32_bf16 v[40:43], v[160:163], v[192:195], 0
	v_mfma_f32_16x16x32_bf16 v[28:31], v[152:155], v[200:203], 0
	v_mfma_f32_16x16x32_bf16 v[24:27], v[160:163], v[200:203], 0
	v_mfma_f32_16x16x32_bf16 v[12:15], v[152:155], v[208:211], 0
	v_mfma_f32_16x16x32_bf16 v[8:11], v[160:163], v[208:211], 0
	v_mfma_f32_16x16x32_bf16 v[60:63], v[156:159], v[188:191], v[60:63]
	v_mfma_f32_16x16x32_bf16 v[56:59], v[164:167], v[188:191], v[56:59]
	v_mfma_f32_16x16x32_bf16 v[44:47], v[156:159], v[196:199], v[44:47]
	v_mfma_f32_16x16x32_bf16 v[40:43], v[164:167], v[196:199], v[40:43]
	v_mfma_f32_16x16x32_bf16 v[28:31], v[156:159], v[204:207], v[28:31]
	v_mfma_f32_16x16x32_bf16 v[24:27], v[164:167], v[204:207], v[24:27]
	v_mfma_f32_16x16x32_bf16 v[12:15], v[156:159], v[212:215], v[12:15]
	v_mfma_f32_16x16x32_bf16 v[8:11], v[164:167], v[212:215], v[8:11]
	v_mfma_f32_16x16x32_bf16 v[52:55], v[168:171], v[184:187], 0
	v_mfma_f32_16x16x32_bf16 v[48:51], v[176:179], v[184:187], 0
	v_mfma_f32_16x16x32_bf16 v[36:39], v[168:171], v[192:195], 0
	v_mfma_f32_16x16x32_bf16 v[32:35], v[176:179], v[192:195], 0
	v_mfma_f32_16x16x32_bf16 v[20:23], v[168:171], v[200:203], 0
	v_mfma_f32_16x16x32_bf16 v[16:19], v[176:179], v[200:203], 0
	v_mfma_f32_16x16x32_bf16 v[4:7], v[168:171], v[208:211], 0
	v_mfma_f32_16x16x32_bf16 v[0:3], v[176:179], v[208:211], 0
	v_mfma_f32_16x16x32_bf16 v[52:55], v[172:175], v[188:191], v[52:55]
	v_mfma_f32_16x16x32_bf16 v[48:51], v[180:183], v[188:191], v[48:51]
	v_mfma_f32_16x16x32_bf16 v[36:39], v[172:175], v[196:199], v[36:39]
	v_mfma_f32_16x16x32_bf16 v[32:35], v[180:183], v[196:199], v[32:35]
	v_mfma_f32_16x16x32_bf16 v[20:23], v[172:175], v[204:207], v[20:23]
	v_mfma_f32_16x16x32_bf16 v[16:19], v[180:183], v[204:207], v[16:19]
	v_mfma_f32_16x16x32_bf16 v[4:7], v[172:175], v[212:215], v[4:7]
	v_mfma_f32_16x16x32_bf16 v[0:3], v[180:183], v[212:215], v[0:3]
	s_barrier
	s_setprio 0
	s_branch .Lzmid13

.Lzmid13:
	v_add_u32_e32 v164, s82, v148
	v_add_u32_e32 v180, s83, v148
	ds_read_b128 v[152:155], v164
	ds_read_b128 v[156:159], v164 offset:1024
	ds_read_b128 v[160:163], v164 offset:2048
	ds_read_b128 v[164:167], v164 offset:3072
	ds_read_b128 v[168:171], v180
	ds_read_b128 v[172:175], v180 offset:1024
	ds_read_b128 v[176:179], v180 offset:2048
	ds_read_b128 v[180:183], v180 offset:3072
	s_add_u32 s28, s28, 0x4000
	s_addc_u32 s29, s29, 0
	s_mov_b32 m0, s33
	ds_read_b128 v[184:187], v151 offset:32768
	ds_read_b128 v[188:191], v151 offset:33792
	ds_read_b128 v[192:195], v151 offset:34816
	ds_read_b128 v[196:199], v151 offset:35840
	ds_read_b128 v[200:203], v151 offset:36864
	ds_read_b128 v[204:207], v151 offset:37888
	ds_read_b128 v[208:211], v151 offset:38912
	ds_read_b128 v[212:215], v151 offset:39936
	global_load_lds_dwordx4 v128, s[28:29]
	v_lshl_add_u64 v[218:219], s[28:29], 0, v[132:133]
	s_mov_b32 m0, s34
	s_nop 0
	global_load_lds_dwordx4 v[218:219], off
	s_waitcnt vmcnt(8)
	s_waitcnt lgkmcnt(0)
	s_setprio 1
	s_barrier
	v_mfma_f32_16x16x32_bf16 v[124:127], v[152:155], v[184:187], v[124:127]
	v_mfma_f32_16x16x32_bf16 v[120:123], v[160:163], v[184:187], v[120:123]
	v_mfma_f32_16x16x32_bf16 v[108:111], v[152:155], v[192:195], v[108:111]
	v_mfma_f32_16x16x32_bf16 v[104:107], v[160:163], v[192:195], v[104:107]
	v_mfma_f32_16x16x32_bf16 v[92:95], v[152:155], v[200:203], v[92:95]
	v_mfma_f32_16x16x32_bf16 v[88:91], v[160:163], v[200:203], v[88:91]
	v_mfma_f32_16x16x32_bf16 v[76:79], v[152:155], v[208:211], v[76:79]
	v_mfma_f32_16x16x32_bf16 v[72:75], v[160:163], v[208:211], v[72:75]
	v_mfma_f32_16x16x32_bf16 v[124:127], v[156:159], v[188:191], v[124:127]
	v_mfma_f32_16x16x32_bf16 v[120:123], v[164:167], v[188:191], v[120:123]
	v_mfma_f32_16x16x32_bf16 v[108:111], v[156:159], v[196:199], v[108:111]
	v_mfma_f32_16x16x32_bf16 v[104:107], v[164:167], v[196:199], v[104:107]
	v_mfma_f32_16x16x32_bf16 v[92:95], v[156:159], v[204:207], v[92:95]
	v_mfma_f32_16x16x32_bf16 v[88:91], v[164:167], v[204:207], v[88:91]
	v_mfma_f32_16x16x32_bf16 v[76:79], v[156:159], v[212:215], v[76:79]
	v_mfma_f32_16x16x32_bf16 v[72:75], v[164:167], v[212:215], v[72:75]
	v_mfma_f32_16x16x32_bf16 v[116:119], v[168:171], v[184:187], v[116:119]
	v_mfma_f32_16x16x32_bf16 v[112:115], v[176:179], v[184:187], v[112:115]
	v_mfma_f32_16x16x32_bf16 v[100:103], v[168:171], v[192:195], v[100:103]
	v_mfma_f32_16x16x32_bf16 v[96:99], v[176:179], v[192:195], v[96:99]
	v_mfma_f32_16x16x32_bf16 v[84:87], v[168:171], v[200:203], v[84:87]
	v_mfma_f32_16x16x32_bf16 v[80:83], v[176:179], v[200:203], v[80:83]
	v_mfma_f32_16x16x32_bf16 v[68:71], v[168:171], v[208:211], v[68:71]
	v_mfma_f32_16x16x32_bf16 v[64:67], v[176:179], v[208:211], v[64:67]
	v_mfma_f32_16x16x32_bf16 v[116:119], v[172:175], v[188:191], v[116:119]
	v_mfma_f32_16x16x32_bf16 v[112:115], v[180:183], v[188:191], v[112:115]
	v_mfma_f32_16x16x32_bf16 v[100:103], v[172:175], v[196:199], v[100:103]
	v_mfma_f32_16x16x32_bf16 v[96:99], v[180:183], v[196:199], v[96:99]
	v_mfma_f32_16x16x32_bf16 v[84:87], v[172:175], v[204:207], v[84:87]
	v_mfma_f32_16x16x32_bf16 v[80:83], v[180:183], v[204:207], v[80:83]
	v_mfma_f32_16x16x32_bf16 v[68:71], v[172:175], v[212:215], v[68:71]
	v_mfma_f32_16x16x32_bf16 v[64:67], v[180:183], v[212:215], v[64:67]
	s_barrier
	s_setprio 0
	s_add_i32 s28, s82, s5
	v_lshl_add_u64 v[144:145], v[144:145], 0, s[10:11]
	s_mov_b32 m0, s28
	ds_read_b128 v[184:187], v151 offset:49152
	ds_read_b128 v[188:191], v151 offset:50176
	ds_read_b128 v[192:195], v151 offset:51200
	ds_read_b128 v[196:199], v151 offset:52224
	ds_read_b128 v[200:203], v151 offset:53248
	ds_read_b128 v[204:207], v151 offset:54272
	ds_read_b128 v[208:211], v151 offset:55296
	ds_read_b128 v[212:215], v151 offset:56320
	global_load_lds_dwordx4 v[144:145], off
	s_add_i32 m0, s28, 0x2000
	s_add_u32 s26, s26, 0x80080
	v_lshl_add_u64 v[144:145], v[216:217], 0, s[10:11]
	s_addc_u32 s27, s27, 0
	s_add_i32 s28, s83, s5
	global_load_lds_dwordx4 v[144:145], off
	s_mov_b32 m0, s28
	s_nop 0
	global_load_lds_dwordx4 v130, s[26:27]
	s_add_i32 m0, s28, 0x2000
	s_nop 0
	global_load_lds_dwordx4 v134, s[26:27]
	s_mov_b32 m0, s37
	s_nop 0
	global_load_lds_dwordx4 v128, s[24:25]
	s_mov_b32 m0, s38
	s_nop 0
	global_load_lds_dwordx4 v132, s[24:25]
	s_waitcnt vmcnt(8)
	s_waitcnt lgkmcnt(0)
	s_setprio 1
	s_barrier
	v_mfma_f32_16x16x32_bf16 v[60:63], v[152:155], v[184:187], v[60:63]
	v_mfma_f32_16x16x32_bf16 v[56:59], v[160:163], v[184:187], v[56:59]
	v_mfma_f32_16x16x32_bf16 v[44:47], v[152:155], v[192:195], v[44:47]
	v_mfma_f32_16x16x32_bf16 v[40:43], v[160:163], v[192:195], v[40:43]
	v_mfma_f32_16x16x32_bf16 v[28:31], v[152:155], v[200:203], v[28:31]
	v_mfma_f32_16x16x32_bf16 v[24:27], v[160:163], v[200:203], v[24:27]
	v_mfma_f32_16x16x32_bf16 v[12:15], v[152:155], v[208:211], v[12:15]
	v_mfma_f32_16x16x32_bf16 v[8:11], v[160:163], v[208:211], v[8:11]
	v_mfma_f32_16x16x32_bf16 v[60:63], v[156:159], v[188:191], v[60:63]
	v_mfma_f32_16x16x32_bf16 v[56:59], v[164:167], v[188:191], v[56:59]
	v_mfma_f32_16x16x32_bf16 v[44:47], v[156:159], v[196:199], v[44:47]
	v_mfma_f32_16x16x32_bf16 v[40:43], v[164:167], v[196:199], v[40:43]
	v_mfma_f32_16x16x32_bf16 v[28:31], v[156:159], v[204:207], v[28:31]
	v_mfma_f32_16x16x32_bf16 v[24:27], v[164:167], v[204:207], v[24:27]
	v_mfma_f32_16x16x32_bf16 v[12:15], v[156:159], v[212:215], v[12:15]
	v_mfma_f32_16x16x32_bf16 v[8:11], v[164:167], v[212:215], v[8:11]
	v_mfma_f32_16x16x32_bf16 v[52:55], v[168:171], v[184:187], v[52:55]
	v_mfma_f32_16x16x32_bf16 v[48:51], v[176:179], v[184:187], v[48:51]
	v_mfma_f32_16x16x32_bf16 v[36:39], v[168:171], v[192:195], v[36:39]
	v_mfma_f32_16x16x32_bf16 v[32:35], v[176:179], v[192:195], v[32:35]
	v_mfma_f32_16x16x32_bf16 v[20:23], v[168:171], v[200:203], v[20:23]
	v_mfma_f32_16x16x32_bf16 v[16:19], v[176:179], v[200:203], v[16:19]
	v_mfma_f32_16x16x32_bf16 v[4:7], v[168:171], v[208:211], v[4:7]
	v_mfma_f32_16x16x32_bf16 v[0:3], v[176:179], v[208:211], v[0:3]
	v_mfma_f32_16x16x32_bf16 v[52:55], v[172:175], v[188:191], v[52:55]
	v_mfma_f32_16x16x32_bf16 v[48:51], v[180:183], v[188:191], v[48:51]
	v_mfma_f32_16x16x32_bf16 v[36:39], v[172:175], v[196:199], v[36:39]
	v_mfma_f32_16x16x32_bf16 v[32:35], v[180:183], v[196:199], v[32:35]
	v_mfma_f32_16x16x32_bf16 v[20:23], v[172:175], v[204:207], v[20:23]
	v_mfma_f32_16x16x32_bf16 v[16:19], v[180:183], v[204:207], v[16:19]
	v_mfma_f32_16x16x32_bf16 v[4:7], v[172:175], v[212:215], v[4:7]
	v_mfma_f32_16x16x32_bf16 v[0:3], v[180:183], v[212:215], v[0:3]
	s_barrier
	s_setprio 0
	s_add_i32 s64, s64, 2
	s_add_u32 s55, s55, 0x100
	s_addc_u32 s56, s56, 0
	s_add_u32 s22, s22, 0x800000
	s_addc_u32 s23, s23, 0
	s_cmp_gt_u32 s64, 29
	s_cbranch_scc0 .LBB0_2664
	s_and_b64 vcc, exec, s[12:13]
	s_cbranch_vccz .LBB0_2667
	s_barrier

.LBB0_2771:
	s_mov_b32 s27, s11
	s_lshl_b64 s[30:31], s[26:27], 1
	s_add_u32 s30, s91, s30
	s_addc_u32 s31, s92, s31
	s_and_b64 s[34:35], s[8:9], exec
	s_mov_b32 s29, s11
	s_cselect_b32 s10, s31, s7
	s_cselect_b32 s13, s30, s6
	s_lshl_b64 s[34:35], s[28:29], 1
	s_add_u32 s34, s80, s34
	s_addc_u32 s35, s86, s35
	s_and_b64 s[8:9], s[8:9], exec
	s_cselect_b32 s27, s35, s1
	s_cselect_b32 s29, s34, s0
	s_add_u32 s39, s0, 0x100
	s_addc_u32 s40, s1, 0
	s_add_u32 s0, s6, 0x404000
	s_addc_u32 s1, s7, 0
	s_mov_b32 s41, -2
	ds_read_b128 v[128:131], v180
	ds_read_b128 v[132:135], v180 offset:1024
	ds_read_b128 v[136:139], v180 offset:2048
	ds_read_b128 v[140:143], v180 offset:3072
	ds_read_b128 v[144:147], v181
	ds_read_b128 v[148:151], v181 offset:1024
	ds_read_b128 v[152:155], v181 offset:2048
	ds_read_b128 v[156:159], v181 offset:3072
	s_add_u32 s6, s0, 0x3fc000
	s_addc_u32 s7, s1, 0
	s_cmp_eq_u32 s41, 12
	s_cselect_b32 s36, s13, s6
	s_cselect_b32 s37, s10, s7
	s_cselect_b32 s8, s29, s39
	s_cselect_b32 s9, s27, s40
	s_add_u32 s6, s36, 0x400000
	s_addc_u32 s7, s37, 0
	s_add_i32 m0, s25, 0xc000
	ds_read_b128 v[186:189], v182
	ds_read_b128 v[190:193], v182 offset:1024
	ds_read_b128 v[194:197], v182 offset:2048
	ds_read_b128 v[198:201], v182 offset:3072
	ds_read_b128 v[202:205], v182 offset:4096
	ds_read_b128 v[206:209], v182 offset:5120
	ds_read_b128 v[210:213], v182 offset:6144
	ds_read_b128 v[214:217], v182 offset:7168
	global_load_lds_dwordx4 v168, s[0:1]
	s_add_i32 m0, s25, 0xe000
	s_nop 0
	global_load_lds_dwordx4 v170, s[0:1]
	s_waitcnt vmcnt(8)
	s_waitcnt lgkmcnt(0)
	s_setprio 1
	s_barrier
	v_mfma_f32_16x16x32_bf16 v[104:107], v[128:131], v[186:189], 0
	v_mfma_f32_16x16x32_bf16 v[96:99], v[136:139], v[186:189], 0
	v_mfma_f32_16x16x32_bf16 v[84:87], v[128:131], v[194:197], 0
	v_mfma_f32_16x16x32_bf16 v[80:83], v[136:139], v[194:197], 0
	v_mfma_f32_16x16x32_bf16 v[92:95], v[128:131], v[202:205], 0
	v_mfma_f32_16x16x32_bf16 v[88:91], v[136:139], v[202:205], 0
	v_mfma_f32_16x16x32_bf16 v[108:111], v[128:131], v[210:213], 0
	v_mfma_f32_16x16x32_bf16 v[100:103], v[136:139], v[210:213], 0
	v_mfma_f32_16x16x32_bf16 v[104:107], v[132:135], v[190:193], v[104:107]
	v_mfma_f32_16x16x32_bf16 v[96:99], v[140:143], v[190:193], v[96:99]
	v_mfma_f32_16x16x32_bf16 v[84:87], v[132:135], v[198:201], v[84:87]
	v_mfma_f32_16x16x32_bf16 v[80:83], v[140:143], v[198:201], v[80:83]
	v_mfma_f32_16x16x32_bf16 v[92:95], v[132:135], v[206:209], v[92:95]
	v_mfma_f32_16x16x32_bf16 v[88:91], v[140:143], v[206:209], v[88:91]
	v_mfma_f32_16x16x32_bf16 v[108:111], v[132:135], v[214:217], v[108:111]
	v_mfma_f32_16x16x32_bf16 v[100:103], v[140:143], v[214:217], v[100:103]
	v_mfma_f32_16x16x32_bf16 v[28:31], v[144:147], v[186:189], 0
	v_mfma_f32_16x16x32_bf16 v[16:19], v[152:155], v[186:189], 0
	v_mfma_f32_16x16x32_bf16 v[4:7], v[144:147], v[194:197], 0
	v_mfma_f32_16x16x32_bf16 v[0:3], v[152:155], v[194:197], 0
	v_mfma_f32_16x16x32_bf16 v[12:15], v[144:147], v[202:205], 0
	v_mfma_f32_16x16x32_bf16 v[8:11], v[152:155], v[202:205], 0
	v_mfma_f32_16x16x32_bf16 v[24:27], v[144:147], v[210:213], 0
	v_mfma_f32_16x16x32_bf16 v[20:23], v[152:155], v[210:213], 0
	v_mfma_f32_16x16x32_bf16 v[28:31], v[148:151], v[190:193], v[28:31]
	v_mfma_f32_16x16x32_bf16 v[16:19], v[156:159], v[190:193], v[16:19]
	v_mfma_f32_16x16x32_bf16 v[4:7], v[148:151], v[198:201], v[4:7]
	v_mfma_f32_16x16x32_bf16 v[0:3], v[156:159], v[198:201], v[0:3]
	v_mfma_f32_16x16x32_bf16 v[12:15], v[148:151], v[206:209], v[12:15]
	v_mfma_f32_16x16x32_bf16 v[8:11], v[156:159], v[206:209], v[8:11]
	v_mfma_f32_16x16x32_bf16 v[24:27], v[148:151], v[214:217], v[24:27]
	v_mfma_f32_16x16x32_bf16 v[20:23], v[156:159], v[214:217], v[20:23]
	s_barrier
	s_setprio 0
	s_add_i32 s42, s57, s3
	v_lshl_add_u64 v[174:175], s[8:9], 0, v[162:163]
	s_mov_b32 m0, s42
	ds_read_b128 v[186:189], v182 offset:16384
	ds_read_b128 v[190:193], v182 offset:17408
	ds_read_b128 v[194:197], v182 offset:18432
	ds_read_b128 v[198:201], v182 offset:19456
	ds_read_b128 v[202:205], v182 offset:20480
	ds_read_b128 v[206:209], v182 offset:21504
	ds_read_b128 v[210:213], v182 offset:22528
	ds_read_b128 v[214:217], v182 offset:23552
	global_load_lds_dwordx4 v[174:175], off
	s_add_i32 m0, s42, 0x2000
	s_add_u32 s42, s8, 0x40000
	v_lshl_add_u64 v[218:219], s[8:9], 0, v[166:167]
	s_addc_u32 s43, s9, 0
	s_add_i32 s44, s81, s3
	global_load_lds_dwordx4 v[218:219], off
	s_mov_b32 m0, s44
	s_nop 0
	global_load_lds_dwordx4 v162, s[42:43]
	s_add_i32 m0, s44, 0x2000
	s_nop 0
	global_load_lds_dwordx4 v166, s[42:43]
	s_mov_b32 m0, s25
	s_nop 0
	global_load_lds_dwordx4 v160, s[36:37]
	s_mov_b32 m0, s33
	s_nop 0
	global_load_lds_dwordx4 v164, s[36:37]
	s_waitcnt vmcnt(8)
	s_waitcnt lgkmcnt(0)
	s_setprio 1
	s_barrier
	v_mfma_f32_16x16x32_bf16 v[116:119], v[128:131], v[186:189], 0
	v_mfma_f32_16x16x32_bf16 v[112:115], v[136:139], v[186:189], 0
	v_mfma_f32_16x16x32_bf16 v[124:127], v[128:131], v[194:197], 0
	v_mfma_f32_16x16x32_bf16 v[120:123], v[136:139], v[194:197], 0
	v_mfma_f32_16x16x32_bf16 v[76:79], v[128:131], v[202:205], 0
	v_mfma_f32_16x16x32_bf16 v[72:75], v[136:139], v[202:205], 0
	v_mfma_f32_16x16x32_bf16 v[68:71], v[128:131], v[210:213], 0
	v_mfma_f32_16x16x32_bf16 v[64:67], v[136:139], v[210:213], 0
	v_mfma_f32_16x16x32_bf16 v[116:119], v[132:135], v[190:193], v[116:119]
	v_mfma_f32_16x16x32_bf16 v[112:115], v[140:143], v[190:193], v[112:115]
	v_mfma_f32_16x16x32_bf16 v[124:127], v[132:135], v[198:201], v[124:127]
	v_mfma_f32_16x16x32_bf16 v[120:123], v[140:143], v[198:201], v[120:123]
	v_mfma_f32_16x16x32_bf16 v[76:79], v[132:135], v[206:209], v[76:79]
	v_mfma_f32_16x16x32_bf16 v[72:75], v[140:143], v[206:209], v[72:75]
	v_mfma_f32_16x16x32_bf16 v[68:71], v[132:135], v[214:217], v[68:71]
	v_mfma_f32_16x16x32_bf16 v[64:67], v[140:143], v[214:217], v[64:67]
	v_mfma_f32_16x16x32_bf16 v[36:39], v[144:147], v[186:189], 0
	v_mfma_f32_16x16x32_bf16 v[32:35], v[152:155], v[186:189], 0
	v_mfma_f32_16x16x32_bf16 v[44:47], v[144:147], v[194:197], 0
	v_mfma_f32_16x16x32_bf16 v[40:43], v[152:155], v[194:197], 0
	v_mfma_f32_16x16x32_bf16 v[52:55], v[144:147], v[202:205], 0
	v_mfma_f32_16x16x32_bf16 v[48:51], v[152:155], v[202:205], 0
	v_mfma_f32_16x16x32_bf16 v[60:63], v[144:147], v[210:213], 0
	v_mfma_f32_16x16x32_bf16 v[56:59], v[152:155], v[210:213], 0
	v_mfma_f32_16x16x32_bf16 v[36:39], v[148:151], v[190:193], v[36:39]
	v_mfma_f32_16x16x32_bf16 v[32:35], v[156:159], v[190:193], v[32:35]
	v_mfma_f32_16x16x32_bf16 v[44:47], v[148:151], v[198:201], v[44:47]
	v_mfma_f32_16x16x32_bf16 v[40:43], v[156:159], v[198:201], v[40:43]
	v_mfma_f32_16x16x32_bf16 v[52:55], v[148:151], v[206:209], v[52:55]
	v_mfma_f32_16x16x32_bf16 v[48:51], v[156:159], v[206:209], v[48:51]
	v_mfma_f32_16x16x32_bf16 v[60:63], v[148:151], v[214:217], v[60:63]
	v_mfma_f32_16x16x32_bf16 v[56:59], v[156:159], v[214:217], v[56:59]
	s_barrier
	s_setprio 0
	s_branch .Lzmid14

.Lzmid14:
	v_add_u32_e32 v140, s82, v179
	v_add_u32_e32 v156, s83, v179
	ds_read_b128 v[128:131], v140
	ds_read_b128 v[132:135], v140 offset:1024
	ds_read_b128 v[136:139], v140 offset:2048
	ds_read_b128 v[140:143], v140 offset:3072
	ds_read_b128 v[144:147], v156
	ds_read_b128 v[148:151], v156 offset:1024
	ds_read_b128 v[152:155], v156 offset:2048
	ds_read_b128 v[156:159], v156 offset:3072
	s_add_u32 s36, s36, 0x4000
	s_addc_u32 s37, s37, 0
	s_mov_b32 m0, s46
	ds_read_b128 v[186:189], v182 offset:32768
	ds_read_b128 v[190:193], v182 offset:33792
	ds_read_b128 v[194:197], v182 offset:34816
	ds_read_b128 v[198:201], v182 offset:35840
	ds_read_b128 v[202:205], v182 offset:36864
	ds_read_b128 v[206:209], v182 offset:37888
	ds_read_b128 v[210:213], v182 offset:38912
	ds_read_b128 v[214:217], v182 offset:39936
	global_load_lds_dwordx4 v160, s[36:37]
	v_lshl_add_u64 v[220:221], s[36:37], 0, v[164:165]
	s_mov_b32 m0, s47
	s_nop 0
	global_load_lds_dwordx4 v[220:221], off
	s_waitcnt vmcnt(8)
	s_waitcnt lgkmcnt(0)
	s_setprio 1
	s_barrier
	v_mfma_f32_16x16x32_bf16 v[104:107], v[128:131], v[186:189], v[104:107]
	v_mfma_f32_16x16x32_bf16 v[96:99], v[136:139], v[186:189], v[96:99]
	v_mfma_f32_16x16x32_bf16 v[84:87], v[128:131], v[194:197], v[84:87]
	v_mfma_f32_16x16x32_bf16 v[80:83], v[136:139], v[194:197], v[80:83]
	v_mfma_f32_16x16x32_bf16 v[92:95], v[128:131], v[202:205], v[92:95]
	v_mfma_f32_16x16x32_bf16 v[88:91], v[136:139], v[202:205], v[88:91]
	v_mfma_f32_16x16x32_bf16 v[108:111], v[128:131], v[210:213], v[108:111]
	v_mfma_f32_16x16x32_bf16 v[100:103], v[136:139], v[210:213], v[100:103]
	v_mfma_f32_16x16x32_bf16 v[104:107], v[132:135], v[190:193], v[104:107]
	v_mfma_f32_16x16x32_bf16 v[96:99], v[140:143], v[190:193], v[96:99]
	v_mfma_f32_16x16x32_bf16 v[84:87], v[132:135], v[198:201], v[84:87]
	v_mfma_f32_16x16x32_bf16 v[80:83], v[140:143], v[198:201], v[80:83]
	v_mfma_f32_16x16x32_bf16 v[92:95], v[132:135], v[206:209], v[92:95]
	v_mfma_f32_16x16x32_bf16 v[88:91], v[140:143], v[206:209], v[88:91]
	v_mfma_f32_16x16x32_bf16 v[108:111], v[132:135], v[214:217], v[108:111]
	v_mfma_f32_16x16x32_bf16 v[100:103], v[140:143], v[214:217], v[100:103]
	v_mfma_f32_16x16x32_bf16 v[28:31], v[144:147], v[186:189], v[28:31]
	v_mfma_f32_16x16x32_bf16 v[16:19], v[152:155], v[186:189], v[16:19]
	v_mfma_f32_16x16x32_bf16 v[4:7], v[144:147], v[194:197], v[4:7]
	v_mfma_f32_16x16x32_bf16 v[0:3], v[152:155], v[194:197], v[0:3]
	v_mfma_f32_16x16x32_bf16 v[12:15], v[144:147], v[202:205], v[12:15]
	v_mfma_f32_16x16x32_bf16 v[8:11], v[152:155], v[202:205], v[8:11]
	v_mfma_f32_16x16x32_bf16 v[24:27], v[144:147], v[210:213], v[24:27]
	v_mfma_f32_16x16x32_bf16 v[20:23], v[152:155], v[210:213], v[20:23]
	v_mfma_f32_16x16x32_bf16 v[28:31], v[148:151], v[190:193], v[28:31]
	v_mfma_f32_16x16x32_bf16 v[16:19], v[156:159], v[190:193], v[16:19]
	v_mfma_f32_16x16x32_bf16 v[4:7], v[148:151], v[198:201], v[4:7]
	v_mfma_f32_16x16x32_bf16 v[0:3], v[156:159], v[198:201], v[0:3]
	v_mfma_f32_16x16x32_bf16 v[12:15], v[148:151], v[206:209], v[12:15]
	v_mfma_f32_16x16x32_bf16 v[8:11], v[156:159], v[206:209], v[8:11]
	v_mfma_f32_16x16x32_bf16 v[24:27], v[148:151], v[214:217], v[24:27]
	v_mfma_f32_16x16x32_bf16 v[20:23], v[156:159], v[214:217], v[20:23]
	s_barrier
	s_setprio 0
	s_add_i32 s36, s82, s3
	v_lshl_add_u64 v[174:175], v[174:175], 0, s[20:21]
	s_mov_b32 m0, s36
	ds_read_b128 v[186:189], v182 offset:49152
	ds_read_b128 v[190:193], v182 offset:50176
	ds_read_b128 v[194:197], v182 offset:51200
	ds_read_b128 v[198:201], v182 offset:52224
	ds_read_b128 v[202:205], v182 offset:53248
	ds_read_b128 v[206:209], v182 offset:54272
	ds_read_b128 v[210:213], v182 offset:55296
	ds_read_b128 v[214:217], v182 offset:56320
	global_load_lds_dwordx4 v[174:175], off
	s_add_i32 m0, s36, 0x2000
	s_add_u32 s8, s8, 0x40080
	v_lshl_add_u64 v[174:175], v[218:219], 0, s[20:21]
	s_addc_u32 s9, s9, 0
	s_add_i32 s36, s83, s3
	global_load_lds_dwordx4 v[174:175], off
	s_mov_b32 m0, s36
	s_nop 0
	global_load_lds_dwordx4 v162, s[8:9]
	s_add_i32 m0, s36, 0x2000
	s_nop 0
	global_load_lds_dwordx4 v166, s[8:9]
	s_mov_b32 m0, s54
	s_nop 0
	global_load_lds_dwordx4 v160, s[6:7]
	s_mov_b32 m0, s55
	s_nop 0
	global_load_lds_dwordx4 v164, s[6:7]
	s_waitcnt vmcnt(8)
	s_waitcnt lgkmcnt(0)
	s_setprio 1
	s_barrier
	v_mfma_f32_16x16x32_bf16 v[116:119], v[128:131], v[186:189], v[116:119]
	v_mfma_f32_16x16x32_bf16 v[112:115], v[136:139], v[186:189], v[112:115]
	v_mfma_f32_16x16x32_bf16 v[124:127], v[128:131], v[194:197], v[124:127]
	v_mfma_f32_16x16x32_bf16 v[120:123], v[136:139], v[194:197], v[120:123]
	v_mfma_f32_16x16x32_bf16 v[76:79], v[128:131], v[202:205], v[76:79]
	v_mfma_f32_16x16x32_bf16 v[72:75], v[136:139], v[202:205], v[72:75]
	v_mfma_f32_16x16x32_bf16 v[68:71], v[128:131], v[210:213], v[68:71]
	v_mfma_f32_16x16x32_bf16 v[64:67], v[136:139], v[210:213], v[64:67]
	v_mfma_f32_16x16x32_bf16 v[116:119], v[132:135], v[190:193], v[116:119]
	v_mfma_f32_16x16x32_bf16 v[112:115], v[140:143], v[190:193], v[112:115]
	v_mfma_f32_16x16x32_bf16 v[124:127], v[132:135], v[198:201], v[124:127]
	v_mfma_f32_16x16x32_bf16 v[120:123], v[140:143], v[198:201], v[120:123]
	v_mfma_f32_16x16x32_bf16 v[76:79], v[132:135], v[206:209], v[76:79]
	v_mfma_f32_16x16x32_bf16 v[72:75], v[140:143], v[206:209], v[72:75]
	v_mfma_f32_16x16x32_bf16 v[68:71], v[132:135], v[214:217], v[68:71]
	v_mfma_f32_16x16x32_bf16 v[64:67], v[140:143], v[214:217], v[64:67]
	v_mfma_f32_16x16x32_bf16 v[36:39], v[144:147], v[186:189], v[36:39]
	v_mfma_f32_16x16x32_bf16 v[32:35], v[152:155], v[186:189], v[32:35]
	v_mfma_f32_16x16x32_bf16 v[44:47], v[144:147], v[194:197], v[44:47]
	v_mfma_f32_16x16x32_bf16 v[40:43], v[152:155], v[194:197], v[40:43]
	v_mfma_f32_16x16x32_bf16 v[52:55], v[144:147], v[202:205], v[52:55]
	v_mfma_f32_16x16x32_bf16 v[48:51], v[152:155], v[202:205], v[48:51]
	v_mfma_f32_16x16x32_bf16 v[60:63], v[144:147], v[210:213], v[60:63]
	v_mfma_f32_16x16x32_bf16 v[56:59], v[152:155], v[210:213], v[56:59]
	v_mfma_f32_16x16x32_bf16 v[36:39], v[148:151], v[190:193], v[36:39]
	v_mfma_f32_16x16x32_bf16 v[32:35], v[156:159], v[190:193], v[32:35]
	v_mfma_f32_16x16x32_bf16 v[44:47], v[148:151], v[198:201], v[44:47]
	v_mfma_f32_16x16x32_bf16 v[40:43], v[156:159], v[198:201], v[40:43]
	v_mfma_f32_16x16x32_bf16 v[52:55], v[148:151], v[206:209], v[52:55]
	v_mfma_f32_16x16x32_bf16 v[48:51], v[156:159], v[206:209], v[48:51]
	v_mfma_f32_16x16x32_bf16 v[60:63], v[148:151], v[214:217], v[60:63]
	v_mfma_f32_16x16x32_bf16 v[56:59], v[156:159], v[214:217], v[56:59]
	s_barrier
	s_setprio 0
	s_add_i32 s41, s41, 2
	s_add_u32 s39, s39, 0x100
	s_addc_u32 s40, s40, 0
	s_add_u32 s0, s0, 0x800000
	s_addc_u32 s1, s1, 0
	s_cmp_gt_u32 s41, 13
	s_cbranch_scc0 .LBB0_2772
	s_and_b64 vcc, exec, s[22:23]
	s_cbranch_vccz .LBB0_2775
	s_barrier

.LBB0_2887:
	s_mov_b32 s15, s7
	s_lshl_b64 s[18:19], s[14:15], 1
	s_add_u32 s18, s58, s18
	s_addc_u32 s19, s59, s19
	s_and_b64 s[20:21], s[0:1], exec
	s_mov_b32 s17, s7
	s_cselect_b32 s15, s19, s25
	s_cselect_b32 s50, s18, s24
	s_lshl_b64 s[20:21], s[16:17], 1
	s_add_u32 s20, s4, s20
	s_addc_u32 s21, s5, s21
	s_and_b64 s[26:27], s[0:1], exec
	s_cselect_b32 s17, s21, s23
	s_cselect_b32 s51, s20, s22
	s_add_u32 s52, s22, 0x2c0000
	s_addc_u32 s53, s23, 0
	s_add_u32 s22, s24, 0x404000
	s_addc_u32 s23, s25, 0
	s_mov_b32 s54, -2
	ds_read_b128 v[152:155], v149
	ds_read_b128 v[156:159], v149 offset:1024
	ds_read_b128 v[160:163], v149 offset:2048
	ds_read_b128 v[164:167], v149 offset:3072
	ds_read_b128 v[168:171], v150
	ds_read_b128 v[172:175], v150 offset:1024
	ds_read_b128 v[176:179], v150 offset:2048
	ds_read_b128 v[180:183], v150 offset:3072
	s_add_u32 s24, s22, 0x3fc000
	s_addc_u32 s25, s23, 0
	s_cmp_eq_u32 s54, 28
	s_cselect_b32 s28, s50, s24
	s_cselect_b32 s29, s15, s25
	s_cselect_b32 s26, s51, s52
	s_cselect_b32 s27, s17, s53
	s_add_u32 s24, s28, 0x400000
	s_addc_u32 s25, s29, 0
	s_add_i32 m0, s31, 0xc000
	ds_read_b128 v[184:187], v151
	ds_read_b128 v[188:191], v151 offset:1024
	ds_read_b128 v[192:195], v151 offset:2048
	ds_read_b128 v[196:199], v151 offset:3072
	ds_read_b128 v[200:203], v151 offset:4096
	ds_read_b128 v[204:207], v151 offset:5120
	ds_read_b128 v[208:211], v151 offset:6144
	ds_read_b128 v[212:215], v151 offset:7168
	global_load_lds_dwordx4 v136, s[22:23]
	s_add_i32 m0, s31, 0xe000
	s_nop 0
	global_load_lds_dwordx4 v138, s[22:23]
	s_waitcnt vmcnt(8)
	s_waitcnt lgkmcnt(0)
	s_setprio 1
	s_barrier
	v_mfma_f32_16x16x32_bf16 v[124:127], v[152:155], v[184:187], 0
	v_mfma_f32_16x16x32_bf16 v[120:123], v[160:163], v[184:187], 0
	v_mfma_f32_16x16x32_bf16 v[108:111], v[152:155], v[192:195], 0
	v_mfma_f32_16x16x32_bf16 v[104:107], v[160:163], v[192:195], 0
	v_mfma_f32_16x16x32_bf16 v[92:95], v[152:155], v[200:203], 0
	v_mfma_f32_16x16x32_bf16 v[88:91], v[160:163], v[200:203], 0
	v_mfma_f32_16x16x32_bf16 v[76:79], v[152:155], v[208:211], 0
	v_mfma_f32_16x16x32_bf16 v[72:75], v[160:163], v[208:211], 0
	v_mfma_f32_16x16x32_bf16 v[124:127], v[156:159], v[188:191], v[124:127]
	v_mfma_f32_16x16x32_bf16 v[120:123], v[164:167], v[188:191], v[120:123]
	v_mfma_f32_16x16x32_bf16 v[108:111], v[156:159], v[196:199], v[108:111]
	v_mfma_f32_16x16x32_bf16 v[104:107], v[164:167], v[196:199], v[104:107]
	v_mfma_f32_16x16x32_bf16 v[92:95], v[156:159], v[204:207], v[92:95]
	v_mfma_f32_16x16x32_bf16 v[88:91], v[164:167], v[204:207], v[88:91]
	v_mfma_f32_16x16x32_bf16 v[76:79], v[156:159], v[212:215], v[76:79]
	v_mfma_f32_16x16x32_bf16 v[72:75], v[164:167], v[212:215], v[72:75]
	v_mfma_f32_16x16x32_bf16 v[116:119], v[168:171], v[184:187], 0
	v_mfma_f32_16x16x32_bf16 v[112:115], v[176:179], v[184:187], 0
	v_mfma_f32_16x16x32_bf16 v[100:103], v[168:171], v[192:195], 0
	v_mfma_f32_16x16x32_bf16 v[96:99], v[176:179], v[192:195], 0
	v_mfma_f32_16x16x32_bf16 v[84:87], v[168:171], v[200:203], 0
	v_mfma_f32_16x16x32_bf16 v[80:83], v[176:179], v[200:203], 0
	v_mfma_f32_16x16x32_bf16 v[68:71], v[168:171], v[208:211], 0
	v_mfma_f32_16x16x32_bf16 v[64:67], v[176:179], v[208:211], 0
	v_mfma_f32_16x16x32_bf16 v[116:119], v[172:175], v[188:191], v[116:119]
	v_mfma_f32_16x16x32_bf16 v[112:115], v[180:183], v[188:191], v[112:115]
	v_mfma_f32_16x16x32_bf16 v[100:103], v[172:175], v[196:199], v[100:103]
	v_mfma_f32_16x16x32_bf16 v[96:99], v[180:183], v[196:199], v[96:99]
	v_mfma_f32_16x16x32_bf16 v[84:87], v[172:175], v[204:207], v[84:87]
	v_mfma_f32_16x16x32_bf16 v[80:83], v[180:183], v[204:207], v[80:83]
	v_mfma_f32_16x16x32_bf16 v[68:71], v[172:175], v[212:215], v[68:71]
	v_mfma_f32_16x16x32_bf16 v[64:67], v[180:183], v[212:215], v[64:67]
	s_barrier
	s_setprio 0
	s_add_i32 s55, s57, s30
	s_mov_b32 m0, s55
	ds_read_b128 v[184:187], v151 offset:16384
	ds_read_b128 v[188:191], v151 offset:17408
	ds_read_b128 v[192:195], v151 offset:18432
	ds_read_b128 v[196:199], v151 offset:19456
	ds_read_b128 v[200:203], v151 offset:20480
	ds_read_b128 v[204:207], v151 offset:21504
	ds_read_b128 v[208:211], v151 offset:22528
	ds_read_b128 v[212:215], v151 offset:23552
	global_load_lds_dwordx4 v132, s[26:27]
	s_add_i32 m0, s55, 0x2000
	s_add_u32 s64, s26, 0x4000
	s_addc_u32 s65, s27, 0
	s_add_i32 s55, s81, s30
	global_load_lds_dwordx4 v128, s[26:27]
	s_mov_b32 m0, s55
	s_nop 0
	global_load_lds_dwordx4 v132, s[64:65]
	s_add_i32 m0, s55, 0x2000
	s_nop 0
	global_load_lds_dwordx4 v128, s[64:65]
	s_mov_b32 m0, s31
	s_nop 0
	global_load_lds_dwordx4 v134, s[28:29]
	s_mov_b32 m0, s33
	s_nop 0
	global_load_lds_dwordx4 v130, s[28:29]
	s_waitcnt vmcnt(8)
	s_waitcnt lgkmcnt(0)
	s_setprio 1
	s_barrier
	v_mfma_f32_16x16x32_bf16 v[60:63], v[152:155], v[184:187], 0
	v_mfma_f32_16x16x32_bf16 v[56:59], v[160:163], v[184:187], 0
	v_mfma_f32_16x16x32_bf16 v[44:47], v[152:155], v[192:195], 0
	v_mfma_f32_16x16x32_bf16 v[40:43], v[160:163], v[192:195], 0
	v_mfma_f32_16x16x32_bf16 v[28:31], v[152:155], v[200:203], 0
	v_mfma_f32_16x16x32_bf16 v[24:27], v[160:163], v[200:203], 0
	v_mfma_f32_16x16x32_bf16 v[12:15], v[152:155], v[208:211], 0
	v_mfma_f32_16x16x32_bf16 v[8:11], v[160:163], v[208:211], 0
	v_mfma_f32_16x16x32_bf16 v[60:63], v[156:159], v[188:191], v[60:63]
	v_mfma_f32_16x16x32_bf16 v[56:59], v[164:167], v[188:191], v[56:59]
	v_mfma_f32_16x16x32_bf16 v[44:47], v[156:159], v[196:199], v[44:47]
	v_mfma_f32_16x16x32_bf16 v[40:43], v[164:167], v[196:199], v[40:43]
	v_mfma_f32_16x16x32_bf16 v[28:31], v[156:159], v[204:207], v[28:31]
	v_mfma_f32_16x16x32_bf16 v[24:27], v[164:167], v[204:207], v[24:27]
	v_mfma_f32_16x16x32_bf16 v[12:15], v[156:159], v[212:215], v[12:15]
	v_mfma_f32_16x16x32_bf16 v[8:11], v[164:167], v[212:215], v[8:11]
	v_mfma_f32_16x16x32_bf16 v[52:55], v[168:171], v[184:187], 0
	v_mfma_f32_16x16x32_bf16 v[48:51], v[176:179], v[184:187], 0
	v_mfma_f32_16x16x32_bf16 v[36:39], v[168:171], v[192:195], 0
	v_mfma_f32_16x16x32_bf16 v[32:35], v[176:179], v[192:195], 0
	v_mfma_f32_16x16x32_bf16 v[20:23], v[168:171], v[200:203], 0
	v_mfma_f32_16x16x32_bf16 v[16:19], v[176:179], v[200:203], 0
	v_mfma_f32_16x16x32_bf16 v[4:7], v[168:171], v[208:211], 0
	v_mfma_f32_16x16x32_bf16 v[0:3], v[176:179], v[208:211], 0
	v_mfma_f32_16x16x32_bf16 v[52:55], v[172:175], v[188:191], v[52:55]
	v_mfma_f32_16x16x32_bf16 v[48:51], v[180:183], v[188:191], v[48:51]
	v_mfma_f32_16x16x32_bf16 v[36:39], v[172:175], v[196:199], v[36:39]
	v_mfma_f32_16x16x32_bf16 v[32:35], v[180:183], v[196:199], v[32:35]
	v_mfma_f32_16x16x32_bf16 v[20:23], v[172:175], v[204:207], v[20:23]
	v_mfma_f32_16x16x32_bf16 v[16:19], v[180:183], v[204:207], v[16:19]
	v_mfma_f32_16x16x32_bf16 v[4:7], v[172:175], v[212:215], v[4:7]
	v_mfma_f32_16x16x32_bf16 v[0:3], v[180:183], v[212:215], v[0:3]
	s_barrier
	s_setprio 0
	s_branch .Lzmid15

.Lzmid15:
	v_add_u32_e32 v144, s82, v148
	ds_read_b128 v[152:155], v144
	ds_read_b128 v[156:159], v144 offset:1024
	ds_read_b128 v[160:163], v144 offset:2048
	ds_read_b128 v[164:167], v144 offset:3072
	v_add_u32_e32 v144, s83, v148
	ds_read_b128 v[168:171], v144
	ds_read_b128 v[172:175], v144 offset:1024
	ds_read_b128 v[176:179], v144 offset:2048
	ds_read_b128 v[180:183], v144 offset:3072
	s_add_u32 s28, s28, 0x4000
	s_addc_u32 s29, s29, 0
	s_mov_b32 m0, s34
	ds_read_b128 v[184:187], v151 offset:32768
	ds_read_b128 v[188:191], v151 offset:33792
	ds_read_b128 v[192:195], v151 offset:34816
	ds_read_b128 v[196:199], v151 offset:35840
	ds_read_b128 v[200:203], v151 offset:36864
	ds_read_b128 v[204:207], v151 offset:37888
	ds_read_b128 v[208:211], v151 offset:38912
	ds_read_b128 v[212:215], v151 offset:39936
	global_load_lds_dwordx4 v134, s[28:29]
	s_mov_b32 m0, s35
	s_nop 0
	global_load_lds_dwordx4 v130, s[28:29]
	s_waitcnt vmcnt(8)
	s_waitcnt lgkmcnt(0)
	s_setprio 1
	s_barrier
	v_mfma_f32_16x16x32_bf16 v[124:127], v[152:155], v[184:187], v[124:127]
	v_mfma_f32_16x16x32_bf16 v[120:123], v[160:163], v[184:187], v[120:123]
	v_mfma_f32_16x16x32_bf16 v[108:111], v[152:155], v[192:195], v[108:111]
	v_mfma_f32_16x16x32_bf16 v[104:107], v[160:163], v[192:195], v[104:107]
	v_mfma_f32_16x16x32_bf16 v[92:95], v[152:155], v[200:203], v[92:95]
	v_mfma_f32_16x16x32_bf16 v[88:91], v[160:163], v[200:203], v[88:91]
	v_mfma_f32_16x16x32_bf16 v[76:79], v[152:155], v[208:211], v[76:79]
	v_mfma_f32_16x16x32_bf16 v[72:75], v[160:163], v[208:211], v[72:75]
	v_mfma_f32_16x16x32_bf16 v[124:127], v[156:159], v[188:191], v[124:127]
	v_mfma_f32_16x16x32_bf16 v[120:123], v[164:167], v[188:191], v[120:123]
	v_mfma_f32_16x16x32_bf16 v[108:111], v[156:159], v[196:199], v[108:111]
	v_mfma_f32_16x16x32_bf16 v[104:107], v[164:167], v[196:199], v[104:107]
	v_mfma_f32_16x16x32_bf16 v[92:95], v[156:159], v[204:207], v[92:95]
	v_mfma_f32_16x16x32_bf16 v[88:91], v[164:167], v[204:207], v[88:91]
	v_mfma_f32_16x16x32_bf16 v[76:79], v[156:159], v[212:215], v[76:79]
	v_mfma_f32_16x16x32_bf16 v[72:75], v[164:167], v[212:215], v[72:75]
	v_mfma_f32_16x16x32_bf16 v[116:119], v[168:171], v[184:187], v[116:119]
	v_mfma_f32_16x16x32_bf16 v[112:115], v[176:179], v[184:187], v[112:115]
	v_mfma_f32_16x16x32_bf16 v[100:103], v[168:171], v[192:195], v[100:103]
	v_mfma_f32_16x16x32_bf16 v[96:99], v[176:179], v[192:195], v[96:99]
	v_mfma_f32_16x16x32_bf16 v[84:87], v[168:171], v[200:203], v[84:87]
	v_mfma_f32_16x16x32_bf16 v[80:83], v[176:179], v[200:203], v[80:83]
	v_mfma_f32_16x16x32_bf16 v[68:71], v[168:171], v[208:211], v[68:71]
	v_mfma_f32_16x16x32_bf16 v[64:67], v[176:179], v[208:211], v[64:67]
	v_mfma_f32_16x16x32_bf16 v[116:119], v[172:175], v[188:191], v[116:119]
	v_mfma_f32_16x16x32_bf16 v[112:115], v[180:183], v[188:191], v[112:115]
	v_mfma_f32_16x16x32_bf16 v[100:103], v[172:175], v[196:199], v[100:103]
	v_mfma_f32_16x16x32_bf16 v[96:99], v[180:183], v[196:199], v[96:99]
	v_mfma_f32_16x16x32_bf16 v[84:87], v[172:175], v[204:207], v[84:87]
	v_mfma_f32_16x16x32_bf16 v[80:83], v[180:183], v[204:207], v[80:83]
	v_mfma_f32_16x16x32_bf16 v[68:71], v[172:175], v[212:215], v[68:71]
	v_mfma_f32_16x16x32_bf16 v[64:67], v[180:183], v[212:215], v[64:67]
	s_barrier
	s_setprio 0
	s_add_u32 s28, s26, 0x160000
	s_addc_u32 s29, s27, 0
	s_add_i32 s55, s82, s30
	s_mov_b32 m0, s55
	ds_read_b128 v[184:187], v151 offset:49152
	ds_read_b128 v[188:191], v151 offset:50176
	ds_read_b128 v[192:195], v151 offset:51200
	ds_read_b128 v[196:199], v151 offset:52224
	ds_read_b128 v[200:203], v151 offset:53248
	ds_read_b128 v[204:207], v151 offset:54272
	ds_read_b128 v[208:211], v151 offset:55296
	ds_read_b128 v[212:215], v151 offset:56320
	global_load_lds_dwordx4 v132, s[28:29]
	s_add_i32 m0, s55, 0x2000
	s_add_u32 s26, s26, 0x164000
	global_load_lds_dwordx4 v128, s[28:29]
	s_addc_u32 s27, s27, 0
	s_add_i32 s28, s83, s30
	s_mov_b32 m0, s28
	s_nop 0
	global_load_lds_dwordx4 v132, s[26:27]
	s_add_i32 m0, s28, 0x2000
	s_nop 0
	global_load_lds_dwordx4 v128, s[26:27]
	s_mov_b32 m0, s38
	s_nop 0
	global_load_lds_dwordx4 v134, s[24:25]
	s_mov_b32 m0, s39
	s_nop 0
	global_load_lds_dwordx4 v130, s[24:25]
	s_waitcnt vmcnt(8)
	s_waitcnt lgkmcnt(0)
	s_setprio 1
	s_barrier
	v_mfma_f32_16x16x32_bf16 v[60:63], v[152:155], v[184:187], v[60:63]
	v_mfma_f32_16x16x32_bf16 v[56:59], v[160:163], v[184:187], v[56:59]
	v_mfma_f32_16x16x32_bf16 v[44:47], v[152:155], v[192:195], v[44:47]
	v_mfma_f32_16x16x32_bf16 v[40:43], v[160:163], v[192:195], v[40:43]
	v_mfma_f32_16x16x32_bf16 v[28:31], v[152:155], v[200:203], v[28:31]
	v_mfma_f32_16x16x32_bf16 v[24:27], v[160:163], v[200:203], v[24:27]
	v_mfma_f32_16x16x32_bf16 v[12:15], v[152:155], v[208:211], v[12:15]
	v_mfma_f32_16x16x32_bf16 v[8:11], v[160:163], v[208:211], v[8:11]
	v_mfma_f32_16x16x32_bf16 v[60:63], v[156:159], v[188:191], v[60:63]
	v_mfma_f32_16x16x32_bf16 v[56:59], v[164:167], v[188:191], v[56:59]
	v_mfma_f32_16x16x32_bf16 v[44:47], v[156:159], v[196:199], v[44:47]
	v_mfma_f32_16x16x32_bf16 v[40:43], v[164:167], v[196:199], v[40:43]
	v_mfma_f32_16x16x32_bf16 v[28:31], v[156:159], v[204:207], v[28:31]
	v_mfma_f32_16x16x32_bf16 v[24:27], v[164:167], v[204:207], v[24:27]
	v_mfma_f32_16x16x32_bf16 v[12:15], v[156:159], v[212:215], v[12:15]
	v_mfma_f32_16x16x32_bf16 v[8:11], v[164:167], v[212:215], v[8:11]
	v_mfma_f32_16x16x32_bf16 v[52:55], v[168:171], v[184:187], v[52:55]
	v_mfma_f32_16x16x32_bf16 v[48:51], v[176:179], v[184:187], v[48:51]
	v_mfma_f32_16x16x32_bf16 v[36:39], v[168:171], v[192:195], v[36:39]
	v_mfma_f32_16x16x32_bf16 v[32:35], v[176:179], v[192:195], v[32:35]
	v_mfma_f32_16x16x32_bf16 v[20:23], v[168:171], v[200:203], v[20:23]
	v_mfma_f32_16x16x32_bf16 v[16:19], v[176:179], v[200:203], v[16:19]
	v_mfma_f32_16x16x32_bf16 v[4:7], v[168:171], v[208:211], v[4:7]
	v_mfma_f32_16x16x32_bf16 v[0:3], v[176:179], v[208:211], v[0:3]
	v_mfma_f32_16x16x32_bf16 v[52:55], v[172:175], v[188:191], v[52:55]
	v_mfma_f32_16x16x32_bf16 v[48:51], v[180:183], v[188:191], v[48:51]
	v_mfma_f32_16x16x32_bf16 v[36:39], v[172:175], v[196:199], v[36:39]
	v_mfma_f32_16x16x32_bf16 v[32:35], v[180:183], v[196:199], v[32:35]
	v_mfma_f32_16x16x32_bf16 v[20:23], v[172:175], v[204:207], v[20:23]
	v_mfma_f32_16x16x32_bf16 v[16:19], v[180:183], v[204:207], v[16:19]
	v_mfma_f32_16x16x32_bf16 v[4:7], v[172:175], v[212:215], v[4:7]
	v_mfma_f32_16x16x32_bf16 v[0:3], v[180:183], v[212:215], v[0:3]
	s_barrier
	s_setprio 0
	s_add_i32 s54, s54, 2
	s_add_u32 s52, s52, 0x2c0000
	s_addc_u32 s53, s53, 0
	s_add_u32 s22, s22, 0x800000
	s_addc_u32 s23, s23, 0
	s_cmp_gt_u32 s54, 29
	s_cbranch_scc0 .LBB0_2888
	s_and_b64 vcc, exec, s[10:11]
	s_cbranch_vccz .LBB0_2891
	s_barrier

.LBB0_2965:
	s_mov_b32 s25, s7
	s_lshl_b64 s[26:27], s[24:25], 1
	s_add_u32 s26, s60, s26
	s_addc_u32 s27, s61, s27
	s_and_b64 s[34:35], exec, s[4:5]
	s_cselect_b32 s6, s27, s3
	s_cselect_b32 s9, s26, s2
	s_lshl_b64 s[28:29], s[28:29], 1
	s_add_u32 s28, s23, s28
	s_addc_u32 s29, s44, s29
	s_and_b64 s[4:5], exec, s[4:5]
	s_cselect_b32 s25, s29, s1
	s_cselect_b32 s36, s28, s0
	s_add_u32 s37, s0, 0x80000
	s_addc_u32 s38, s1, 0
	s_add_u32 s0, s2, 0x404000
	s_addc_u32 s1, s3, 0
	s_mov_b32 s39, -2
	ds_read_b128 v[128:131], v186
	ds_read_b128 v[132:135], v186 offset:1024
	ds_read_b128 v[136:139], v186 offset:2048
	ds_read_b128 v[140:143], v186 offset:3072
	ds_read_b128 v[144:147], v187
	ds_read_b128 v[148:151], v187 offset:1024
	ds_read_b128 v[152:155], v187 offset:2048
	ds_read_b128 v[156:159], v187 offset:3072
	s_add_u32 s2, s0, 0x3fc000
	s_addc_u32 s3, s1, 0
	s_cmpk_eq_i32 s39, 0x54
	s_cselect_b32 s34, s9, s2
	s_cselect_b32 s35, s6, s3
	s_cselect_b32 s4, s36, s37
	s_cselect_b32 s5, s25, s38
	s_add_u32 s2, s34, 0x400000
	s_addc_u32 s3, s35, 0
	s_add_i32 m0, s52, 0xc000
	ds_read_b128 v[174:177], v188
	ds_read_b128 v[178:181], v188 offset:1024
	ds_read_b128 v[192:195], v188 offset:2048
	ds_read_b128 v[196:199], v188 offset:3072
	ds_read_b128 v[200:203], v188 offset:4096
	ds_read_b128 v[204:207], v188 offset:5120
	ds_read_b128 v[208:211], v188 offset:6144
	ds_read_b128 v[212:215], v188 offset:7168
	global_load_lds_dwordx4 v168, s[0:1]
	s_add_i32 m0, s52, 0xe000
	s_nop 0
	global_load_lds_dwordx4 v170, s[0:1]
	s_waitcnt vmcnt(8)
	s_waitcnt lgkmcnt(0)
	s_setprio 1
	s_barrier
	v_mfma_f32_16x16x32_bf16 v[52:55], v[128:131], v[174:177], 0
	v_mfma_f32_16x16x32_bf16 v[48:51], v[136:139], v[174:177], 0
	v_mfma_f32_16x16x32_bf16 v[12:15], v[128:131], v[192:195], 0
	v_mfma_f32_16x16x32_bf16 v[0:3], v[136:139], v[192:195], 0
	v_mfma_f32_16x16x32_bf16 v[64:67], v[128:131], v[200:203], 0
	v_mfma_f32_16x16x32_bf16 v[68:71], v[136:139], v[200:203], 0
	v_mfma_f32_16x16x32_bf16 v[80:83], v[128:131], v[208:211], 0
	v_mfma_f32_16x16x32_bf16 v[84:87], v[136:139], v[208:211], 0
	v_mfma_f32_16x16x32_bf16 v[52:55], v[132:135], v[178:181], v[52:55]
	v_mfma_f32_16x16x32_bf16 v[48:51], v[140:143], v[178:181], v[48:51]
	v_mfma_f32_16x16x32_bf16 v[12:15], v[132:135], v[196:199], v[12:15]
	v_mfma_f32_16x16x32_bf16 v[0:3], v[140:143], v[196:199], v[0:3]
	v_mfma_f32_16x16x32_bf16 v[64:67], v[132:135], v[204:207], v[64:67]
	v_mfma_f32_16x16x32_bf16 v[68:71], v[140:143], v[204:207], v[68:71]
	v_mfma_f32_16x16x32_bf16 v[80:83], v[132:135], v[212:215], v[80:83]
	v_mfma_f32_16x16x32_bf16 v[84:87], v[140:143], v[212:215], v[84:87]
	v_mfma_f32_16x16x32_bf16 v[44:47], v[144:147], v[174:177], 0
	v_mfma_f32_16x16x32_bf16 v[40:43], v[152:155], v[174:177], 0
	v_mfma_f32_16x16x32_bf16 v[4:7], v[144:147], v[192:195], 0
	v_mfma_f32_16x16x32_bf16 v[8:11], v[152:155], v[192:195], 0
	v_mfma_f32_16x16x32_bf16 v[16:19], v[144:147], v[200:203], 0
	v_mfma_f32_16x16x32_bf16 v[20:23], v[152:155], v[200:203], 0
	v_mfma_f32_16x16x32_bf16 v[24:27], v[144:147], v[208:211], 0
	v_mfma_f32_16x16x32_bf16 v[28:31], v[152:155], v[208:211], 0
	v_mfma_f32_16x16x32_bf16 v[44:47], v[148:151], v[178:181], v[44:47]
	v_mfma_f32_16x16x32_bf16 v[40:43], v[156:159], v[178:181], v[40:43]
	v_mfma_f32_16x16x32_bf16 v[4:7], v[148:151], v[196:199], v[4:7]
	v_mfma_f32_16x16x32_bf16 v[8:11], v[156:159], v[196:199], v[8:11]
	v_mfma_f32_16x16x32_bf16 v[16:19], v[148:151], v[204:207], v[16:19]
	v_mfma_f32_16x16x32_bf16 v[20:23], v[156:159], v[204:207], v[20:23]
	v_mfma_f32_16x16x32_bf16 v[24:27], v[148:151], v[212:215], v[24:27]
	v_mfma_f32_16x16x32_bf16 v[28:31], v[156:159], v[212:215], v[28:31]
	s_barrier
	s_setprio 0
	s_add_i32 s40, s57, s46
	s_mov_b32 m0, s40
	ds_read_b128 v[174:177], v188 offset:16384
	ds_read_b128 v[178:181], v188 offset:17408
	ds_read_b128 v[192:195], v188 offset:18432
	ds_read_b128 v[196:199], v188 offset:19456
	ds_read_b128 v[200:203], v188 offset:20480
	ds_read_b128 v[204:207], v188 offset:21504
	ds_read_b128 v[208:211], v188 offset:22528
	ds_read_b128 v[212:215], v188 offset:23552
	global_load_lds_dwordx4 v162, s[4:5]
	s_add_i32 m0, s40, 0x2000
	s_add_u32 s40, s4, 0x4000
	s_addc_u32 s41, s5, 0
	s_add_i32 s42, s81, s46
	global_load_lds_dwordx4 v166, s[4:5]
	s_mov_b32 m0, s42
	s_nop 0
	global_load_lds_dwordx4 v162, s[40:41]
	s_add_i32 m0, s42, 0x2000
	s_nop 0
	global_load_lds_dwordx4 v166, s[40:41]
	s_mov_b32 m0, s52
	s_nop 0
	global_load_lds_dwordx4 v160, s[34:35]
	s_mov_b32 m0, s53
	s_nop 0
	global_load_lds_dwordx4 v164, s[34:35]
	s_waitcnt vmcnt(8)
	s_waitcnt lgkmcnt(0)
	s_setprio 1
	s_barrier
	v_mfma_f32_16x16x32_bf16 v[104:107], v[128:131], v[174:177], 0
	v_mfma_f32_16x16x32_bf16 v[108:111], v[136:139], v[174:177], 0
	v_mfma_f32_16x16x32_bf16 v[120:123], v[128:131], v[192:195], 0
	v_mfma_f32_16x16x32_bf16 v[124:127], v[136:139], v[192:195], 0
	v_mfma_f32_16x16x32_bf16 v[116:119], v[128:131], v[200:203], 0
	v_mfma_f32_16x16x32_bf16 v[112:115], v[136:139], v[200:203], 0
	v_mfma_f32_16x16x32_bf16 v[100:103], v[128:131], v[208:211], 0
	v_mfma_f32_16x16x32_bf16 v[96:99], v[136:139], v[208:211], 0
	v_mfma_f32_16x16x32_bf16 v[104:107], v[132:135], v[178:181], v[104:107]
	v_mfma_f32_16x16x32_bf16 v[108:111], v[140:143], v[178:181], v[108:111]
	v_mfma_f32_16x16x32_bf16 v[120:123], v[132:135], v[196:199], v[120:123]
	v_mfma_f32_16x16x32_bf16 v[124:127], v[140:143], v[196:199], v[124:127]
	v_mfma_f32_16x16x32_bf16 v[116:119], v[132:135], v[204:207], v[116:119]
	v_mfma_f32_16x16x32_bf16 v[112:115], v[140:143], v[204:207], v[112:115]
	v_mfma_f32_16x16x32_bf16 v[100:103], v[132:135], v[212:215], v[100:103]
	v_mfma_f32_16x16x32_bf16 v[96:99], v[140:143], v[212:215], v[96:99]
	v_mfma_f32_16x16x32_bf16 v[32:35], v[144:147], v[174:177], 0
	v_mfma_f32_16x16x32_bf16 v[36:39], v[152:155], v[174:177], 0
	v_mfma_f32_16x16x32_bf16 v[56:59], v[144:147], v[192:195], 0
	v_mfma_f32_16x16x32_bf16 v[60:63], v[152:155], v[192:195], 0
	v_mfma_f32_16x16x32_bf16 v[72:75], v[144:147], v[200:203], 0
	v_mfma_f32_16x16x32_bf16 v[76:79], v[152:155], v[200:203], 0
	v_mfma_f32_16x16x32_bf16 v[92:95], v[144:147], v[208:211], 0
	v_mfma_f32_16x16x32_bf16 v[88:91], v[152:155], v[208:211], 0
	v_mfma_f32_16x16x32_bf16 v[32:35], v[148:151], v[178:181], v[32:35]
	v_mfma_f32_16x16x32_bf16 v[36:39], v[156:159], v[178:181], v[36:39]
	v_mfma_f32_16x16x32_bf16 v[56:59], v[148:151], v[196:199], v[56:59]
	v_mfma_f32_16x16x32_bf16 v[60:63], v[156:159], v[196:199], v[60:63]
	v_mfma_f32_16x16x32_bf16 v[72:75], v[148:151], v[204:207], v[72:75]
	v_mfma_f32_16x16x32_bf16 v[76:79], v[156:159], v[204:207], v[76:79]
	v_mfma_f32_16x16x32_bf16 v[92:95], v[148:151], v[212:215], v[92:95]
	v_mfma_f32_16x16x32_bf16 v[88:91], v[156:159], v[212:215], v[88:91]
	s_barrier
	s_setprio 0
	s_branch .Lzmid16

.Lzmid16:
	v_add_u32_e32 v140, s82, v185
	v_add_u32_e32 v156, s83, v185
	ds_read_b128 v[128:131], v140
	ds_read_b128 v[132:135], v140 offset:1024
	ds_read_b128 v[136:139], v140 offset:2048
	ds_read_b128 v[140:143], v140 offset:3072
	ds_read_b128 v[144:147], v156
	ds_read_b128 v[148:151], v156 offset:1024
	ds_read_b128 v[152:155], v156 offset:2048
	ds_read_b128 v[156:159], v156 offset:3072
	s_add_u32 s34, s34, 0x4000
	s_addc_u32 s35, s35, 0
	s_mov_b32 m0, s54
	ds_read_b128 v[174:177], v188 offset:32768
	ds_read_b128 v[178:181], v188 offset:33792
	ds_read_b128 v[192:195], v188 offset:34816
	ds_read_b128 v[196:199], v188 offset:35840
	ds_read_b128 v[200:203], v188 offset:36864
	ds_read_b128 v[204:207], v188 offset:37888
	ds_read_b128 v[208:211], v188 offset:38912
	ds_read_b128 v[212:215], v188 offset:39936
	global_load_lds_dwordx4 v160, s[34:35]
	s_mov_b32 m0, s55
	s_nop 0
	global_load_lds_dwordx4 v164, s[34:35]
	s_waitcnt vmcnt(8)
	s_waitcnt lgkmcnt(0)
	s_setprio 1
	s_barrier
	v_mfma_f32_16x16x32_bf16 v[52:55], v[128:131], v[174:177], v[52:55]
	v_mfma_f32_16x16x32_bf16 v[48:51], v[136:139], v[174:177], v[48:51]
	v_mfma_f32_16x16x32_bf16 v[12:15], v[128:131], v[192:195], v[12:15]
	v_mfma_f32_16x16x32_bf16 v[0:3], v[136:139], v[192:195], v[0:3]
	v_mfma_f32_16x16x32_bf16 v[64:67], v[128:131], v[200:203], v[64:67]
	v_mfma_f32_16x16x32_bf16 v[68:71], v[136:139], v[200:203], v[68:71]
	v_mfma_f32_16x16x32_bf16 v[80:83], v[128:131], v[208:211], v[80:83]
	v_mfma_f32_16x16x32_bf16 v[84:87], v[136:139], v[208:211], v[84:87]
	v_mfma_f32_16x16x32_bf16 v[52:55], v[132:135], v[178:181], v[52:55]
	v_mfma_f32_16x16x32_bf16 v[48:51], v[140:143], v[178:181], v[48:51]
	v_mfma_f32_16x16x32_bf16 v[12:15], v[132:135], v[196:199], v[12:15]
	v_mfma_f32_16x16x32_bf16 v[0:3], v[140:143], v[196:199], v[0:3]
	v_mfma_f32_16x16x32_bf16 v[64:67], v[132:135], v[204:207], v[64:67]
	v_mfma_f32_16x16x32_bf16 v[68:71], v[140:143], v[204:207], v[68:71]
	v_mfma_f32_16x16x32_bf16 v[80:83], v[132:135], v[212:215], v[80:83]
	v_mfma_f32_16x16x32_bf16 v[84:87], v[140:143], v[212:215], v[84:87]
	v_mfma_f32_16x16x32_bf16 v[44:47], v[144:147], v[174:177], v[44:47]
	v_mfma_f32_16x16x32_bf16 v[40:43], v[152:155], v[174:177], v[40:43]
	v_mfma_f32_16x16x32_bf16 v[4:7], v[144:147], v[192:195], v[4:7]
	v_mfma_f32_16x16x32_bf16 v[8:11], v[152:155], v[192:195], v[8:11]
	v_mfma_f32_16x16x32_bf16 v[16:19], v[144:147], v[200:203], v[16:19]
	v_mfma_f32_16x16x32_bf16 v[20:23], v[152:155], v[200:203], v[20:23]
	v_mfma_f32_16x16x32_bf16 v[24:27], v[144:147], v[208:211], v[24:27]
	v_mfma_f32_16x16x32_bf16 v[28:31], v[152:155], v[208:211], v[28:31]
	v_mfma_f32_16x16x32_bf16 v[44:47], v[148:151], v[178:181], v[44:47]
	v_mfma_f32_16x16x32_bf16 v[40:43], v[156:159], v[178:181], v[40:43]
	v_mfma_f32_16x16x32_bf16 v[4:7], v[148:151], v[196:199], v[4:7]
	v_mfma_f32_16x16x32_bf16 v[8:11], v[156:159], v[196:199], v[8:11]
	v_mfma_f32_16x16x32_bf16 v[16:19], v[148:151], v[204:207], v[16:19]
	v_mfma_f32_16x16x32_bf16 v[20:23], v[156:159], v[204:207], v[20:23]
	v_mfma_f32_16x16x32_bf16 v[24:27], v[148:151], v[212:215], v[24:27]
	v_mfma_f32_16x16x32_bf16 v[28:31], v[156:159], v[212:215], v[28:31]
	s_barrier
	s_setprio 0
	s_add_u32 s34, s4, 0x40000
	s_addc_u32 s35, s5, 0
	s_add_i32 s40, s82, s46
	s_mov_b32 m0, s40
	ds_read_b128 v[174:177], v188 offset:49152
	ds_read_b128 v[178:181], v188 offset:50176
	ds_read_b128 v[192:195], v188 offset:51200
	ds_read_b128 v[196:199], v188 offset:52224
	ds_read_b128 v[200:203], v188 offset:53248
	ds_read_b128 v[204:207], v188 offset:54272
	ds_read_b128 v[208:211], v188 offset:55296
	ds_read_b128 v[212:215], v188 offset:56320
	global_load_lds_dwordx4 v162, s[34:35]
	s_add_i32 m0, s40, 0x2000
	s_add_u32 s4, s4, 0x44000
	global_load_lds_dwordx4 v166, s[34:35]
	s_addc_u32 s5, s5, 0
	s_add_i32 s34, s83, s46
	s_mov_b32 m0, s34
	s_nop 0
	global_load_lds_dwordx4 v162, s[4:5]
	s_add_i32 m0, s34, 0x2000
	s_nop 0
	global_load_lds_dwordx4 v166, s[4:5]
	s_mov_b32 m0, s68
	s_nop 0
	global_load_lds_dwordx4 v160, s[2:3]
	v_lshl_add_u64 v[216:217], s[2:3], 0, v[164:165]
	s_mov_b32 m0, s69
	s_nop 0
	global_load_lds_dwordx4 v[216:217], off
	s_waitcnt vmcnt(8)
	s_waitcnt lgkmcnt(0)
	s_setprio 1
	s_barrier
	v_mfma_f32_16x16x32_bf16 v[104:107], v[128:131], v[174:177], v[104:107]
	v_mfma_f32_16x16x32_bf16 v[108:111], v[136:139], v[174:177], v[108:111]
	v_mfma_f32_16x16x32_bf16 v[120:123], v[128:131], v[192:195], v[120:123]
	v_mfma_f32_16x16x32_bf16 v[124:127], v[136:139], v[192:195], v[124:127]
	v_mfma_f32_16x16x32_bf16 v[116:119], v[128:131], v[200:203], v[116:119]
	v_mfma_f32_16x16x32_bf16 v[112:115], v[136:139], v[200:203], v[112:115]
	v_mfma_f32_16x16x32_bf16 v[100:103], v[128:131], v[208:211], v[100:103]
	v_mfma_f32_16x16x32_bf16 v[96:99], v[136:139], v[208:211], v[96:99]
	v_mfma_f32_16x16x32_bf16 v[104:107], v[132:135], v[178:181], v[104:107]
	v_mfma_f32_16x16x32_bf16 v[108:111], v[140:143], v[178:181], v[108:111]
	v_mfma_f32_16x16x32_bf16 v[120:123], v[132:135], v[196:199], v[120:123]
	v_mfma_f32_16x16x32_bf16 v[124:127], v[140:143], v[196:199], v[124:127]
	v_mfma_f32_16x16x32_bf16 v[116:119], v[132:135], v[204:207], v[116:119]
	v_mfma_f32_16x16x32_bf16 v[112:115], v[140:143], v[204:207], v[112:115]
	v_mfma_f32_16x16x32_bf16 v[100:103], v[132:135], v[212:215], v[100:103]
	v_mfma_f32_16x16x32_bf16 v[96:99], v[140:143], v[212:215], v[96:99]
	v_mfma_f32_16x16x32_bf16 v[32:35], v[144:147], v[174:177], v[32:35]
	v_mfma_f32_16x16x32_bf16 v[36:39], v[152:155], v[174:177], v[36:39]
	v_mfma_f32_16x16x32_bf16 v[56:59], v[144:147], v[192:195], v[56:59]
	v_mfma_f32_16x16x32_bf16 v[60:63], v[152:155], v[192:195], v[60:63]
	v_mfma_f32_16x16x32_bf16 v[72:75], v[144:147], v[200:203], v[72:75]
	v_mfma_f32_16x16x32_bf16 v[76:79], v[152:155], v[200:203], v[76:79]
	v_mfma_f32_16x16x32_bf16 v[92:95], v[144:147], v[208:211], v[92:95]
	v_mfma_f32_16x16x32_bf16 v[88:91], v[152:155], v[208:211], v[88:91]
	v_mfma_f32_16x16x32_bf16 v[32:35], v[148:151], v[178:181], v[32:35]
	v_mfma_f32_16x16x32_bf16 v[36:39], v[156:159], v[178:181], v[36:39]
	v_mfma_f32_16x16x32_bf16 v[56:59], v[148:151], v[196:199], v[56:59]
	v_mfma_f32_16x16x32_bf16 v[60:63], v[156:159], v[196:199], v[60:63]
	v_mfma_f32_16x16x32_bf16 v[72:75], v[148:151], v[204:207], v[72:75]
	v_mfma_f32_16x16x32_bf16 v[76:79], v[156:159], v[204:207], v[76:79]
	v_mfma_f32_16x16x32_bf16 v[92:95], v[148:151], v[212:215], v[92:95]
	v_mfma_f32_16x16x32_bf16 v[88:91], v[156:159], v[212:215], v[88:91]
	s_barrier
	s_setprio 0
	s_add_i32 s39, s39, 2
	s_add_u32 s37, s37, 0x80000
	s_addc_u32 s38, s38, 0
	s_add_u32 s0, s0, 0x800000
	s_addc_u32 s1, s1, 0
	s_cmpk_gt_u32 s39, 0x55
	s_cbranch_scc0 .LBB0_2966
	s_and_b64 vcc, exec, s[20:21]
	s_cbranch_vccz .LBB0_2969
	s_barrier
